# GEMM k-loops: one static s_setprio 1 for waves 4-7 (younger wave per SIMD), reset after the loop
# speedup vs baseline: 1.0145x; 1.0131x over previous
.LBB0_22:
	s_add_i32 s2, s7, s8
	s_cmpk_gt_i32 s2, 0x1ff
	s_mov_b64 s[0:1], -1
	s_cbranch_scc1 .LBB0_21
	s_ashr_i32 s0, s2, 31
	s_lshr_b32 s0, s0, 27
	s_add_i32 s0, s2, s0
	s_and_b32 s1, s0, 0xffffffe0
	s_sub_i32 s1, s2, s1
	s_ashr_i32 s2, s1, 31
	s_lshr_b32 s2, s2, 29
	s_add_i32 s2, s1, s2
	s_and_b32 s3, s2, 0xfffff8
	s_sub_i32 s1, s1, s3
	s_lshl_b32 s0, s0, 6
	s_and_b32 s0, s0, 0xfffff800
	s_lshl_b32 s1, s1, 8
	s_add_i32 s0, s1, s0
	s_ashr_i32 s1, s0, 31
	s_lshl_b64 s[4:5], s[0:1], 12
	s_lshl_b32 s1, s2, 5
	s_and_b32 s2, s1, 0xffffff00
	s_ashr_i32 s3, s2, 31
	s_lshl_b64 s[10:11], s[2:3], 12
	s_add_u32 s12, s64, s4
	v_mov_b32_e32 v0, v138
	s_addc_u32 s13, s65, s5
	s_barrier
	v_readlane_b32 s14, v251, 22
	v_lshl_add_u64 v[2:3], v[0:1], 1, s[12:13]
	v_add_u32_e32 v0, 32, v139
	v_readlane_b32 s15, v251, 23
	v_readfirstlane_b32 s1, v0
	s_mov_b32 m0, s1
	v_mov_b32_e32 v0, v140
	global_load_lds_dwordx4 v[2:3], off
	s_add_u32 s14, s14, s10
	v_lshl_add_u64 v[2:3], v[0:1], 1, s[12:13]
	v_add_u32_e32 v0, 32, v141
	s_addc_u32 s15, s15, s11
	v_readfirstlane_b32 s1, v0
	s_mov_b32 m0, s1
	v_mov_b32_e32 v0, v142
	global_load_lds_dwordx4 v[2:3], off
	v_readlane_b32 s3, v254, 3
	v_lshl_add_u64 v[2:3], v[0:1], 1, s[12:13]
	v_add_u32_e32 v0, 32, v143
	s_mov_b32 s27, s51
	v_readfirstlane_b32 s1, v0
	s_mov_b32 m0, s1
	v_mov_b32_e32 v0, v144
	global_load_lds_dwordx4 v[2:3], off
	s_nop 0
	v_lshl_add_u64 v[2:3], v[0:1], 1, s[12:13]
	v_add_u32_e32 v0, 32, v145
	s_nop 0
	v_readfirstlane_b32 s1, v0
	s_mov_b32 m0, s1
	v_mov_b32_e32 v0, v138
	global_load_lds_dwordx4 v[2:3], off
	s_nop 0
	v_lshl_add_u64 v[2:3], v[0:1], 1, s[14:15]
	v_add_u32_e32 v0, s3, v139
	s_nop 0
	v_readfirstlane_b32 s1, v0
	s_mov_b32 m0, s1
	v_mov_b32_e32 v0, v140
	global_load_lds_dwordx4 v[2:3], off
	s_nop 0
	v_lshl_add_u64 v[2:3], v[0:1], 1, s[14:15]
	v_add_u32_e32 v0, s3, v141
	s_nop 0
	v_readfirstlane_b32 s1, v0
	s_mov_b32 m0, s1
	v_mov_b32_e32 v0, v142
	global_load_lds_dwordx4 v[2:3], off
	s_nop 0
	v_lshl_add_u64 v[2:3], v[0:1], 1, s[14:15]
	v_add_u32_e32 v0, s3, v143
	s_nop 0
	v_readfirstlane_b32 s1, v0
	s_mov_b32 m0, s1
	v_mov_b32_e32 v0, v144
	global_load_lds_dwordx4 v[2:3], off
	s_nop 0
	v_lshl_add_u64 v[2:3], v[0:1], 1, s[14:15]
	v_add_u32_e32 v0, s3, v145
	v_readlane_b32 s3, v253, 26
	v_readfirstlane_b32 s1, v0
	s_mov_b32 m0, s1
	v_readlane_b32 s1, v253, 25
	global_load_lds_dwordx4 v[2:3], off
	s_add_u32 s1, s1, s4
	s_waitcnt vmcnt(0)
	s_addc_u32 s3, s3, s5
	v_readlane_b32 s4, v253, 27
	s_add_u32 s9, s4, s10
	v_readlane_b32 s4, v253, 28
	v_mov_b32_e32 v2, 0
	s_addc_u32 s10, s4, s11
	s_mov_b64 s[4:5], 0
	s_mov_b32 s11, 0
	v_mov_b32_e32 v3, v2
	v_mov_b32_e32 v4, v2
	v_mov_b32_e32 v5, v2
	v_mov_b32_e32 v6, v2
	v_mov_b32_e32 v7, v2
	v_mov_b32_e32 v8, v2
	v_mov_b32_e32 v9, v2
	v_mov_b32_e32 v10, v2
	v_mov_b32_e32 v11, v2
	v_mov_b32_e32 v12, v2
	v_mov_b32_e32 v13, v2
	s_waitcnt vmcnt(0)
	v_mov_b32_e32 v14, v2
	v_mov_b32_e32 v15, v2
	v_mov_b32_e32 v16, v2
	v_mov_b32_e32 v17, v2
	v_mov_b32_e32 v18, v2
	v_mov_b32_e32 v19, v2
	v_mov_b32_e32 v20, v2
	v_mov_b32_e32 v21, v2
	v_mov_b32_e32 v22, v2
	v_mov_b32_e32 v23, v2
	v_mov_b32_e32 v24, v2
	v_mov_b32_e32 v25, v2
	v_mov_b32_e32 v26, v2
	v_mov_b32_e32 v27, v2
	v_mov_b32_e32 v28, v2
	v_mov_b32_e32 v29, v2
	v_mov_b32_e32 v30, v2
	v_mov_b32_e32 v31, v2
	v_mov_b32_e32 v32, v2
	v_mov_b32_e32 v33, v2
	v_mov_b32_e32 v34, v2
	v_mov_b32_e32 v35, v2
	v_mov_b32_e32 v36, v2
	v_mov_b32_e32 v37, v2
	v_mov_b32_e32 v38, v2
	v_mov_b32_e32 v39, v2
	v_mov_b32_e32 v40, v2
	v_mov_b32_e32 v41, v2
	v_mov_b32_e32 v42, v2
	v_mov_b32_e32 v43, v2
	v_mov_b32_e32 v44, v2
	v_mov_b32_e32 v45, v2
	v_mov_b32_e32 v46, v2
	v_mov_b32_e32 v47, v2
	v_mov_b32_e32 v48, v2
	v_mov_b32_e32 v49, v2
	v_mov_b32_e32 v50, v2
	v_mov_b32_e32 v51, v2
	v_mov_b32_e32 v52, v2
	v_mov_b32_e32 v53, v2
	v_mov_b32_e32 v54, v2
	v_mov_b32_e32 v55, v2
	v_mov_b32_e32 v56, v2
	v_mov_b32_e32 v57, v2
	v_mov_b32_e32 v58, v2
	v_mov_b32_e32 v59, v2
	v_mov_b32_e32 v60, v2
	v_mov_b32_e32 v61, v2
	v_mov_b32_e32 v62, v2
	v_mov_b32_e32 v63, v2
	v_mov_b32_e32 v64, v2
	v_mov_b32_e32 v65, v2
	v_mov_b32_e32 v66, v2
	v_mov_b32_e32 v67, v2
	v_mov_b32_e32 v68, v2
	v_mov_b32_e32 v69, v2
	v_mov_b32_e32 v70, v2
	v_mov_b32_e32 v71, v2
	v_mov_b32_e32 v72, v2
	v_mov_b32_e32 v73, v2
	v_mov_b32_e32 v74, v2
	v_mov_b32_e32 v75, v2
	v_mov_b32_e32 v76, v2
	v_mov_b32_e32 v77, v2
	v_mov_b32_e32 v78, v2
	v_mov_b32_e32 v79, v2
	v_mov_b32_e32 v80, v2
	v_mov_b32_e32 v81, v2
	v_mov_b32_e32 v82, v2
	v_mov_b32_e32 v83, v2
	v_mov_b32_e32 v84, v2
	v_mov_b32_e32 v85, v2
	v_mov_b32_e32 v86, v2
	v_mov_b32_e32 v87, v2
	v_mov_b32_e32 v88, v2
	v_mov_b32_e32 v89, v2
	v_mov_b32_e32 v90, v2
	v_mov_b32_e32 v91, v2
	v_mov_b32_e32 v92, v2
	v_mov_b32_e32 v93, v2
	v_mov_b32_e32 v94, v2
	v_mov_b32_e32 v95, v2
	v_mov_b32_e32 v96, v2
	v_mov_b32_e32 v97, v2
	v_mov_b32_e32 v98, v2
	v_mov_b32_e32 v99, v2
	v_mov_b32_e32 v100, v2
	v_mov_b32_e32 v101, v2
	v_mov_b32_e32 v102, v2
	v_mov_b32_e32 v103, v2
	v_mov_b32_e32 v104, v2
	v_mov_b32_e32 v105, v2
	v_mov_b32_e32 v106, v2
	v_mov_b32_e32 v107, v2
	v_mov_b32_e32 v108, v2
	v_mov_b32_e32 v109, v2
	v_mov_b32_e32 v110, v2
	v_mov_b32_e32 v111, v2
	v_mov_b32_e32 v112, v2
	v_mov_b32_e32 v113, v2
	v_mov_b32_e32 v114, v2
	v_mov_b32_e32 v115, v2
	v_mov_b32_e32 v116, v2
	v_mov_b32_e32 v117, v2
	v_mov_b32_e32 v118, v2
	v_mov_b32_e32 v119, v2
	v_mov_b32_e32 v120, v2
	v_mov_b32_e32 v121, v2
	v_mov_b32_e32 v122, v2
	v_mov_b32_e32 v123, v2
	v_mov_b32_e32 v124, v2
	v_mov_b32_e32 v125, v2
	v_mov_b32_e32 v126, v2
	v_mov_b32_e32 v127, v2
	v_mov_b32_e32 v128, v2
	v_mov_b32_e32 v129, v2
	s_waitcnt vmcnt(0) lgkmcnt(0)
	s_barrier
	v_lshlrev_b32_e32 v155, 1, v138
	v_readfirstlane_b32 s14, v139
	v_add_u32_e32 v177, v146, v148
	v_add_u32_e32 v207, v147, v148
	v_add_u32_e32 v204, v146, v152
	v_add_u32_e32 v208, v147, v152
	v_add_u32_e32 v205, v146, v153
	v_add_u32_e32 v209, v147, v153
	v_add_u32_e32 v206, v146, v154
	v_add_u32_e32 v210, v147, v154
	s_mov_b32 s11, 15
	v_readfirstlane_b32 s66, v179
	s_cmp_ge_u32 s66, 0x100
	s_cbranch_scc0 .Lg24_np
	s_setprio 1
.Lg24_np:
	s_add_u32 m0, s14, 0x8020
	s_add_u32 s12, s1, s4
	s_addc_u32 s13, s3, s5
	global_load_lds_dwordx4 v155, s[12:13]
	s_add_u32 m0, s14, 0xa020
	s_add_u32 s12, s12, 0x40000
	s_addc_u32 s13, s13, 0
	global_load_lds_dwordx4 v155, s[12:13]
	s_add_u32 m0, s14, 0xc020
	s_add_u32 s12, s12, 0x40000
	s_addc_u32 s13, s13, 0
	global_load_lds_dwordx4 v155, s[12:13]
	s_add_u32 m0, s14, 0xe020
	s_add_u32 s12, s12, 0x40000
	s_addc_u32 s13, s13, 0
	global_load_lds_dwordx4 v155, s[12:13]
	s_add_u32 m0, s14, 0x18020
	s_add_u32 s12, s9, s4
	s_addc_u32 s13, s10, s5
	global_load_lds_dwordx4 v155, s[12:13]
	ds_read_b128 v[130:133], v177 offset:0
	ds_read_b128 v[164:167], v207 offset:0
	ds_read_b128 v[168:171], v207 offset:4096
	ds_read_b128 v[134:137], v177 offset:4096
	ds_read_b128 v[156:159], v177 offset:8192
	ds_read_b128 v[160:163], v177 offset:12288
.Lg24_loop:
	s_waitcnt lgkmcnt(4)
	v_mfma_f32_32x32x16_bf16 v[114:129], v[130:133], v[164:167], v[114:129]
	ds_read_b128 v[172:175], v204 offset:0
	s_waitcnt lgkmcnt(4)
	v_mfma_f32_32x32x16_bf16 v[98:113], v[130:133], v[168:171], v[98:113]
	ds_read_b128 v[192:195], v208 offset:0
	s_add_u32 m0, s14, 0x1a020
	s_add_u32 s12, s12, 0x40000
	s_addc_u32 s13, s13, 0
	global_load_lds_dwordx4 v155, s[12:13]
	s_waitcnt lgkmcnt(4)
	v_mfma_f32_32x32x16_bf16 v[82:97], v[134:137], v[164:167], v[82:97]
	ds_read_b128 v[200:203], v208 offset:4096
	v_mfma_f32_32x32x16_bf16 v[66:81], v[134:137], v[168:171], v[66:81]
	ds_read_b128 v[180:183], v204 offset:4096
	s_add_u32 m0, s14, 0x1c020
	s_add_u32 s12, s12, 0x40000
	s_addc_u32 s13, s13, 0
	global_load_lds_dwordx4 v155, s[12:13]
	s_waitcnt lgkmcnt(5)
	v_mfma_f32_32x32x16_bf16 v[50:65], v[156:159], v[164:167], v[50:65]
	ds_read_b128 v[184:187], v204 offset:8192
	v_mfma_f32_32x32x16_bf16 v[34:49], v[156:159], v[168:171], v[34:49]
	ds_read_b128 v[188:191], v204 offset:12288
	s_add_u32 m0, s14, 0x1e020
	s_add_u32 s12, s12, 0x40000
	s_addc_u32 s13, s13, 0
	global_load_lds_dwordx4 v155, s[12:13]
	s_add_u32 s4, s4, 0x80
	s_addc_u32 s5, s5, 0
	s_waitcnt lgkmcnt(6)
	v_mfma_f32_32x32x16_bf16 v[18:33], v[160:163], v[164:167], v[18:33]
	v_mfma_f32_32x32x16_bf16 v[2:17], v[160:163], v[168:171], v[2:17]
	s_waitcnt lgkmcnt(4)
	v_mfma_f32_32x32x16_bf16 v[114:129], v[172:175], v[192:195], v[114:129]
	ds_read_b128 v[130:133], v205 offset:0
	s_waitcnt lgkmcnt(4)
	v_mfma_f32_32x32x16_bf16 v[98:113], v[172:175], v[200:203], v[98:113]
	ds_read_b128 v[164:167], v209 offset:0
	s_waitcnt lgkmcnt(4)
	v_mfma_f32_32x32x16_bf16 v[82:97], v[180:183], v[192:195], v[82:97]
	ds_read_b128 v[168:171], v209 offset:4096
	v_mfma_f32_32x32x16_bf16 v[66:81], v[180:183], v[200:203], v[66:81]
	ds_read_b128 v[134:137], v205 offset:4096
	s_waitcnt lgkmcnt(5)
	v_mfma_f32_32x32x16_bf16 v[50:65], v[184:187], v[192:195], v[50:65]
	ds_read_b128 v[156:159], v205 offset:8192
	v_mfma_f32_32x32x16_bf16 v[34:49], v[184:187], v[200:203], v[34:49]
	ds_read_b128 v[160:163], v205 offset:12288
	s_waitcnt lgkmcnt(6)
	v_mfma_f32_32x32x16_bf16 v[18:33], v[188:191], v[192:195], v[18:33]
	v_mfma_f32_32x32x16_bf16 v[2:17], v[188:191], v[200:203], v[2:17]
	s_waitcnt lgkmcnt(4)
	v_mfma_f32_32x32x16_bf16 v[114:129], v[130:133], v[164:167], v[114:129]
	ds_read_b128 v[172:175], v206 offset:0
	ds_read_b128 v[192:195], v210 offset:0
	s_waitcnt lgkmcnt(5)
	v_mfma_f32_32x32x16_bf16 v[98:113], v[130:133], v[168:171], v[98:113]
	ds_read_b128 v[200:203], v210 offset:4096
	ds_read_b128 v[180:183], v206 offset:4096
	s_waitcnt lgkmcnt(6)
	v_mfma_f32_32x32x16_bf16 v[82:97], v[134:137], v[164:167], v[82:97]
	ds_read_b128 v[184:187], v206 offset:8192
	ds_read_b128 v[188:191], v206 offset:12288
	v_mfma_f32_32x32x16_bf16 v[66:81], v[134:137], v[168:171], v[66:81]
	s_waitcnt lgkmcnt(7)
	v_mfma_f32_32x32x16_bf16 v[50:65], v[156:159], v[164:167], v[50:65]
	v_mfma_f32_32x32x16_bf16 v[34:49], v[156:159], v[168:171], v[34:49]
	s_waitcnt lgkmcnt(6)
	v_mfma_f32_32x32x16_bf16 v[18:33], v[160:163], v[164:167], v[18:33]
	v_mfma_f32_32x32x16_bf16 v[2:17], v[160:163], v[168:171], v[2:17]
	s_waitcnt vmcnt(0) lgkmcnt(0)
	s_barrier
	v_mfma_f32_32x32x16_bf16 v[114:129], v[172:175], v[192:195], v[114:129]
	ds_read_b128 v[130:133], v177 offset:32768
	s_add_u32 m0, s14, 0x20
	s_add_u32 s12, s1, s4
	s_addc_u32 s13, s3, s5
	global_load_lds_dwordx4 v155, s[12:13]
	v_mfma_f32_32x32x16_bf16 v[98:113], v[172:175], v[200:203], v[98:113]
	ds_read_b128 v[164:167], v207 offset:32768
	s_add_u32 m0, s14, 0x2020
	s_add_u32 s12, s12, 0x40000
	s_addc_u32 s13, s13, 0
	global_load_lds_dwordx4 v155, s[12:13]
	v_mfma_f32_32x32x16_bf16 v[82:97], v[180:183], v[192:195], v[82:97]
	ds_read_b128 v[168:171], v207 offset:36864
	s_add_u32 m0, s14, 0x4020
	s_add_u32 s12, s12, 0x40000
	s_addc_u32 s13, s13, 0
	global_load_lds_dwordx4 v155, s[12:13]
	v_mfma_f32_32x32x16_bf16 v[66:81], v[180:183], v[200:203], v[66:81]
	ds_read_b128 v[134:137], v177 offset:36864
	s_add_u32 m0, s14, 0x6020
	s_add_u32 s12, s12, 0x40000
	s_addc_u32 s13, s13, 0
	global_load_lds_dwordx4 v155, s[12:13]
	v_mfma_f32_32x32x16_bf16 v[50:65], v[184:187], v[192:195], v[50:65]
	ds_read_b128 v[156:159], v177 offset:40960
	s_add_u32 m0, s14, 0x10020
	s_add_u32 s12, s9, s4
	s_addc_u32 s13, s10, s5
	global_load_lds_dwordx4 v155, s[12:13]
	v_mfma_f32_32x32x16_bf16 v[34:49], v[184:187], v[200:203], v[34:49]
	ds_read_b128 v[160:163], v177 offset:45056
	v_mfma_f32_32x32x16_bf16 v[18:33], v[188:191], v[192:195], v[18:33]
	v_mfma_f32_32x32x16_bf16 v[2:17], v[188:191], v[200:203], v[2:17]
	s_waitcnt lgkmcnt(4)
	v_mfma_f32_32x32x16_bf16 v[114:129], v[130:133], v[164:167], v[114:129]
	ds_read_b128 v[172:175], v204 offset:32768
	s_waitcnt lgkmcnt(4)
	v_mfma_f32_32x32x16_bf16 v[98:113], v[130:133], v[168:171], v[98:113]
	ds_read_b128 v[192:195], v208 offset:32768
	s_add_u32 m0, s14, 0x12020
	s_add_u32 s12, s12, 0x40000
	s_addc_u32 s13, s13, 0
	global_load_lds_dwordx4 v155, s[12:13]
	s_waitcnt lgkmcnt(4)
	v_mfma_f32_32x32x16_bf16 v[82:97], v[134:137], v[164:167], v[82:97]
	ds_read_b128 v[200:203], v208 offset:36864
	v_mfma_f32_32x32x16_bf16 v[66:81], v[134:137], v[168:171], v[66:81]
	ds_read_b128 v[180:183], v204 offset:36864
	s_add_u32 m0, s14, 0x14020
	s_add_u32 s12, s12, 0x40000
	s_addc_u32 s13, s13, 0
	global_load_lds_dwordx4 v155, s[12:13]
	s_waitcnt lgkmcnt(5)
	v_mfma_f32_32x32x16_bf16 v[50:65], v[156:159], v[164:167], v[50:65]
	ds_read_b128 v[184:187], v204 offset:40960
	v_mfma_f32_32x32x16_bf16 v[34:49], v[156:159], v[168:171], v[34:49]
	ds_read_b128 v[188:191], v204 offset:45056
	s_add_u32 m0, s14, 0x16020
	s_add_u32 s12, s12, 0x40000
	s_addc_u32 s13, s13, 0
	global_load_lds_dwordx4 v155, s[12:13]
	s_add_u32 s4, s4, 0x80
	s_addc_u32 s5, s5, 0
	s_waitcnt lgkmcnt(6)
	v_mfma_f32_32x32x16_bf16 v[18:33], v[160:163], v[164:167], v[18:33]
	v_mfma_f32_32x32x16_bf16 v[2:17], v[160:163], v[168:171], v[2:17]
	s_waitcnt lgkmcnt(4)
	v_mfma_f32_32x32x16_bf16 v[114:129], v[172:175], v[192:195], v[114:129]
	ds_read_b128 v[130:133], v205 offset:32768
	s_waitcnt lgkmcnt(4)
	v_mfma_f32_32x32x16_bf16 v[98:113], v[172:175], v[200:203], v[98:113]
	ds_read_b128 v[164:167], v209 offset:32768
	s_waitcnt lgkmcnt(4)
	v_mfma_f32_32x32x16_bf16 v[82:97], v[180:183], v[192:195], v[82:97]
	ds_read_b128 v[168:171], v209 offset:36864
	v_mfma_f32_32x32x16_bf16 v[66:81], v[180:183], v[200:203], v[66:81]
	ds_read_b128 v[134:137], v205 offset:36864
	s_waitcnt lgkmcnt(5)
	v_mfma_f32_32x32x16_bf16 v[50:65], v[184:187], v[192:195], v[50:65]
	ds_read_b128 v[156:159], v205 offset:40960
	v_mfma_f32_32x32x16_bf16 v[34:49], v[184:187], v[200:203], v[34:49]
	ds_read_b128 v[160:163], v205 offset:45056
	s_waitcnt lgkmcnt(6)
	v_mfma_f32_32x32x16_bf16 v[18:33], v[188:191], v[192:195], v[18:33]
	v_mfma_f32_32x32x16_bf16 v[2:17], v[188:191], v[200:203], v[2:17]
	s_waitcnt lgkmcnt(4)
	v_mfma_f32_32x32x16_bf16 v[114:129], v[130:133], v[164:167], v[114:129]
	ds_read_b128 v[172:175], v206 offset:32768
	ds_read_b128 v[192:195], v210 offset:32768
	s_waitcnt lgkmcnt(5)
	v_mfma_f32_32x32x16_bf16 v[98:113], v[130:133], v[168:171], v[98:113]
	ds_read_b128 v[200:203], v210 offset:36864
	ds_read_b128 v[180:183], v206 offset:36864
	s_waitcnt lgkmcnt(6)
	v_mfma_f32_32x32x16_bf16 v[82:97], v[134:137], v[164:167], v[82:97]
	ds_read_b128 v[184:187], v206 offset:40960
	ds_read_b128 v[188:191], v206 offset:45056
	v_mfma_f32_32x32x16_bf16 v[66:81], v[134:137], v[168:171], v[66:81]
	s_waitcnt lgkmcnt(7)
	v_mfma_f32_32x32x16_bf16 v[50:65], v[156:159], v[164:167], v[50:65]
	v_mfma_f32_32x32x16_bf16 v[34:49], v[156:159], v[168:171], v[34:49]
	s_waitcnt lgkmcnt(6)
	v_mfma_f32_32x32x16_bf16 v[18:33], v[160:163], v[164:167], v[18:33]
	v_mfma_f32_32x32x16_bf16 v[2:17], v[160:163], v[168:171], v[2:17]
	s_waitcnt vmcnt(0) lgkmcnt(0)
	s_barrier
	v_mfma_f32_32x32x16_bf16 v[114:129], v[172:175], v[192:195], v[114:129]
	ds_read_b128 v[130:133], v177 offset:0
	s_add_u32 m0, s14, 0x8020
	s_add_u32 s12, s1, s4
	s_addc_u32 s13, s3, s5
	global_load_lds_dwordx4 v155, s[12:13]
	v_mfma_f32_32x32x16_bf16 v[98:113], v[172:175], v[200:203], v[98:113]
	ds_read_b128 v[164:167], v207 offset:0
	s_add_u32 m0, s14, 0xa020
	s_add_u32 s12, s12, 0x40000
	s_addc_u32 s13, s13, 0
	global_load_lds_dwordx4 v155, s[12:13]
	v_mfma_f32_32x32x16_bf16 v[82:97], v[180:183], v[192:195], v[82:97]
	ds_read_b128 v[168:171], v207 offset:4096
	s_add_u32 m0, s14, 0xc020
	s_add_u32 s12, s12, 0x40000
	s_addc_u32 s13, s13, 0
	global_load_lds_dwordx4 v155, s[12:13]
	v_mfma_f32_32x32x16_bf16 v[66:81], v[180:183], v[200:203], v[66:81]
	ds_read_b128 v[134:137], v177 offset:4096
	s_add_u32 m0, s14, 0xe020
	s_add_u32 s12, s12, 0x40000
	s_addc_u32 s13, s13, 0
	global_load_lds_dwordx4 v155, s[12:13]
	v_mfma_f32_32x32x16_bf16 v[50:65], v[184:187], v[192:195], v[50:65]
	ds_read_b128 v[156:159], v177 offset:8192
	s_add_u32 m0, s14, 0x18020
	s_add_u32 s12, s9, s4
	s_addc_u32 s13, s10, s5
	global_load_lds_dwordx4 v155, s[12:13]
	v_mfma_f32_32x32x16_bf16 v[34:49], v[184:187], v[200:203], v[34:49]
	ds_read_b128 v[160:163], v177 offset:12288
	v_mfma_f32_32x32x16_bf16 v[18:33], v[188:191], v[192:195], v[18:33]
	v_mfma_f32_32x32x16_bf16 v[2:17], v[188:191], v[200:203], v[2:17]
	s_sub_u32 s11, s11, 1
	s_cmp_lg_u32 s11, 0
	s_cbranch_scc1 .Lg24_loop
	s_waitcnt lgkmcnt(4)
	v_mfma_f32_32x32x16_bf16 v[114:129], v[130:133], v[164:167], v[114:129]
	ds_read_b128 v[172:175], v204 offset:0
	s_waitcnt lgkmcnt(4)
	v_mfma_f32_32x32x16_bf16 v[98:113], v[130:133], v[168:171], v[98:113]
	ds_read_b128 v[192:195], v208 offset:0
	s_add_u32 m0, s14, 0x1a020
	s_add_u32 s12, s12, 0x40000
	s_addc_u32 s13, s13, 0
	global_load_lds_dwordx4 v155, s[12:13]
	s_waitcnt lgkmcnt(4)
	v_mfma_f32_32x32x16_bf16 v[82:97], v[134:137], v[164:167], v[82:97]
	ds_read_b128 v[200:203], v208 offset:4096
	v_mfma_f32_32x32x16_bf16 v[66:81], v[134:137], v[168:171], v[66:81]
	ds_read_b128 v[180:183], v204 offset:4096
	s_add_u32 m0, s14, 0x1c020
	s_add_u32 s12, s12, 0x40000
	s_addc_u32 s13, s13, 0
	global_load_lds_dwordx4 v155, s[12:13]
	s_waitcnt lgkmcnt(5)
	v_mfma_f32_32x32x16_bf16 v[50:65], v[156:159], v[164:167], v[50:65]
	ds_read_b128 v[184:187], v204 offset:8192
	v_mfma_f32_32x32x16_bf16 v[34:49], v[156:159], v[168:171], v[34:49]
	ds_read_b128 v[188:191], v204 offset:12288
	s_add_u32 m0, s14, 0x1e020
	s_add_u32 s12, s12, 0x40000
	s_addc_u32 s13, s13, 0
	global_load_lds_dwordx4 v155, s[12:13]
	s_add_u32 s4, s4, 0x80
	s_addc_u32 s5, s5, 0
	s_waitcnt lgkmcnt(6)
	v_mfma_f32_32x32x16_bf16 v[18:33], v[160:163], v[164:167], v[18:33]
	v_mfma_f32_32x32x16_bf16 v[2:17], v[160:163], v[168:171], v[2:17]
	s_waitcnt lgkmcnt(4)
	v_mfma_f32_32x32x16_bf16 v[114:129], v[172:175], v[192:195], v[114:129]
	ds_read_b128 v[130:133], v205 offset:0
	s_waitcnt lgkmcnt(4)
	v_mfma_f32_32x32x16_bf16 v[98:113], v[172:175], v[200:203], v[98:113]
	ds_read_b128 v[164:167], v209 offset:0
	s_waitcnt lgkmcnt(4)
	v_mfma_f32_32x32x16_bf16 v[82:97], v[180:183], v[192:195], v[82:97]
	ds_read_b128 v[168:171], v209 offset:4096
	v_mfma_f32_32x32x16_bf16 v[66:81], v[180:183], v[200:203], v[66:81]
	ds_read_b128 v[134:137], v205 offset:4096
	s_waitcnt lgkmcnt(5)
	v_mfma_f32_32x32x16_bf16 v[50:65], v[184:187], v[192:195], v[50:65]
	ds_read_b128 v[156:159], v205 offset:8192
	v_mfma_f32_32x32x16_bf16 v[34:49], v[184:187], v[200:203], v[34:49]
	ds_read_b128 v[160:163], v205 offset:12288
	s_waitcnt lgkmcnt(6)
	v_mfma_f32_32x32x16_bf16 v[18:33], v[188:191], v[192:195], v[18:33]
	v_mfma_f32_32x32x16_bf16 v[2:17], v[188:191], v[200:203], v[2:17]
	s_waitcnt lgkmcnt(4)
	v_mfma_f32_32x32x16_bf16 v[114:129], v[130:133], v[164:167], v[114:129]
	ds_read_b128 v[172:175], v206 offset:0
	ds_read_b128 v[192:195], v210 offset:0
	s_waitcnt lgkmcnt(5)
	v_mfma_f32_32x32x16_bf16 v[98:113], v[130:133], v[168:171], v[98:113]
	ds_read_b128 v[200:203], v210 offset:4096
	ds_read_b128 v[180:183], v206 offset:4096
	s_waitcnt lgkmcnt(6)
	v_mfma_f32_32x32x16_bf16 v[82:97], v[134:137], v[164:167], v[82:97]
	ds_read_b128 v[184:187], v206 offset:8192
	ds_read_b128 v[188:191], v206 offset:12288
	v_mfma_f32_32x32x16_bf16 v[66:81], v[134:137], v[168:171], v[66:81]
	s_waitcnt lgkmcnt(7)
	v_mfma_f32_32x32x16_bf16 v[50:65], v[156:159], v[164:167], v[50:65]
	v_mfma_f32_32x32x16_bf16 v[34:49], v[156:159], v[168:171], v[34:49]
	s_waitcnt lgkmcnt(6)
	v_mfma_f32_32x32x16_bf16 v[18:33], v[160:163], v[164:167], v[18:33]
	v_mfma_f32_32x32x16_bf16 v[2:17], v[160:163], v[168:171], v[2:17]
	s_waitcnt vmcnt(0) lgkmcnt(0)
	s_barrier
	v_mfma_f32_32x32x16_bf16 v[114:129], v[172:175], v[192:195], v[114:129]
	ds_read_b128 v[130:133], v177 offset:32768
	v_mfma_f32_32x32x16_bf16 v[98:113], v[172:175], v[200:203], v[98:113]
	ds_read_b128 v[164:167], v207 offset:32768
	v_mfma_f32_32x32x16_bf16 v[82:97], v[180:183], v[192:195], v[82:97]
	ds_read_b128 v[168:171], v207 offset:36864
	v_mfma_f32_32x32x16_bf16 v[66:81], v[180:183], v[200:203], v[66:81]
	ds_read_b128 v[134:137], v177 offset:36864
	v_mfma_f32_32x32x16_bf16 v[50:65], v[184:187], v[192:195], v[50:65]
	ds_read_b128 v[156:159], v177 offset:40960
	v_mfma_f32_32x32x16_bf16 v[34:49], v[184:187], v[200:203], v[34:49]
	ds_read_b128 v[160:163], v177 offset:45056
	v_mfma_f32_32x32x16_bf16 v[18:33], v[188:191], v[192:195], v[18:33]
	v_mfma_f32_32x32x16_bf16 v[2:17], v[188:191], v[200:203], v[2:17]
	s_waitcnt lgkmcnt(4)
	v_mfma_f32_32x32x16_bf16 v[114:129], v[130:133], v[164:167], v[114:129]
	ds_read_b128 v[172:175], v204 offset:32768
	s_waitcnt lgkmcnt(4)
	v_mfma_f32_32x32x16_bf16 v[98:113], v[130:133], v[168:171], v[98:113]
	ds_read_b128 v[192:195], v208 offset:32768
	s_waitcnt lgkmcnt(4)
	v_mfma_f32_32x32x16_bf16 v[82:97], v[134:137], v[164:167], v[82:97]
	ds_read_b128 v[200:203], v208 offset:36864
	v_mfma_f32_32x32x16_bf16 v[66:81], v[134:137], v[168:171], v[66:81]
	ds_read_b128 v[180:183], v204 offset:36864
	s_waitcnt lgkmcnt(5)
	v_mfma_f32_32x32x16_bf16 v[50:65], v[156:159], v[164:167], v[50:65]
	ds_read_b128 v[184:187], v204 offset:40960
	v_mfma_f32_32x32x16_bf16 v[34:49], v[156:159], v[168:171], v[34:49]
	ds_read_b128 v[188:191], v204 offset:45056
	s_waitcnt lgkmcnt(6)
	v_mfma_f32_32x32x16_bf16 v[18:33], v[160:163], v[164:167], v[18:33]
	v_mfma_f32_32x32x16_bf16 v[2:17], v[160:163], v[168:171], v[2:17]
	s_waitcnt lgkmcnt(4)
	v_mfma_f32_32x32x16_bf16 v[114:129], v[172:175], v[192:195], v[114:129]
	ds_read_b128 v[130:133], v205 offset:32768
	s_waitcnt lgkmcnt(4)
	v_mfma_f32_32x32x16_bf16 v[98:113], v[172:175], v[200:203], v[98:113]
	ds_read_b128 v[164:167], v209 offset:32768
	s_waitcnt lgkmcnt(4)
	v_mfma_f32_32x32x16_bf16 v[82:97], v[180:183], v[192:195], v[82:97]
	ds_read_b128 v[168:171], v209 offset:36864
	v_mfma_f32_32x32x16_bf16 v[66:81], v[180:183], v[200:203], v[66:81]
	ds_read_b128 v[134:137], v205 offset:36864
	s_waitcnt lgkmcnt(5)
	v_mfma_f32_32x32x16_bf16 v[50:65], v[184:187], v[192:195], v[50:65]
	ds_read_b128 v[156:159], v205 offset:40960
	v_mfma_f32_32x32x16_bf16 v[34:49], v[184:187], v[200:203], v[34:49]
	ds_read_b128 v[160:163], v205 offset:45056
	s_waitcnt lgkmcnt(6)
	v_mfma_f32_32x32x16_bf16 v[18:33], v[188:191], v[192:195], v[18:33]
	v_mfma_f32_32x32x16_bf16 v[2:17], v[188:191], v[200:203], v[2:17]
	s_waitcnt lgkmcnt(4)
	v_mfma_f32_32x32x16_bf16 v[114:129], v[130:133], v[164:167], v[114:129]
	ds_read_b128 v[172:175], v206 offset:32768
	ds_read_b128 v[192:195], v210 offset:32768
	s_waitcnt lgkmcnt(5)
	v_mfma_f32_32x32x16_bf16 v[98:113], v[130:133], v[168:171], v[98:113]
	ds_read_b128 v[200:203], v210 offset:36864
	ds_read_b128 v[180:183], v206 offset:36864
	s_waitcnt lgkmcnt(6)
	v_mfma_f32_32x32x16_bf16 v[82:97], v[134:137], v[164:167], v[82:97]
	ds_read_b128 v[184:187], v206 offset:40960
	ds_read_b128 v[188:191], v206 offset:45056
	v_mfma_f32_32x32x16_bf16 v[66:81], v[134:137], v[168:171], v[66:81]
	s_waitcnt lgkmcnt(7)
	v_mfma_f32_32x32x16_bf16 v[50:65], v[156:159], v[164:167], v[50:65]
	v_mfma_f32_32x32x16_bf16 v[34:49], v[156:159], v[168:171], v[34:49]
	s_waitcnt lgkmcnt(6)
	v_mfma_f32_32x32x16_bf16 v[18:33], v[160:163], v[164:167], v[18:33]
	v_mfma_f32_32x32x16_bf16 v[2:17], v[160:163], v[168:171], v[2:17]
	s_waitcnt vmcnt(0) lgkmcnt(0)
	s_barrier
	v_mfma_f32_32x32x16_bf16 v[114:129], v[172:175], v[192:195], v[114:129]
	v_mfma_f32_32x32x16_bf16 v[98:113], v[172:175], v[200:203], v[98:113]
	v_mfma_f32_32x32x16_bf16 v[82:97], v[180:183], v[192:195], v[82:97]
	v_mfma_f32_32x32x16_bf16 v[66:81], v[180:183], v[200:203], v[66:81]
	v_mfma_f32_32x32x16_bf16 v[50:65], v[184:187], v[192:195], v[50:65]
	v_mfma_f32_32x32x16_bf16 v[34:49], v[184:187], v[200:203], v[34:49]
	v_mfma_f32_32x32x16_bf16 v[18:33], v[188:191], v[192:195], v[18:33]
	v_mfma_f32_32x32x16_bf16 v[2:17], v[188:191], v[200:203], v[2:17]
	s_setprio 0
	v_add_u32_e32 v130, s0, v149
	v_ashrrev_i32_e32 v131, 31, v130
	v_lshrrev_b32_e32 v155, 18, v131
	v_add_u32_e32 v0, v130, v155
	v_ashrrev_i32_e32 v0, 14, v0
	v_mul_i32_i24_e32 v133, 0x4000, v0
	v_sub_u32_e32 v133, v130, v133
	v_add_u32_e32 v156, 0x100, v133
	v_mul_hi_i32_i24_e32 v137, 0x4100, v0
	v_mul_i32_i24_e32 v136, 0x4100, v0
	v_ashrrev_i32_e32 v157, 31, v156
	v_lshl_add_u64 v[136:137], v[136:137], 0, v[156:157]
	v_mov_b32_e32 v156, v179
	s_waitcnt vmcnt(0)
	s_barrier
	v_mul_i32_i24_e32 v134, 0xc00, v0
	v_readlane_b32 s40, v251, 2
	v_and_b32_e32 v0, 31, v156
	v_bfe_u32 v133, v156, 5, 1
	v_mul_u32_u24_e32 v133, 0x240, v133
	v_lshlrev_b32_e32 v0, 2, v0
	v_add3_u32 v0, v151, v133, v0
	ds_write2_b32 v0, v114, v115 offset1:36
	ds_write2_b32 v0, v116, v117 offset0:72 offset1:108
	v_add_u32_e32 v114, 0x400, v0
	v_or_b32_e32 v132, s2, v150
	ds_write2_b32 v114, v118, v119 offset0:32 offset1:68
	ds_write2_b32 v114, v120, v121 offset0:104 offset1:140
	v_add_u32_e32 v114, 0x800, v0
	v_add_u32_e32 v0, 0xc00, v0
	v_readlane_b32 s41, v251, 3
	v_readlane_b32 s42, v251, 4
	v_readlane_b32 s43, v251, 5
	v_readlane_b32 s44, v251, 6
	v_readlane_b32 s45, v251, 7
	v_readlane_b32 s46, v251, 8
	v_readlane_b32 s47, v251, 9
	v_readlane_b32 s48, v251, 10
	v_readlane_b32 s49, v251, 11
	v_readlane_b32 s50, v251, 12
	v_readlane_b32 s51, v251, 13
	v_readlane_b32 s0, v251, 26
	v_ashrrev_i32_e32 v135, 31, v134
	v_lshlrev_b64 v[136:137], 11, v[136:137]
	ds_write2_b32 v114, v122, v123 offset0:64 offset1:100
	ds_write2_b32 v114, v124, v125 offset0:136 offset1:172
	ds_write2_b32 v0, v126, v127 offset0:96 offset1:132
	ds_write2_b32 v0, v128, v129 offset0:168 offset1:204
	v_readlane_b32 s54, v251, 16
	v_readlane_b32 s55, v251, 17
	v_ashrrev_i32_e32 v133, 31, v132
	v_readlane_b32 s1, v251, 27
	v_readlane_b32 s36, v253, 47
	v_lshlrev_b32_e32 v0, 2, v156
	v_readlane_b32 s52, v251, 14
	v_readlane_b32 s53, v251, 15
	v_lshl_add_u64 v[114:115], v[134:135], 2, s[54:55]
	s_mov_b64 s[2:3], 0x1b0b000
	v_lshl_add_u64 v[118:119], s[0:1], 0, v[136:137]
	v_lshlrev_b64 v[116:117], 1, v[132:133]
	v_lshlrev_b64 v[122:123], 12, v[130:131]
	v_readlane_b32 s37, v253, 48
	v_and_b32_e32 v128, 28, v0
	v_lshl_add_u64 v[120:121], v[114:115], 0, s[2:3]
	v_lshlrev_b64 v[114:115], 2, v[132:133]
	v_lshl_add_u64 v[118:119], v[118:119], 0, v[116:117]
	v_lshl_add_u64 v[124:125], s[36:37], 0, v[122:123]
	v_lshl_add_u64 v[122:123], s[52:53], 0, v[122:123]
	v_lshlrev_b32_e32 v0, 2, v128
	v_lshlrev_b32_e32 v128, 1, v128
	v_mov_b32_e32 v129, v1
	v_bfe_u32 v133, v156, 3, 3
	v_lshl_add_u64 v[126:127], v[120:121], 0, v[114:115]
	v_lshl_add_u64 v[124:125], v[124:125], 0, v[114:115]
	v_lshl_add_u64 v[122:123], v[122:123], 0, v[114:115]
	v_lshl_add_u64 v[134:135], v[118:119], 0, v[128:129]
	v_mul_u32_u24_e32 v131, 0x90, v133
	v_lshlrev_b32_e32 v156, 11, v133
	v_mov_b32_e32 v157, v1
	s_waitcnt lgkmcnt(0)
	v_lshl_add_u64 v[126:127], v[126:127], 0, v[0:1]
	v_lshl_add_u64 v[136:137], v[124:125], 0, v[0:1]
	v_lshl_add_u64 v[128:129], v[122:123], 0, v[0:1]
	v_add3_u32 v131, v151, v0, v131
	v_lshlrev_b32_e32 v0, 12, v133
	v_lshl_add_u64 v[156:157], v[134:135], 0, v[156:157]
	v_lshl_add_u64 v[164:165], v[136:137], 0, v[0:1]
	global_load_dwordx4 v[180:183], v[126:127], off
	v_mov_b32_e32 v212, v133
	v_lshlrev_b32_e32 v184, 11, v212
	v_mov_b32_e32 v185, v1
	v_lshl_add_u64 v[184:185], v[134:135], 0, v[184:185]
	global_load_dwordx2 v[184:185], v[184:185], off
	v_lshlrev_b32_e32 v192, 12, v212
	v_mov_b32_e32 v193, v1
	v_lshl_add_u64 v[192:193], v[136:137], 0, v[192:193]
	global_load_dwordx4 v[192:195], v[192:193], off
	v_or_b32_e32 v212, 8, v133
	v_lshlrev_b32_e32 v186, 11, v212
	v_mov_b32_e32 v187, v1
	v_lshl_add_u64 v[186:187], v[134:135], 0, v[186:187]
	global_load_dwordx2 v[186:187], v[186:187], off
	v_lshlrev_b32_e32 v200, 12, v212
	v_mov_b32_e32 v201, v1
	v_lshl_add_u64 v[200:201], v[136:137], 0, v[200:201]
	global_load_dwordx4 v[200:203], v[200:201], off
	v_or_b32_e32 v212, 16, v133
	v_lshlrev_b32_e32 v188, 11, v212
	v_mov_b32_e32 v189, v1
	v_lshl_add_u64 v[188:189], v[134:135], 0, v[188:189]
	global_load_dwordx2 v[188:189], v[188:189], off
	v_lshlrev_b32_e32 v204, 12, v212
	v_mov_b32_e32 v205, v1
	v_lshl_add_u64 v[204:205], v[136:137], 0, v[204:205]
	global_load_dwordx4 v[204:207], v[204:205], off
	v_or_b32_e32 v212, 24, v133
	v_lshlrev_b32_e32 v190, 11, v212
	v_mov_b32_e32 v191, v1
	v_lshl_add_u64 v[190:191], v[134:135], 0, v[190:191]
	global_load_dwordx2 v[190:191], v[190:191], off
	v_lshlrev_b32_e32 v208, 12, v212
	v_mov_b32_e32 v209, v1
	v_lshl_add_u64 v[208:209], v[136:137], 0, v[208:209]
	global_load_dwordx4 v[208:211], v[208:209], off
	s_waitcnt vmcnt(6)
	v_mov_b32_e32 v168, v184
	v_mov_b32_e32 v169, v185
	ds_read_b128 v[156:159], v131
	v_mov_b32_e32 v160, v180
	v_mov_b32_e32 v161, v181
	v_mov_b32_e32 v162, v182
	v_mov_b32_e32 v163, v183
	s_nop 0
	v_mov_b32_e32 v164, v192
	v_mov_b32_e32 v165, v193
	v_mov_b32_e32 v166, v194
	v_mov_b32_e32 v167, v195
	v_lshl_add_u64 v[170:171], v[128:129], 0, v[0:1]
	v_readlane_b32 s38, v253, 49
	v_readlane_b32 s39, v253, 50
	v_readlane_b32 s42, v253, 53
	v_readlane_b32 s43, v253, 54
	v_readlane_b32 s44, v253, 55
	v_readlane_b32 s45, v253, 56
	v_readlane_b32 s46, v253, 57
	v_readlane_b32 s47, v253, 58
	v_readlane_b32 s48, v253, 59
	v_readlane_b32 s49, v253, 60
	v_readlane_b32 s51, v253, 62
	v_readlane_b32 s40, v253, 51
	v_readlane_b32 s41, v253, 52
	v_readlane_b32 s50, v253, 61
	v_and_b32_e32 v173, 0xffff0000, v168
	v_lshlrev_b32_e32 v172, 16, v168
	v_pk_add_f32 v[164:165], v[164:165], v[172:173]
	s_waitcnt lgkmcnt(0)
	v_pk_fma_f32 v[156:157], v[156:157], v[160:161], v[164:165]
	v_and_b32_e32 v161, 0xffff0000, v169
	v_lshlrev_b32_e32 v160, 16, v169
	v_pk_add_f32 v[160:161], v[166:167], v[160:161]
	s_nop 0
	v_pk_fma_f32 v[158:159], v[158:159], v[162:163], v[160:161]
	global_store_dwordx4 v[170:171], v[156:159], off
	s_nop 1
	v_or_b32_e32 v156, 8, v133
	v_lshlrev_b32_e32 v0, 12, v156
	v_lshlrev_b32_e32 v156, 11, v156
	v_mov_b32_e32 v157, v1
	v_lshl_add_u64 v[156:157], v[134:135], 0, v[156:157]
	v_lshl_add_u64 v[164:165], v[136:137], 0, v[0:1]
	s_waitcnt vmcnt(5)
	v_mov_b32_e32 v168, v186
	v_mov_b32_e32 v169, v187
	ds_read_b128 v[156:159], v131 offset:1152
	v_mov_b32_e32 v160, v180
	v_mov_b32_e32 v161, v181
	v_mov_b32_e32 v162, v182
	v_mov_b32_e32 v163, v183
	s_nop 0
	v_mov_b32_e32 v164, v200
	v_mov_b32_e32 v165, v201
	v_mov_b32_e32 v166, v202
	v_mov_b32_e32 v167, v203
	v_lshl_add_u64 v[170:171], v[128:129], 0, v[0:1]
	v_or_b32_e32 v0, 16, v133
	v_and_b32_e32 v173, 0xffff0000, v168
	v_lshlrev_b32_e32 v172, 16, v168
	v_pk_add_f32 v[164:165], v[164:165], v[172:173]
	s_waitcnt lgkmcnt(0)
	v_pk_fma_f32 v[156:157], v[156:157], v[160:161], v[164:165]
	v_and_b32_e32 v161, 0xffff0000, v169
	v_lshlrev_b32_e32 v160, 16, v169
	v_pk_add_f32 v[160:161], v[166:167], v[160:161]
	s_nop 0
	v_pk_fma_f32 v[158:159], v[158:159], v[162:163], v[160:161]
	global_store_dwordx4 v[170:171], v[156:159], off
	s_nop 1
	v_lshlrev_b32_e32 v158, 11, v0
	v_mov_b32_e32 v159, v1
	v_lshlrev_b32_e32 v156, 12, v0
	v_mov_b32_e32 v157, v1
	v_lshl_add_u64 v[158:159], v[134:135], 0, v[158:159]
	v_lshl_add_u64 v[164:165], v[136:137], 0, v[156:157]
	s_waitcnt vmcnt(4)
	v_mov_b32_e32 v168, v188
	v_mov_b32_e32 v169, v189
	v_lshl_add_u64 v[170:171], v[128:129], 0, v[156:157]
	ds_read_b128 v[156:159], v131 offset:2304
	v_mov_b32_e32 v160, v180
	v_mov_b32_e32 v161, v181
	v_mov_b32_e32 v162, v182
	v_mov_b32_e32 v163, v183
	s_nop 0
	v_mov_b32_e32 v164, v204
	v_mov_b32_e32 v165, v205
	v_mov_b32_e32 v166, v206
	v_mov_b32_e32 v167, v207
	v_or_b32_e32 v0, 24, v133
	v_and_b32_e32 v173, 0xffff0000, v168
	v_lshlrev_b32_e32 v172, 16, v168
	v_pk_add_f32 v[164:165], v[164:165], v[172:173]
	s_waitcnt lgkmcnt(0)
	v_pk_fma_f32 v[156:157], v[156:157], v[160:161], v[164:165]
	v_and_b32_e32 v161, 0xffff0000, v169
	v_lshlrev_b32_e32 v160, 16, v169
	v_pk_add_f32 v[160:161], v[166:167], v[160:161]
	s_nop 0
	v_pk_fma_f32 v[158:159], v[158:159], v[162:163], v[160:161]
	global_store_dwordx4 v[170:171], v[156:159], off
	s_nop 1
	v_lshlrev_b32_e32 v156, 12, v0
	v_mov_b32_e32 v157, v1
	v_lshl_add_u64 v[158:159], v[136:137], 0, v[156:157]
	v_lshlrev_b32_e32 v136, 11, v0
	v_mov_b32_e32 v137, v1
	v_lshl_add_u64 v[134:135], v[134:135], 0, v[136:137]
	s_waitcnt vmcnt(3)
	v_mov_b32_e32 v160, v190
	v_mov_b32_e32 v161, v191
	v_lshl_add_u64 v[162:163], v[128:129], 0, v[156:157]
	ds_read_b128 v[134:137], v131 offset:3456
	v_mov_b32_e32 v126, v180
	v_mov_b32_e32 v127, v181
	v_mov_b32_e32 v128, v182
	v_mov_b32_e32 v129, v183
	s_nop 0
	v_mov_b32_e32 v156, v208
	v_mov_b32_e32 v157, v209
	v_mov_b32_e32 v158, v210
	v_mov_b32_e32 v159, v211
	v_and_b32_e32 v165, 0xffff0000, v160
	v_lshlrev_b32_e32 v164, 16, v160
	v_pk_add_f32 v[156:157], v[156:157], v[164:165]
	s_waitcnt lgkmcnt(0)
	v_pk_fma_f32 v[126:127], v[134:135], v[126:127], v[156:157]
	v_and_b32_e32 v135, 0xffff0000, v161
	v_lshlrev_b32_e32 v134, 16, v161
	v_pk_add_f32 v[134:135], v[158:159], v[134:135]
	s_nop 0
	v_pk_fma_f32 v[128:129], v[136:137], v[128:129], v[134:135]
	global_store_dwordx4 v[162:163], v[126:129], off
	v_mov_b32_e32 v0, v179
	s_nop 0
	v_or_b32_e32 v126, 32, v132
	v_and_b32_e32 v127, 31, v0
	v_bfe_u32 v128, v0, 5, 1
	v_mul_u32_u24_e32 v128, 0x240, v128
	v_lshlrev_b32_e32 v127, 2, v127
	v_add3_u32 v127, v151, v128, v127
	ds_write2_b32 v127, v98, v99 offset1:36
	ds_write2_b32 v127, v100, v101 offset0:72 offset1:108
	v_add_u32_e32 v98, 0x400, v127
	ds_write2_b32 v98, v102, v103 offset0:32 offset1:68
	ds_write2_b32 v98, v104, v105 offset0:104 offset1:140
	v_add_u32_e32 v98, 0x800, v127
	ds_write2_b32 v98, v106, v107 offset0:64 offset1:100
	ds_write2_b32 v98, v108, v109 offset0:136 offset1:172
	v_add_u32_e32 v98, 0xc00, v127
	ds_write2_b32 v98, v110, v111 offset0:96 offset1:132
	ds_write2_b32 v98, v112, v113 offset0:168 offset1:204
	v_lshlrev_b32_e32 v98, 2, v0
	v_and_b32_e32 v102, 28, v98
	v_lshlrev_b32_e32 v108, 2, v102
	v_lshlrev_b32_e32 v102, 1, v102
	v_mov_b32_e32 v103, v1
	v_bfe_u32 v131, v0, 3, 3
	v_ashrrev_i32_e32 v127, 31, v126
	v_mov_b32_e32 v109, v1
	v_lshl_add_u64 v[104:105], v[118:119], 0, v[102:103]
	v_lshlrev_b32_e32 v110, 11, v131
	v_mov_b32_e32 v111, v1
	s_waitcnt lgkmcnt(0)
	v_lshl_add_u64 v[100:101], v[120:121], 0, v[108:109]
	v_lshlrev_b64 v[98:99], 2, v[126:127]
	v_mul_u32_u24_e32 v0, 0x90, v131
	v_lshl_add_u64 v[110:111], v[104:105], 0, v[110:111]
	v_lshl_add_u64 v[100:101], v[100:101], 0, v[98:99]
	v_lshl_add_u64 v[106:107], v[124:125], 0, v[108:109]
	v_lshl_add_u64 v[102:103], v[122:123], 0, v[108:109]
	v_add3_u32 v0, v151, v108, v0
	v_lshlrev_b32_e32 v108, 12, v131
	global_load_dwordx4 v[180:183], v[100:101], off
	v_mov_b32_e32 v212, v131
	v_lshlrev_b32_e32 v184, 11, v212
	v_mov_b32_e32 v185, v1
	v_lshl_add_u64 v[184:185], v[104:105], 0, v[184:185]
	global_load_dwordx2 v[184:185], v[184:185], off offset:64
	v_lshlrev_b32_e32 v192, 12, v212
	v_mov_b32_e32 v193, v1
	v_lshl_add_u64 v[192:193], v[106:107], 0, v[192:193]
	global_load_dwordx4 v[192:195], v[192:193], off offset:128
	v_or_b32_e32 v212, 8, v131
	v_lshlrev_b32_e32 v186, 11, v212
	v_mov_b32_e32 v187, v1
	v_lshl_add_u64 v[186:187], v[104:105], 0, v[186:187]
	global_load_dwordx2 v[186:187], v[186:187], off offset:64
	v_lshlrev_b32_e32 v200, 12, v212
	v_mov_b32_e32 v201, v1
	v_lshl_add_u64 v[200:201], v[106:107], 0, v[200:201]
	global_load_dwordx4 v[200:203], v[200:201], off offset:128
	v_or_b32_e32 v212, 16, v131
	v_lshlrev_b32_e32 v188, 11, v212
	v_mov_b32_e32 v189, v1
	v_lshl_add_u64 v[188:189], v[104:105], 0, v[188:189]
	global_load_dwordx2 v[188:189], v[188:189], off offset:64
	v_lshlrev_b32_e32 v204, 12, v212
	v_mov_b32_e32 v205, v1
	v_lshl_add_u64 v[204:205], v[106:107], 0, v[204:205]
	global_load_dwordx4 v[204:207], v[204:205], off offset:128
	v_or_b32_e32 v212, 24, v131
	v_lshlrev_b32_e32 v190, 11, v212
	v_mov_b32_e32 v191, v1
	v_lshl_add_u64 v[190:191], v[104:105], 0, v[190:191]
	global_load_dwordx2 v[190:191], v[190:191], off offset:64
	v_lshlrev_b32_e32 v208, 12, v212
	v_mov_b32_e32 v209, v1
	v_lshl_add_u64 v[208:209], v[106:107], 0, v[208:209]
	global_load_dwordx4 v[208:211], v[208:209], off offset:128
	s_waitcnt vmcnt(6)
	v_mov_b32_e32 v126, v184
	v_mov_b32_e32 v127, v185
	v_lshl_add_u64 v[112:113], v[106:107], 0, v[108:109]
	v_lshl_add_u64 v[128:129], v[102:103], 0, v[108:109]
	ds_read_b128 v[108:111], v0
	v_mov_b32_e32 v118, v180
	v_mov_b32_e32 v119, v181
	v_mov_b32_e32 v120, v182
	v_mov_b32_e32 v121, v183
	v_mov_b32_e32 v122, v192
	v_mov_b32_e32 v123, v193
	v_mov_b32_e32 v124, v194
	v_mov_b32_e32 v125, v195
	v_and_b32_e32 v113, 0xffff0000, v126
	v_lshlrev_b32_e32 v112, 16, v126
	v_pk_add_f32 v[112:113], v[122:123], v[112:113]
	s_waitcnt lgkmcnt(0)
	v_pk_fma_f32 v[108:109], v[108:109], v[118:119], v[112:113]
	v_and_b32_e32 v113, 0xffff0000, v127
	v_lshlrev_b32_e32 v112, 16, v127
	v_pk_add_f32 v[112:113], v[124:125], v[112:113]
	s_nop 0
	v_pk_fma_f32 v[110:111], v[110:111], v[120:121], v[112:113]
	global_store_dwordx4 v[128:129], v[108:111], off offset:128
	s_nop 1
	v_or_b32_e32 v110, 8, v131
	v_lshlrev_b32_e32 v108, 12, v110
	v_lshlrev_b32_e32 v110, 11, v110
	v_mov_b32_e32 v111, v1
	v_lshl_add_u64 v[110:111], v[104:105], 0, v[110:111]
	v_mov_b32_e32 v109, v1
	s_waitcnt vmcnt(5)
	v_mov_b32_e32 v126, v186
	v_mov_b32_e32 v127, v187
	v_lshl_add_u64 v[112:113], v[106:107], 0, v[108:109]
	v_lshl_add_u64 v[128:129], v[102:103], 0, v[108:109]
	ds_read_b128 v[108:111], v0 offset:1152
	v_mov_b32_e32 v118, v180
	v_mov_b32_e32 v119, v181
	v_mov_b32_e32 v120, v182
	v_mov_b32_e32 v121, v183
	v_mov_b32_e32 v122, v200
	v_mov_b32_e32 v123, v201
	v_mov_b32_e32 v124, v202
	v_mov_b32_e32 v125, v203
	v_and_b32_e32 v113, 0xffff0000, v126
	v_lshlrev_b32_e32 v112, 16, v126
	v_pk_add_f32 v[112:113], v[122:123], v[112:113]
	s_waitcnt lgkmcnt(0)
	v_pk_fma_f32 v[108:109], v[108:109], v[118:119], v[112:113]
	v_and_b32_e32 v113, 0xffff0000, v127
	v_lshlrev_b32_e32 v112, 16, v127
	v_pk_add_f32 v[112:113], v[124:125], v[112:113]
	s_nop 0
	v_pk_fma_f32 v[110:111], v[110:111], v[120:121], v[112:113]
	global_store_dwordx4 v[128:129], v[108:111], off offset:128
	s_nop 1
	v_or_b32_e32 v110, 16, v131
	v_lshlrev_b32_e32 v108, 12, v110
	v_lshlrev_b32_e32 v110, 11, v110
	v_mov_b32_e32 v111, v1
	v_lshl_add_u64 v[110:111], v[104:105], 0, v[110:111]
	v_mov_b32_e32 v109, v1
	s_waitcnt vmcnt(4)
	v_mov_b32_e32 v126, v188
	v_mov_b32_e32 v127, v189
	v_lshl_add_u64 v[112:113], v[106:107], 0, v[108:109]
	v_lshl_add_u64 v[128:129], v[102:103], 0, v[108:109]
	ds_read_b128 v[108:111], v0 offset:2304
	v_mov_b32_e32 v118, v180
	v_mov_b32_e32 v119, v181
	v_mov_b32_e32 v120, v182
	v_mov_b32_e32 v121, v183
	v_mov_b32_e32 v122, v204
	v_mov_b32_e32 v123, v205
	v_mov_b32_e32 v124, v206
	v_mov_b32_e32 v125, v207
	v_and_b32_e32 v113, 0xffff0000, v126
	v_lshlrev_b32_e32 v112, 16, v126
	v_pk_add_f32 v[112:113], v[122:123], v[112:113]
	s_waitcnt lgkmcnt(0)
	v_pk_fma_f32 v[108:109], v[108:109], v[118:119], v[112:113]
	v_and_b32_e32 v113, 0xffff0000, v127
	v_lshlrev_b32_e32 v112, 16, v127
	v_pk_add_f32 v[112:113], v[124:125], v[112:113]
	s_nop 0
	v_pk_fma_f32 v[110:111], v[110:111], v[120:121], v[112:113]
	v_or_b32_e32 v112, 24, v131
	global_store_dwordx4 v[128:129], v[108:111], off offset:128
	s_nop 1
	v_lshlrev_b32_e32 v108, 12, v112
	v_mov_b32_e32 v109, v1
	v_lshl_add_u64 v[110:111], v[106:107], 0, v[108:109]
	v_lshlrev_b32_e32 v106, 11, v112
	v_mov_b32_e32 v107, v1
	v_lshl_add_u64 v[104:105], v[104:105], 0, v[106:107]
	s_waitcnt vmcnt(3)
	v_mov_b32_e32 v118, v190
	v_mov_b32_e32 v119, v191
	v_lshl_add_u64 v[120:121], v[102:103], 0, v[108:109]
	ds_read_b128 v[102:105], v0 offset:3456
	v_mov_b32_e32 v106, v180
	v_mov_b32_e32 v107, v181
	v_mov_b32_e32 v108, v182
	v_mov_b32_e32 v109, v183
	s_nop 0
	v_mov_b32_e32 v110, v208
	v_mov_b32_e32 v111, v209
	v_mov_b32_e32 v112, v210
	v_mov_b32_e32 v113, v211
	v_and_b32_e32 v101, 0xffff0000, v118
	v_lshlrev_b32_e32 v100, 16, v118
	v_pk_add_f32 v[100:101], v[110:111], v[100:101]
	s_waitcnt lgkmcnt(0)
	v_pk_fma_f32 v[100:101], v[102:103], v[106:107], v[100:101]
	v_and_b32_e32 v103, 0xffff0000, v119
	v_lshlrev_b32_e32 v102, 16, v119
	v_pk_add_f32 v[102:103], v[112:113], v[102:103]
	s_nop 0
	v_pk_fma_f32 v[102:103], v[104:105], v[108:109], v[102:103]
	global_store_dwordx4 v[120:121], v[100:103], off offset:128
	s_nop 1
	v_or_b32_e32 v100, 32, v130
	v_add_u32_e32 v0, v100, v155
	v_ashrrev_i32_e32 v0, 14, v0
	v_mul_i32_i24_e32 v101, 0x4000, v0
	v_sub_u32_e32 v101, v100, v101
	v_add_u32_e32 v106, 0x100, v101
	v_mul_i32_i24_e32 v102, 0xc00, v0
	v_mul_hi_i32_i24_e32 v105, 0x4100, v0
	v_mul_i32_i24_e32 v104, 0x4100, v0
	v_ashrrev_i32_e32 v107, 31, v106
	v_mov_b32_e32 v0, v179
	v_lshl_add_u64 v[104:105], v[104:105], 0, v[106:107]
	v_ashrrev_i32_e32 v103, 31, v102
	v_and_b32_e32 v106, 31, v0
	v_bfe_u32 v107, v0, 5, 1
	v_mul_u32_u24_e32 v107, 0x240, v107
	v_lshlrev_b32_e32 v106, 2, v106
	v_add3_u32 v106, v151, v107, v106
	ds_write2_b32 v106, v82, v83 offset1:36
	ds_write2_b32 v106, v84, v85 offset0:72 offset1:108
	v_add_u32_e32 v82, 0x400, v106
	ds_write2_b32 v82, v86, v87 offset0:32 offset1:68
	ds_write2_b32 v82, v88, v89 offset0:104 offset1:140
	v_add_u32_e32 v82, 0x800, v106
	ds_write2_b32 v82, v90, v91 offset0:64 offset1:100
	ds_write2_b32 v82, v92, v93 offset0:136 offset1:172
	v_add_u32_e32 v82, 0xc00, v106
	v_lshlrev_b64 v[104:105], 11, v[104:105]
	v_ashrrev_i32_e32 v101, 31, v100
	ds_write2_b32 v82, v94, v95 offset0:96 offset1:132
	ds_write2_b32 v82, v96, v97 offset0:168 offset1:204
	v_lshl_add_u64 v[82:83], v[102:103], 2, s[54:55]
	v_lshlrev_b32_e32 v92, 2, v0
	v_lshl_add_u64 v[86:87], v[82:83], 0, s[2:3]
	v_lshl_add_u64 v[82:83], s[0:1], 0, v[104:105]
	v_lshlrev_b64 v[84:85], 12, v[100:101]
	v_and_b32_e32 v92, 28, v92
	v_lshl_add_u64 v[82:83], v[82:83], 0, v[116:117]
	v_lshl_add_u64 v[88:89], s[36:37], 0, v[84:85]
	v_lshl_add_u64 v[84:85], s[52:53], 0, v[84:85]
	v_lshlrev_b32_e32 v100, 2, v92
	v_lshlrev_b32_e32 v92, 1, v92
	v_mov_b32_e32 v93, v1
	v_bfe_u32 v122, v0, 3, 3
	v_lshl_add_u64 v[90:91], v[86:87], 0, v[114:115]
	v_lshl_add_u64 v[88:89], v[88:89], 0, v[114:115]
	v_lshl_add_u64 v[84:85], v[84:85], 0, v[114:115]
	v_mov_b32_e32 v101, v1
	v_lshl_add_u64 v[94:95], v[82:83], 0, v[92:93]
	v_mul_u32_u24_e32 v0, 0x90, v122
	v_lshlrev_b32_e32 v102, 11, v122
	v_mov_b32_e32 v103, v1
	s_waitcnt lgkmcnt(0)
	v_lshl_add_u64 v[90:91], v[90:91], 0, v[100:101]
	v_lshl_add_u64 v[96:97], v[88:89], 0, v[100:101]
	v_lshl_add_u64 v[92:93], v[84:85], 0, v[100:101]
	v_add3_u32 v0, v151, v100, v0
	v_lshlrev_b32_e32 v100, 12, v122
	v_lshl_add_u64 v[102:103], v[94:95], 0, v[102:103]
	v_lshl_add_u64 v[108:109], v[96:97], 0, v[100:101]
	global_load_dwordx4 v[180:183], v[90:91], off
	v_mov_b32_e32 v212, v122
	v_lshlrev_b32_e32 v184, 11, v212
	v_mov_b32_e32 v185, v1
	v_lshl_add_u64 v[184:185], v[94:95], 0, v[184:185]
	global_load_dwordx2 v[184:185], v[184:185], off
	v_lshlrev_b32_e32 v192, 12, v212
	v_mov_b32_e32 v193, v1
	v_lshl_add_u64 v[192:193], v[96:97], 0, v[192:193]
	global_load_dwordx4 v[192:195], v[192:193], off
	v_or_b32_e32 v212, 8, v122
	v_lshlrev_b32_e32 v186, 11, v212
	v_mov_b32_e32 v187, v1
	v_lshl_add_u64 v[186:187], v[94:95], 0, v[186:187]
	global_load_dwordx2 v[186:187], v[186:187], off
	v_lshlrev_b32_e32 v200, 12, v212
	v_mov_b32_e32 v201, v1
	v_lshl_add_u64 v[200:201], v[96:97], 0, v[200:201]
	global_load_dwordx4 v[200:203], v[200:201], off
	v_or_b32_e32 v212, 16, v122
	v_lshlrev_b32_e32 v188, 11, v212
	v_mov_b32_e32 v189, v1
	v_lshl_add_u64 v[188:189], v[94:95], 0, v[188:189]
	global_load_dwordx2 v[188:189], v[188:189], off
	v_lshlrev_b32_e32 v204, 12, v212
	v_mov_b32_e32 v205, v1
	v_lshl_add_u64 v[204:205], v[96:97], 0, v[204:205]
	global_load_dwordx4 v[204:207], v[204:205], off
	v_or_b32_e32 v212, 24, v122
	v_lshlrev_b32_e32 v190, 11, v212
	v_mov_b32_e32 v191, v1
	v_lshl_add_u64 v[190:191], v[94:95], 0, v[190:191]
	global_load_dwordx2 v[190:191], v[190:191], off
	v_lshlrev_b32_e32 v208, 12, v212
	v_mov_b32_e32 v209, v1
	v_lshl_add_u64 v[208:209], v[96:97], 0, v[208:209]
	global_load_dwordx4 v[208:211], v[208:209], off
	s_waitcnt vmcnt(6)
	v_mov_b32_e32 v112, v184
	v_mov_b32_e32 v113, v185
	v_lshl_add_u64 v[118:119], v[92:93], 0, v[100:101]
	ds_read_b128 v[100:103], v0
	v_mov_b32_e32 v104, v180
	v_mov_b32_e32 v105, v181
	v_mov_b32_e32 v106, v182
	v_mov_b32_e32 v107, v183
	s_nop 0
	v_mov_b32_e32 v108, v192
	v_mov_b32_e32 v109, v193
	v_mov_b32_e32 v110, v194
	v_mov_b32_e32 v111, v195
	v_and_b32_e32 v121, 0xffff0000, v112
	v_lshlrev_b32_e32 v120, 16, v112
	v_pk_add_f32 v[108:109], v[108:109], v[120:121]
	s_waitcnt lgkmcnt(0)
	v_pk_fma_f32 v[100:101], v[100:101], v[104:105], v[108:109]
	v_and_b32_e32 v105, 0xffff0000, v113
	v_lshlrev_b32_e32 v104, 16, v113
	v_pk_add_f32 v[104:105], v[110:111], v[104:105]
	s_nop 0
	v_pk_fma_f32 v[102:103], v[102:103], v[106:107], v[104:105]
	global_store_dwordx4 v[118:119], v[100:103], off
	s_nop 1
	v_or_b32_e32 v102, 8, v122
	v_lshlrev_b32_e32 v100, 12, v102
	v_lshlrev_b32_e32 v102, 11, v102
	v_mov_b32_e32 v103, v1
	v_mov_b32_e32 v101, v1
	v_lshl_add_u64 v[102:103], v[94:95], 0, v[102:103]
	v_lshl_add_u64 v[108:109], v[96:97], 0, v[100:101]
	s_waitcnt vmcnt(5)
	v_mov_b32_e32 v112, v186
	v_mov_b32_e32 v113, v187
	v_lshl_add_u64 v[118:119], v[92:93], 0, v[100:101]
	ds_read_b128 v[100:103], v0 offset:1152
	v_mov_b32_e32 v104, v180
	v_mov_b32_e32 v105, v181
	v_mov_b32_e32 v106, v182
	v_mov_b32_e32 v107, v183
	s_nop 0
	v_mov_b32_e32 v108, v200
	v_mov_b32_e32 v109, v201
	v_mov_b32_e32 v110, v202
	v_mov_b32_e32 v111, v203
	v_and_b32_e32 v121, 0xffff0000, v112
	v_lshlrev_b32_e32 v120, 16, v112
	v_pk_add_f32 v[108:109], v[108:109], v[120:121]
	s_waitcnt lgkmcnt(0)
	v_pk_fma_f32 v[100:101], v[100:101], v[104:105], v[108:109]
	v_and_b32_e32 v105, 0xffff0000, v113
	v_lshlrev_b32_e32 v104, 16, v113
	v_pk_add_f32 v[104:105], v[110:111], v[104:105]
	s_nop 0
	v_pk_fma_f32 v[102:103], v[102:103], v[106:107], v[104:105]
	global_store_dwordx4 v[118:119], v[100:103], off
	s_nop 1
	v_or_b32_e32 v102, 16, v122
	v_lshlrev_b32_e32 v100, 12, v102
	v_lshlrev_b32_e32 v102, 11, v102
	v_mov_b32_e32 v103, v1
	v_mov_b32_e32 v101, v1
	v_lshl_add_u64 v[102:103], v[94:95], 0, v[102:103]
	v_lshl_add_u64 v[108:109], v[96:97], 0, v[100:101]
	s_waitcnt vmcnt(4)
	v_mov_b32_e32 v112, v188
	v_mov_b32_e32 v113, v189
	v_lshl_add_u64 v[118:119], v[92:93], 0, v[100:101]
	ds_read_b128 v[100:103], v0 offset:2304
	v_mov_b32_e32 v104, v180
	v_mov_b32_e32 v105, v181
	v_mov_b32_e32 v106, v182
	v_mov_b32_e32 v107, v183
	s_nop 0
	v_mov_b32_e32 v108, v204
	v_mov_b32_e32 v109, v205
	v_mov_b32_e32 v110, v206
	v_mov_b32_e32 v111, v207
	v_and_b32_e32 v121, 0xffff0000, v112
	v_lshlrev_b32_e32 v120, 16, v112
	v_pk_add_f32 v[108:109], v[108:109], v[120:121]
	s_waitcnt lgkmcnt(0)
	v_pk_fma_f32 v[100:101], v[100:101], v[104:105], v[108:109]
	v_and_b32_e32 v105, 0xffff0000, v113
	v_lshlrev_b32_e32 v104, 16, v113
	v_pk_add_f32 v[104:105], v[110:111], v[104:105]
	s_nop 0
	v_pk_fma_f32 v[102:103], v[102:103], v[106:107], v[104:105]
	global_store_dwordx4 v[118:119], v[100:103], off
	s_nop 1
	v_or_b32_e32 v102, 24, v122
	v_lshlrev_b32_e32 v100, 12, v102
	v_lshlrev_b32_e32 v102, 11, v102
	v_mov_b32_e32 v103, v1
	v_lshl_add_u64 v[94:95], v[94:95], 0, v[102:103]
	v_mov_b32_e32 v101, v1
	s_waitcnt vmcnt(3)
	v_mov_b32_e32 v108, v190
	v_mov_b32_e32 v109, v191
	v_lshl_add_u64 v[96:97], v[96:97], 0, v[100:101]
	v_lshl_add_u64 v[110:111], v[92:93], 0, v[100:101]
	ds_read_b128 v[92:95], v0 offset:3456
	v_mov_b32_e32 v100, v180
	v_mov_b32_e32 v101, v181
	v_mov_b32_e32 v102, v182
	v_mov_b32_e32 v103, v183
	v_mov_b32_e32 v104, v208
	v_mov_b32_e32 v105, v209
	v_mov_b32_e32 v106, v210
	v_mov_b32_e32 v107, v211
	v_and_b32_e32 v91, 0xffff0000, v108
	v_lshlrev_b32_e32 v90, 16, v108
	v_pk_add_f32 v[90:91], v[104:105], v[90:91]
	s_waitcnt lgkmcnt(0)
	v_pk_fma_f32 v[90:91], v[92:93], v[100:101], v[90:91]
	v_and_b32_e32 v93, 0xffff0000, v109
	v_lshlrev_b32_e32 v92, 16, v109
	v_pk_add_f32 v[92:93], v[106:107], v[92:93]
	s_nop 0
	v_pk_fma_f32 v[92:93], v[94:95], v[102:103], v[92:93]
	global_store_dwordx4 v[110:111], v[90:93], off
	v_mov_b32_e32 v0, v179
	s_nop 0
	v_and_b32_e32 v90, 31, v0
	v_bfe_u32 v91, v0, 5, 1
	v_mul_u32_u24_e32 v91, 0x240, v91
	v_lshlrev_b32_e32 v90, 2, v90
	v_add3_u32 v90, v151, v91, v90
	ds_write2_b32 v90, v66, v67 offset1:36
	ds_write2_b32 v90, v68, v69 offset0:72 offset1:108
	v_add_u32_e32 v66, 0x400, v90
	ds_write2_b32 v66, v70, v71 offset0:32 offset1:68
	ds_write2_b32 v66, v72, v73 offset0:104 offset1:140
	v_add_u32_e32 v66, 0x800, v90
	ds_write2_b32 v66, v74, v75 offset0:64 offset1:100
	ds_write2_b32 v66, v76, v77 offset0:136 offset1:172
	v_add_u32_e32 v66, 0xc00, v90
	ds_write2_b32 v66, v78, v79 offset0:96 offset1:132
	ds_write2_b32 v66, v80, v81 offset0:168 offset1:204
	v_lshlrev_b32_e32 v66, 2, v0
	v_and_b32_e32 v68, 28, v66
	v_lshlrev_b32_e32 v74, 2, v68
	v_lshlrev_b32_e32 v68, 1, v68
	v_mov_b32_e32 v69, v1
	v_bfe_u32 v92, v0, 3, 3
	v_mov_b32_e32 v75, v1
	v_lshl_add_u64 v[70:71], v[82:83], 0, v[68:69]
	v_mul_u32_u24_e32 v0, 0x90, v92
	v_lshlrev_b32_e32 v76, 11, v92
	v_mov_b32_e32 v77, v1
	s_waitcnt lgkmcnt(0)
	v_lshl_add_u64 v[66:67], v[86:87], 0, v[74:75]
	v_lshl_add_u64 v[72:73], v[88:89], 0, v[74:75]
	v_lshl_add_u64 v[68:69], v[84:85], 0, v[74:75]
	v_add3_u32 v0, v151, v74, v0
	v_lshlrev_b32_e32 v74, 12, v92
	v_lshl_add_u64 v[76:77], v[70:71], 0, v[76:77]
	v_lshl_add_u64 v[66:67], v[66:67], 0, v[98:99]
	v_lshl_add_u64 v[82:83], v[72:73], 0, v[74:75]
	global_load_dwordx4 v[180:183], v[66:67], off
	v_mov_b32_e32 v212, v92
	v_lshlrev_b32_e32 v184, 11, v212
	v_mov_b32_e32 v185, v1
	v_lshl_add_u64 v[184:185], v[70:71], 0, v[184:185]
	global_load_dwordx2 v[184:185], v[184:185], off offset:64
	v_lshlrev_b32_e32 v192, 12, v212
	v_mov_b32_e32 v193, v1
	v_lshl_add_u64 v[192:193], v[72:73], 0, v[192:193]
	global_load_dwordx4 v[192:195], v[192:193], off offset:128
	v_or_b32_e32 v212, 8, v92
	v_lshlrev_b32_e32 v186, 11, v212
	v_mov_b32_e32 v187, v1
	v_lshl_add_u64 v[186:187], v[70:71], 0, v[186:187]
	global_load_dwordx2 v[186:187], v[186:187], off offset:64
	v_lshlrev_b32_e32 v200, 12, v212
	v_mov_b32_e32 v201, v1
	v_lshl_add_u64 v[200:201], v[72:73], 0, v[200:201]
	global_load_dwordx4 v[200:203], v[200:201], off offset:128
	v_or_b32_e32 v212, 16, v92
	v_lshlrev_b32_e32 v188, 11, v212
	v_mov_b32_e32 v189, v1
	v_lshl_add_u64 v[188:189], v[70:71], 0, v[188:189]
	global_load_dwordx2 v[188:189], v[188:189], off offset:64
	v_lshlrev_b32_e32 v204, 12, v212
	v_mov_b32_e32 v205, v1
	v_lshl_add_u64 v[204:205], v[72:73], 0, v[204:205]
	global_load_dwordx4 v[204:207], v[204:205], off offset:128
	v_or_b32_e32 v212, 24, v92
	v_lshlrev_b32_e32 v190, 11, v212
	v_mov_b32_e32 v191, v1
	v_lshl_add_u64 v[190:191], v[70:71], 0, v[190:191]
	global_load_dwordx2 v[190:191], v[190:191], off offset:64
	v_lshlrev_b32_e32 v208, 12, v212
	v_mov_b32_e32 v209, v1
	v_lshl_add_u64 v[208:209], v[72:73], 0, v[208:209]
	global_load_dwordx4 v[208:211], v[208:209], off offset:128
	s_waitcnt vmcnt(6)
	v_mov_b32_e32 v86, v184
	v_mov_b32_e32 v87, v185
	v_lshl_add_u64 v[88:89], v[68:69], 0, v[74:75]
	ds_read_b128 v[74:77], v0
	v_mov_b32_e32 v78, v180
	v_mov_b32_e32 v79, v181
	v_mov_b32_e32 v80, v182
	v_mov_b32_e32 v81, v183
	s_nop 0
	v_mov_b32_e32 v82, v192
	v_mov_b32_e32 v83, v193
	v_mov_b32_e32 v84, v194
	v_mov_b32_e32 v85, v195
	v_and_b32_e32 v91, 0xffff0000, v86
	v_lshlrev_b32_e32 v90, 16, v86
	v_pk_add_f32 v[82:83], v[82:83], v[90:91]
	s_waitcnt lgkmcnt(0)
	v_pk_fma_f32 v[74:75], v[74:75], v[78:79], v[82:83]
	v_and_b32_e32 v79, 0xffff0000, v87
	v_lshlrev_b32_e32 v78, 16, v87
	v_pk_add_f32 v[78:79], v[84:85], v[78:79]
	s_nop 0
	v_pk_fma_f32 v[76:77], v[76:77], v[80:81], v[78:79]
	global_store_dwordx4 v[88:89], v[74:77], off offset:128
	s_nop 1
	v_or_b32_e32 v76, 8, v92
	v_lshlrev_b32_e32 v74, 12, v76
	v_lshlrev_b32_e32 v76, 11, v76
	v_mov_b32_e32 v77, v1
	v_mov_b32_e32 v75, v1
	v_lshl_add_u64 v[76:77], v[70:71], 0, v[76:77]
	v_lshl_add_u64 v[82:83], v[72:73], 0, v[74:75]
	s_waitcnt vmcnt(5)
	v_mov_b32_e32 v86, v186
	v_mov_b32_e32 v87, v187
	v_lshl_add_u64 v[88:89], v[68:69], 0, v[74:75]
	ds_read_b128 v[74:77], v0 offset:1152
	v_mov_b32_e32 v78, v180
	v_mov_b32_e32 v79, v181
	v_mov_b32_e32 v80, v182
	v_mov_b32_e32 v81, v183
	s_nop 0
	v_mov_b32_e32 v82, v200
	v_mov_b32_e32 v83, v201
	v_mov_b32_e32 v84, v202
	v_mov_b32_e32 v85, v203
	v_and_b32_e32 v91, 0xffff0000, v86
	v_lshlrev_b32_e32 v90, 16, v86
	v_pk_add_f32 v[82:83], v[82:83], v[90:91]
	s_waitcnt lgkmcnt(0)
	v_pk_fma_f32 v[74:75], v[74:75], v[78:79], v[82:83]
	v_and_b32_e32 v79, 0xffff0000, v87
	v_lshlrev_b32_e32 v78, 16, v87
	v_pk_add_f32 v[78:79], v[84:85], v[78:79]
	s_nop 0
	v_pk_fma_f32 v[76:77], v[76:77], v[80:81], v[78:79]
	global_store_dwordx4 v[88:89], v[74:77], off offset:128
	s_nop 1
	v_or_b32_e32 v76, 16, v92
	v_lshlrev_b32_e32 v74, 12, v76
	v_lshlrev_b32_e32 v76, 11, v76
	v_mov_b32_e32 v77, v1
	v_mov_b32_e32 v75, v1
	v_lshl_add_u64 v[76:77], v[70:71], 0, v[76:77]
	v_lshl_add_u64 v[82:83], v[72:73], 0, v[74:75]
	s_waitcnt vmcnt(4)
	v_mov_b32_e32 v86, v188
	v_mov_b32_e32 v87, v189
	v_lshl_add_u64 v[88:89], v[68:69], 0, v[74:75]
	ds_read_b128 v[74:77], v0 offset:2304
	v_mov_b32_e32 v78, v180
	v_mov_b32_e32 v79, v181
	v_mov_b32_e32 v80, v182
	v_mov_b32_e32 v81, v183
	s_nop 0
	v_mov_b32_e32 v82, v204
	v_mov_b32_e32 v83, v205
	v_mov_b32_e32 v84, v206
	v_mov_b32_e32 v85, v207
	v_and_b32_e32 v91, 0xffff0000, v86
	v_lshlrev_b32_e32 v90, 16, v86
	v_pk_add_f32 v[82:83], v[82:83], v[90:91]
	s_waitcnt lgkmcnt(0)
	v_pk_fma_f32 v[74:75], v[74:75], v[78:79], v[82:83]
	v_and_b32_e32 v79, 0xffff0000, v87
	v_lshlrev_b32_e32 v78, 16, v87
	v_pk_add_f32 v[78:79], v[84:85], v[78:79]
	s_nop 0
	v_pk_fma_f32 v[76:77], v[76:77], v[80:81], v[78:79]
	v_or_b32_e32 v78, 24, v92
	global_store_dwordx4 v[88:89], v[74:77], off offset:128
	s_nop 1
	v_lshlrev_b32_e32 v74, 12, v78
	v_mov_b32_e32 v75, v1
	v_lshl_add_u64 v[76:77], v[72:73], 0, v[74:75]
	v_lshlrev_b32_e32 v72, 11, v78
	v_mov_b32_e32 v73, v1
	v_lshl_add_u64 v[70:71], v[70:71], 0, v[72:73]
	s_waitcnt vmcnt(3)
	v_mov_b32_e32 v80, v190
	v_mov_b32_e32 v81, v191
	v_lshl_add_u64 v[82:83], v[68:69], 0, v[74:75]
	ds_read_b128 v[68:71], v0 offset:3456
	v_mov_b32_e32 v72, v180
	v_mov_b32_e32 v73, v181
	v_mov_b32_e32 v74, v182
	v_mov_b32_e32 v75, v183
	s_nop 0
	v_mov_b32_e32 v76, v208
	v_mov_b32_e32 v77, v209
	v_mov_b32_e32 v78, v210
	v_mov_b32_e32 v79, v211
	v_and_b32_e32 v67, 0xffff0000, v80
	v_lshlrev_b32_e32 v66, 16, v80
	v_pk_add_f32 v[66:67], v[76:77], v[66:67]
	s_waitcnt lgkmcnt(0)
	v_pk_fma_f32 v[66:67], v[68:69], v[72:73], v[66:67]
	v_and_b32_e32 v69, 0xffff0000, v81
	v_lshlrev_b32_e32 v68, 16, v81
	v_pk_add_f32 v[68:69], v[78:79], v[68:69]
	s_nop 0
	v_pk_fma_f32 v[68:69], v[70:71], v[74:75], v[68:69]
	global_store_dwordx4 v[82:83], v[66:69], off offset:128
	s_nop 1
	v_or_b32_e32 v66, 64, v130
	v_add_u32_e32 v0, v66, v155
	v_ashrrev_i32_e32 v0, 14, v0
	v_mul_i32_i24_e32 v67, 0x4000, v0
	v_sub_u32_e32 v67, v66, v67
	v_add_u32_e32 v72, 0x100, v67
	v_mul_i32_i24_e32 v68, 0xc00, v0
	v_mul_hi_i32_i24_e32 v71, 0x4100, v0
	v_mul_i32_i24_e32 v70, 0x4100, v0
	v_ashrrev_i32_e32 v73, 31, v72
	v_mov_b32_e32 v0, v179
	v_lshl_add_u64 v[70:71], v[70:71], 0, v[72:73]
	v_ashrrev_i32_e32 v69, 31, v68
	v_and_b32_e32 v72, 31, v0
	v_bfe_u32 v73, v0, 5, 1
	v_mul_u32_u24_e32 v73, 0x240, v73
	v_lshlrev_b32_e32 v72, 2, v72
	v_add3_u32 v72, v151, v73, v72
	ds_write2_b32 v72, v50, v51 offset1:36
	ds_write2_b32 v72, v52, v53 offset0:72 offset1:108
	v_add_u32_e32 v50, 0x400, v72
	ds_write2_b32 v50, v54, v55 offset0:32 offset1:68
	ds_write2_b32 v50, v56, v57 offset0:104 offset1:140
	v_add_u32_e32 v50, 0x800, v72
	ds_write2_b32 v50, v58, v59 offset0:64 offset1:100
	ds_write2_b32 v50, v60, v61 offset0:136 offset1:172
	v_add_u32_e32 v50, 0xc00, v72
	v_lshlrev_b64 v[70:71], 11, v[70:71]
	v_ashrrev_i32_e32 v67, 31, v66
	ds_write2_b32 v50, v62, v63 offset0:96 offset1:132
	ds_write2_b32 v50, v64, v65 offset0:168 offset1:204
	v_lshl_add_u64 v[50:51], v[68:69], 2, s[54:55]
	v_lshlrev_b32_e32 v60, 2, v0
	v_lshl_add_u64 v[54:55], v[50:51], 0, s[2:3]
	v_lshl_add_u64 v[50:51], s[0:1], 0, v[70:71]
	v_lshlrev_b64 v[52:53], 12, v[66:67]
	v_and_b32_e32 v60, 28, v60
	v_lshl_add_u64 v[50:51], v[50:51], 0, v[116:117]
	v_lshl_add_u64 v[56:57], s[36:37], 0, v[52:53]
	v_lshl_add_u64 v[52:53], s[52:53], 0, v[52:53]
	v_lshlrev_b32_e32 v66, 2, v60
	v_lshlrev_b32_e32 v60, 1, v60
	v_mov_b32_e32 v61, v1
	v_bfe_u32 v84, v0, 3, 3
	v_lshl_add_u64 v[58:59], v[54:55], 0, v[114:115]
	v_lshl_add_u64 v[56:57], v[56:57], 0, v[114:115]
	v_lshl_add_u64 v[52:53], v[52:53], 0, v[114:115]
	v_mov_b32_e32 v67, v1
	v_lshl_add_u64 v[62:63], v[50:51], 0, v[60:61]
	v_mul_u32_u24_e32 v0, 0x90, v84
	v_lshlrev_b32_e32 v68, 11, v84
	v_mov_b32_e32 v69, v1
	s_waitcnt lgkmcnt(0)
	v_lshl_add_u64 v[58:59], v[58:59], 0, v[66:67]
	v_lshl_add_u64 v[64:65], v[56:57], 0, v[66:67]
	v_lshl_add_u64 v[60:61], v[52:53], 0, v[66:67]
	v_add3_u32 v0, v151, v66, v0
	v_lshlrev_b32_e32 v66, 12, v84
	v_lshl_add_u64 v[68:69], v[62:63], 0, v[68:69]
	v_lshl_add_u64 v[74:75], v[64:65], 0, v[66:67]
	global_load_dwordx4 v[180:183], v[58:59], off
	v_mov_b32_e32 v212, v84
	v_lshlrev_b32_e32 v184, 11, v212
	v_mov_b32_e32 v185, v1
	v_lshl_add_u64 v[184:185], v[62:63], 0, v[184:185]
	global_load_dwordx2 v[184:185], v[184:185], off
	v_lshlrev_b32_e32 v192, 12, v212
	v_mov_b32_e32 v193, v1
	v_lshl_add_u64 v[192:193], v[64:65], 0, v[192:193]
	global_load_dwordx4 v[192:195], v[192:193], off
	v_or_b32_e32 v212, 8, v84
	v_lshlrev_b32_e32 v186, 11, v212
	v_mov_b32_e32 v187, v1
	v_lshl_add_u64 v[186:187], v[62:63], 0, v[186:187]
	global_load_dwordx2 v[186:187], v[186:187], off
	v_lshlrev_b32_e32 v200, 12, v212
	v_mov_b32_e32 v201, v1
	v_lshl_add_u64 v[200:201], v[64:65], 0, v[200:201]
	global_load_dwordx4 v[200:203], v[200:201], off
	v_or_b32_e32 v212, 16, v84
	v_lshlrev_b32_e32 v188, 11, v212
	v_mov_b32_e32 v189, v1
	v_lshl_add_u64 v[188:189], v[62:63], 0, v[188:189]
	global_load_dwordx2 v[188:189], v[188:189], off
	v_lshlrev_b32_e32 v204, 12, v212
	v_mov_b32_e32 v205, v1
	v_lshl_add_u64 v[204:205], v[64:65], 0, v[204:205]
	global_load_dwordx4 v[204:207], v[204:205], off
	v_or_b32_e32 v212, 24, v84
	v_lshlrev_b32_e32 v190, 11, v212
	v_mov_b32_e32 v191, v1
	v_lshl_add_u64 v[190:191], v[62:63], 0, v[190:191]
	global_load_dwordx2 v[190:191], v[190:191], off
	v_lshlrev_b32_e32 v208, 12, v212
	v_mov_b32_e32 v209, v1
	v_lshl_add_u64 v[208:209], v[64:65], 0, v[208:209]
	global_load_dwordx4 v[208:211], v[208:209], off
	s_waitcnt vmcnt(6)
	v_mov_b32_e32 v78, v184
	v_mov_b32_e32 v79, v185
	v_lshl_add_u64 v[80:81], v[60:61], 0, v[66:67]
	ds_read_b128 v[66:69], v0
	v_mov_b32_e32 v70, v180
	v_mov_b32_e32 v71, v181
	v_mov_b32_e32 v72, v182
	v_mov_b32_e32 v73, v183
	s_nop 0
	v_mov_b32_e32 v74, v192
	v_mov_b32_e32 v75, v193
	v_mov_b32_e32 v76, v194
	v_mov_b32_e32 v77, v195
	v_and_b32_e32 v83, 0xffff0000, v78
	v_lshlrev_b32_e32 v82, 16, v78
	v_pk_add_f32 v[74:75], v[74:75], v[82:83]
	s_waitcnt lgkmcnt(0)
	v_pk_fma_f32 v[66:67], v[66:67], v[70:71], v[74:75]
	v_and_b32_e32 v71, 0xffff0000, v79
	v_lshlrev_b32_e32 v70, 16, v79
	v_pk_add_f32 v[70:71], v[76:77], v[70:71]
	s_nop 0
	v_pk_fma_f32 v[68:69], v[68:69], v[72:73], v[70:71]
	global_store_dwordx4 v[80:81], v[66:69], off
	s_nop 1
	v_or_b32_e32 v68, 8, v84
	v_lshlrev_b32_e32 v66, 12, v68
	v_lshlrev_b32_e32 v68, 11, v68
	v_mov_b32_e32 v69, v1
	v_mov_b32_e32 v67, v1
	v_lshl_add_u64 v[68:69], v[62:63], 0, v[68:69]
	v_lshl_add_u64 v[74:75], v[64:65], 0, v[66:67]
	s_waitcnt vmcnt(5)
	v_mov_b32_e32 v78, v186
	v_mov_b32_e32 v79, v187
	v_lshl_add_u64 v[80:81], v[60:61], 0, v[66:67]
	ds_read_b128 v[66:69], v0 offset:1152
	v_mov_b32_e32 v70, v180
	v_mov_b32_e32 v71, v181
	v_mov_b32_e32 v72, v182
	v_mov_b32_e32 v73, v183
	s_nop 0
	v_mov_b32_e32 v74, v200
	v_mov_b32_e32 v75, v201
	v_mov_b32_e32 v76, v202
	v_mov_b32_e32 v77, v203
	v_and_b32_e32 v83, 0xffff0000, v78
	v_lshlrev_b32_e32 v82, 16, v78
	v_pk_add_f32 v[74:75], v[74:75], v[82:83]
	s_waitcnt lgkmcnt(0)
	v_pk_fma_f32 v[66:67], v[66:67], v[70:71], v[74:75]
	v_and_b32_e32 v71, 0xffff0000, v79
	v_lshlrev_b32_e32 v70, 16, v79
	v_pk_add_f32 v[70:71], v[76:77], v[70:71]
	s_nop 0
	v_pk_fma_f32 v[68:69], v[68:69], v[72:73], v[70:71]
	global_store_dwordx4 v[80:81], v[66:69], off
	s_nop 1
	v_or_b32_e32 v68, 16, v84
	v_lshlrev_b32_e32 v66, 12, v68
	v_lshlrev_b32_e32 v68, 11, v68
	v_mov_b32_e32 v69, v1
	v_mov_b32_e32 v67, v1
	v_lshl_add_u64 v[68:69], v[62:63], 0, v[68:69]
	v_lshl_add_u64 v[74:75], v[64:65], 0, v[66:67]
	s_waitcnt vmcnt(4)
	v_mov_b32_e32 v78, v188
	v_mov_b32_e32 v79, v189
	v_lshl_add_u64 v[80:81], v[60:61], 0, v[66:67]
	ds_read_b128 v[66:69], v0 offset:2304
	v_mov_b32_e32 v70, v180
	v_mov_b32_e32 v71, v181
	v_mov_b32_e32 v72, v182
	v_mov_b32_e32 v73, v183
	s_nop 0
	v_mov_b32_e32 v74, v204
	v_mov_b32_e32 v75, v205
	v_mov_b32_e32 v76, v206
	v_mov_b32_e32 v77, v207
	v_and_b32_e32 v83, 0xffff0000, v78
	v_lshlrev_b32_e32 v82, 16, v78
	v_pk_add_f32 v[74:75], v[74:75], v[82:83]
	s_waitcnt lgkmcnt(0)
	v_pk_fma_f32 v[66:67], v[66:67], v[70:71], v[74:75]
	v_and_b32_e32 v71, 0xffff0000, v79
	v_lshlrev_b32_e32 v70, 16, v79
	v_pk_add_f32 v[70:71], v[76:77], v[70:71]
	s_nop 0
	v_pk_fma_f32 v[68:69], v[68:69], v[72:73], v[70:71]
	v_or_b32_e32 v70, 24, v84
	global_store_dwordx4 v[80:81], v[66:69], off
	s_nop 1
	v_lshlrev_b32_e32 v66, 12, v70
	v_mov_b32_e32 v67, v1
	v_lshl_add_u64 v[68:69], v[64:65], 0, v[66:67]
	v_lshlrev_b32_e32 v64, 11, v70
	v_mov_b32_e32 v65, v1
	v_lshl_add_u64 v[62:63], v[62:63], 0, v[64:65]
	s_waitcnt vmcnt(3)
	v_mov_b32_e32 v72, v190
	v_mov_b32_e32 v73, v191
	v_lshl_add_u64 v[74:75], v[60:61], 0, v[66:67]
	ds_read_b128 v[60:63], v0 offset:3456
	v_mov_b32_e32 v64, v180
	v_mov_b32_e32 v65, v181
	v_mov_b32_e32 v66, v182
	v_mov_b32_e32 v67, v183
	s_nop 0
	v_mov_b32_e32 v68, v208
	v_mov_b32_e32 v69, v209
	v_mov_b32_e32 v70, v210
	v_mov_b32_e32 v71, v211
	v_and_b32_e32 v59, 0xffff0000, v72
	v_lshlrev_b32_e32 v58, 16, v72
	v_pk_add_f32 v[58:59], v[68:69], v[58:59]
	s_waitcnt lgkmcnt(0)
	v_pk_fma_f32 v[58:59], v[60:61], v[64:65], v[58:59]
	v_and_b32_e32 v61, 0xffff0000, v73
	v_lshlrev_b32_e32 v60, 16, v73
	v_pk_add_f32 v[60:61], v[70:71], v[60:61]
	s_nop 0
	v_pk_fma_f32 v[60:61], v[62:63], v[66:67], v[60:61]
	global_store_dwordx4 v[74:75], v[58:61], off
	v_mov_b32_e32 v0, v179
	s_nop 0
	v_and_b32_e32 v58, 31, v0
	v_bfe_u32 v59, v0, 5, 1
	v_mul_u32_u24_e32 v59, 0x240, v59
	v_lshlrev_b32_e32 v58, 2, v58
	v_add3_u32 v58, v151, v59, v58
	ds_write2_b32 v58, v34, v35 offset1:36
	ds_write2_b32 v58, v36, v37 offset0:72 offset1:108
	v_add_u32_e32 v34, 0x400, v58
	ds_write2_b32 v34, v38, v39 offset0:32 offset1:68
	ds_write2_b32 v34, v40, v41 offset0:104 offset1:140
	v_add_u32_e32 v34, 0x800, v58
	ds_write2_b32 v34, v42, v43 offset0:64 offset1:100
	ds_write2_b32 v34, v44, v45 offset0:136 offset1:172
	v_add_u32_e32 v34, 0xc00, v58
	ds_write2_b32 v34, v46, v47 offset0:96 offset1:132
	ds_write2_b32 v34, v48, v49 offset0:168 offset1:204
	v_lshlrev_b32_e32 v34, 2, v0
	v_and_b32_e32 v36, 28, v34
	v_lshlrev_b32_e32 v42, 2, v36
	v_lshlrev_b32_e32 v36, 1, v36
	v_mov_b32_e32 v37, v1
	v_bfe_u32 v60, v0, 3, 3
	v_mov_b32_e32 v43, v1
	v_lshl_add_u64 v[38:39], v[50:51], 0, v[36:37]
	v_mul_u32_u24_e32 v0, 0x90, v60
	v_lshlrev_b32_e32 v44, 11, v60
	v_mov_b32_e32 v45, v1
	s_waitcnt lgkmcnt(0)
	v_lshl_add_u64 v[34:35], v[54:55], 0, v[42:43]
	v_lshl_add_u64 v[40:41], v[56:57], 0, v[42:43]
	v_lshl_add_u64 v[36:37], v[52:53], 0, v[42:43]
	v_add3_u32 v0, v151, v42, v0
	v_lshlrev_b32_e32 v42, 12, v60
	v_lshl_add_u64 v[44:45], v[38:39], 0, v[44:45]
	v_lshl_add_u64 v[34:35], v[34:35], 0, v[98:99]
	v_lshl_add_u64 v[50:51], v[40:41], 0, v[42:43]
	global_load_dwordx4 v[180:183], v[34:35], off
	v_mov_b32_e32 v212, v60
	v_lshlrev_b32_e32 v184, 11, v212
	v_mov_b32_e32 v185, v1
	v_lshl_add_u64 v[184:185], v[38:39], 0, v[184:185]
	global_load_dwordx2 v[184:185], v[184:185], off offset:64
	v_lshlrev_b32_e32 v192, 12, v212
	v_mov_b32_e32 v193, v1
	v_lshl_add_u64 v[192:193], v[40:41], 0, v[192:193]
	global_load_dwordx4 v[192:195], v[192:193], off offset:128
	v_or_b32_e32 v212, 8, v60
	v_lshlrev_b32_e32 v186, 11, v212
	v_mov_b32_e32 v187, v1
	v_lshl_add_u64 v[186:187], v[38:39], 0, v[186:187]
	global_load_dwordx2 v[186:187], v[186:187], off offset:64
	v_lshlrev_b32_e32 v200, 12, v212
	v_mov_b32_e32 v201, v1
	v_lshl_add_u64 v[200:201], v[40:41], 0, v[200:201]
	global_load_dwordx4 v[200:203], v[200:201], off offset:128
	v_or_b32_e32 v212, 16, v60
	v_lshlrev_b32_e32 v188, 11, v212
	v_mov_b32_e32 v189, v1
	v_lshl_add_u64 v[188:189], v[38:39], 0, v[188:189]
	global_load_dwordx2 v[188:189], v[188:189], off offset:64
	v_lshlrev_b32_e32 v204, 12, v212
	v_mov_b32_e32 v205, v1
	v_lshl_add_u64 v[204:205], v[40:41], 0, v[204:205]
	global_load_dwordx4 v[204:207], v[204:205], off offset:128
	v_or_b32_e32 v212, 24, v60
	v_lshlrev_b32_e32 v190, 11, v212
	v_mov_b32_e32 v191, v1
	v_lshl_add_u64 v[190:191], v[38:39], 0, v[190:191]
	global_load_dwordx2 v[190:191], v[190:191], off offset:64
	v_lshlrev_b32_e32 v208, 12, v212
	v_mov_b32_e32 v209, v1
	v_lshl_add_u64 v[208:209], v[40:41], 0, v[208:209]
	global_load_dwordx4 v[208:211], v[208:209], off offset:128
	s_waitcnt vmcnt(6)
	v_mov_b32_e32 v54, v184
	v_mov_b32_e32 v55, v185
	v_lshl_add_u64 v[56:57], v[36:37], 0, v[42:43]
	ds_read_b128 v[42:45], v0
	v_mov_b32_e32 v46, v180
	v_mov_b32_e32 v47, v181
	v_mov_b32_e32 v48, v182
	v_mov_b32_e32 v49, v183
	s_nop 0
	v_mov_b32_e32 v50, v192
	v_mov_b32_e32 v51, v193
	v_mov_b32_e32 v52, v194
	v_mov_b32_e32 v53, v195
	v_and_b32_e32 v59, 0xffff0000, v54
	v_lshlrev_b32_e32 v58, 16, v54
	v_pk_add_f32 v[50:51], v[50:51], v[58:59]
	s_waitcnt lgkmcnt(0)
	v_pk_fma_f32 v[42:43], v[42:43], v[46:47], v[50:51]
	v_and_b32_e32 v47, 0xffff0000, v55
	v_lshlrev_b32_e32 v46, 16, v55
	v_pk_add_f32 v[46:47], v[52:53], v[46:47]
	s_nop 0
	v_pk_fma_f32 v[44:45], v[44:45], v[48:49], v[46:47]
	global_store_dwordx4 v[56:57], v[42:45], off offset:128
	s_nop 1
	v_or_b32_e32 v44, 8, v60
	v_lshlrev_b32_e32 v42, 12, v44
	v_lshlrev_b32_e32 v44, 11, v44
	v_mov_b32_e32 v45, v1
	v_mov_b32_e32 v43, v1
	v_lshl_add_u64 v[44:45], v[38:39], 0, v[44:45]
	v_lshl_add_u64 v[50:51], v[40:41], 0, v[42:43]
	s_waitcnt vmcnt(5)
	v_mov_b32_e32 v54, v186
	v_mov_b32_e32 v55, v187
	v_lshl_add_u64 v[56:57], v[36:37], 0, v[42:43]
	ds_read_b128 v[42:45], v0 offset:1152
	v_mov_b32_e32 v46, v180
	v_mov_b32_e32 v47, v181
	v_mov_b32_e32 v48, v182
	v_mov_b32_e32 v49, v183
	s_nop 0
	v_mov_b32_e32 v50, v200
	v_mov_b32_e32 v51, v201
	v_mov_b32_e32 v52, v202
	v_mov_b32_e32 v53, v203
	v_and_b32_e32 v59, 0xffff0000, v54
	v_lshlrev_b32_e32 v58, 16, v54
	v_pk_add_f32 v[50:51], v[50:51], v[58:59]
	s_waitcnt lgkmcnt(0)
	v_pk_fma_f32 v[42:43], v[42:43], v[46:47], v[50:51]
	v_and_b32_e32 v47, 0xffff0000, v55
	v_lshlrev_b32_e32 v46, 16, v55
	v_pk_add_f32 v[46:47], v[52:53], v[46:47]
	s_nop 0
	v_pk_fma_f32 v[44:45], v[44:45], v[48:49], v[46:47]
	global_store_dwordx4 v[56:57], v[42:45], off offset:128
	s_nop 1
	v_or_b32_e32 v44, 16, v60
	v_lshlrev_b32_e32 v42, 12, v44
	v_lshlrev_b32_e32 v44, 11, v44
	v_mov_b32_e32 v45, v1
	v_mov_b32_e32 v43, v1
	v_lshl_add_u64 v[44:45], v[38:39], 0, v[44:45]
	v_lshl_add_u64 v[50:51], v[40:41], 0, v[42:43]
	s_waitcnt vmcnt(4)
	v_mov_b32_e32 v54, v188
	v_mov_b32_e32 v55, v189
	v_lshl_add_u64 v[56:57], v[36:37], 0, v[42:43]
	ds_read_b128 v[42:45], v0 offset:2304
	v_mov_b32_e32 v46, v180
	v_mov_b32_e32 v47, v181
	v_mov_b32_e32 v48, v182
	v_mov_b32_e32 v49, v183
	s_nop 0
	v_mov_b32_e32 v50, v204
	v_mov_b32_e32 v51, v205
	v_mov_b32_e32 v52, v206
	v_mov_b32_e32 v53, v207
	v_and_b32_e32 v59, 0xffff0000, v54
	v_lshlrev_b32_e32 v58, 16, v54
	v_pk_add_f32 v[50:51], v[50:51], v[58:59]
	s_waitcnt lgkmcnt(0)
	v_pk_fma_f32 v[42:43], v[42:43], v[46:47], v[50:51]
	v_and_b32_e32 v47, 0xffff0000, v55
	v_lshlrev_b32_e32 v46, 16, v55
	v_pk_add_f32 v[46:47], v[52:53], v[46:47]
	s_nop 0
	v_pk_fma_f32 v[44:45], v[44:45], v[48:49], v[46:47]
	v_or_b32_e32 v46, 24, v60
	global_store_dwordx4 v[56:57], v[42:45], off offset:128
	s_nop 1
	v_lshlrev_b32_e32 v42, 12, v46
	v_mov_b32_e32 v43, v1
	v_lshl_add_u64 v[44:45], v[40:41], 0, v[42:43]
	v_lshlrev_b32_e32 v40, 11, v46
	v_mov_b32_e32 v41, v1
	v_lshl_add_u64 v[38:39], v[38:39], 0, v[40:41]
	s_waitcnt vmcnt(3)
	v_mov_b32_e32 v48, v190
	v_mov_b32_e32 v49, v191
	v_lshl_add_u64 v[50:51], v[36:37], 0, v[42:43]
	ds_read_b128 v[36:39], v0 offset:3456
	v_mov_b32_e32 v40, v180
	v_mov_b32_e32 v41, v181
	v_mov_b32_e32 v42, v182
	v_mov_b32_e32 v43, v183
	s_nop 0
	v_mov_b32_e32 v44, v208
	v_mov_b32_e32 v45, v209
	v_mov_b32_e32 v46, v210
	v_mov_b32_e32 v47, v211
	v_and_b32_e32 v35, 0xffff0000, v48
	v_lshlrev_b32_e32 v34, 16, v48
	v_pk_add_f32 v[34:35], v[44:45], v[34:35]
	s_waitcnt lgkmcnt(0)
	v_pk_fma_f32 v[34:35], v[36:37], v[40:41], v[34:35]
	v_and_b32_e32 v37, 0xffff0000, v49
	v_lshlrev_b32_e32 v36, 16, v49
	v_pk_add_f32 v[36:37], v[46:47], v[36:37]
	s_nop 0
	v_pk_fma_f32 v[36:37], v[38:39], v[42:43], v[36:37]
	global_store_dwordx4 v[50:51], v[34:37], off offset:128
	s_nop 1
	v_or_b32_e32 v34, 0x60, v130
	v_add_u32_e32 v0, v34, v155
	v_ashrrev_i32_e32 v0, 14, v0
	v_mul_i32_i24_e32 v35, 0x4000, v0
	v_sub_u32_e32 v35, v34, v35
	v_add_u32_e32 v40, 0x100, v35
	v_mul_i32_i24_e32 v36, 0xc00, v0
	v_mul_hi_i32_i24_e32 v39, 0x4100, v0
	v_mul_i32_i24_e32 v38, 0x4100, v0
	v_ashrrev_i32_e32 v41, 31, v40
	v_mov_b32_e32 v0, v179
	v_lshl_add_u64 v[38:39], v[38:39], 0, v[40:41]
	v_ashrrev_i32_e32 v37, 31, v36
	v_and_b32_e32 v40, 31, v0
	v_bfe_u32 v41, v0, 5, 1
	v_mul_u32_u24_e32 v41, 0x240, v41
	v_lshlrev_b32_e32 v40, 2, v40
	v_add3_u32 v40, v151, v41, v40
	ds_write2_b32 v40, v18, v19 offset1:36
	ds_write2_b32 v40, v20, v21 offset0:72 offset1:108
	v_add_u32_e32 v18, 0x400, v40
	ds_write2_b32 v18, v22, v23 offset0:32 offset1:68
	ds_write2_b32 v18, v24, v25 offset0:104 offset1:140
	v_add_u32_e32 v18, 0x800, v40
	ds_write2_b32 v18, v26, v27 offset0:64 offset1:100
	ds_write2_b32 v18, v28, v29 offset0:136 offset1:172
	v_add_u32_e32 v18, 0xc00, v40
	v_lshlrev_b64 v[38:39], 11, v[38:39]
	v_ashrrev_i32_e32 v35, 31, v34
	ds_write2_b32 v18, v30, v31 offset0:96 offset1:132
	ds_write2_b32 v18, v32, v33 offset0:168 offset1:204
	v_lshl_add_u64 v[18:19], v[36:37], 2, s[54:55]
	v_lshlrev_b32_e32 v28, 2, v0
	v_lshl_add_u64 v[20:21], v[18:19], 0, s[2:3]
	v_lshl_add_u64 v[18:19], s[0:1], 0, v[38:39]
	v_lshlrev_b64 v[22:23], 12, v[34:35]
	v_and_b32_e32 v28, 28, v28
	v_lshl_add_u64 v[18:19], v[18:19], 0, v[116:117]
	v_lshl_add_u64 v[24:25], s[36:37], 0, v[22:23]
	v_lshl_add_u64 v[22:23], s[52:53], 0, v[22:23]
	v_lshlrev_b32_e32 v34, 2, v28
	v_lshlrev_b32_e32 v28, 1, v28
	v_mov_b32_e32 v29, v1
	v_bfe_u32 v52, v0, 3, 3
	v_lshl_add_u64 v[26:27], v[20:21], 0, v[114:115]
	v_lshl_add_u64 v[24:25], v[24:25], 0, v[114:115]
	v_lshl_add_u64 v[22:23], v[22:23], 0, v[114:115]
	v_mov_b32_e32 v35, v1
	v_lshl_add_u64 v[30:31], v[18:19], 0, v[28:29]
	v_mul_u32_u24_e32 v0, 0x90, v52
	v_lshlrev_b32_e32 v36, 11, v52
	v_mov_b32_e32 v37, v1
	s_waitcnt lgkmcnt(0)
	v_lshl_add_u64 v[26:27], v[26:27], 0, v[34:35]
	v_lshl_add_u64 v[32:33], v[24:25], 0, v[34:35]
	v_lshl_add_u64 v[28:29], v[22:23], 0, v[34:35]
	v_add3_u32 v0, v151, v34, v0
	v_lshlrev_b32_e32 v34, 12, v52
	v_lshl_add_u64 v[36:37], v[30:31], 0, v[36:37]
	v_lshl_add_u64 v[42:43], v[32:33], 0, v[34:35]
	global_load_dwordx4 v[180:183], v[26:27], off
	v_mov_b32_e32 v212, v52
	v_lshlrev_b32_e32 v184, 11, v212
	v_mov_b32_e32 v185, v1
	v_lshl_add_u64 v[184:185], v[30:31], 0, v[184:185]
	global_load_dwordx2 v[184:185], v[184:185], off
	v_lshlrev_b32_e32 v192, 12, v212
	v_mov_b32_e32 v193, v1
	v_lshl_add_u64 v[192:193], v[32:33], 0, v[192:193]
	global_load_dwordx4 v[192:195], v[192:193], off
	v_or_b32_e32 v212, 8, v52
	v_lshlrev_b32_e32 v186, 11, v212
	v_mov_b32_e32 v187, v1
	v_lshl_add_u64 v[186:187], v[30:31], 0, v[186:187]
	global_load_dwordx2 v[186:187], v[186:187], off
	v_lshlrev_b32_e32 v200, 12, v212
	v_mov_b32_e32 v201, v1
	v_lshl_add_u64 v[200:201], v[32:33], 0, v[200:201]
	global_load_dwordx4 v[200:203], v[200:201], off
	v_or_b32_e32 v212, 16, v52
	v_lshlrev_b32_e32 v188, 11, v212
	v_mov_b32_e32 v189, v1
	v_lshl_add_u64 v[188:189], v[30:31], 0, v[188:189]
	global_load_dwordx2 v[188:189], v[188:189], off
	v_lshlrev_b32_e32 v204, 12, v212
	v_mov_b32_e32 v205, v1
	v_lshl_add_u64 v[204:205], v[32:33], 0, v[204:205]
	global_load_dwordx4 v[204:207], v[204:205], off
	v_or_b32_e32 v212, 24, v52
	v_lshlrev_b32_e32 v190, 11, v212
	v_mov_b32_e32 v191, v1
	v_lshl_add_u64 v[190:191], v[30:31], 0, v[190:191]
	global_load_dwordx2 v[190:191], v[190:191], off
	v_lshlrev_b32_e32 v208, 12, v212
	v_mov_b32_e32 v209, v1
	v_lshl_add_u64 v[208:209], v[32:33], 0, v[208:209]
	global_load_dwordx4 v[208:211], v[208:209], off
	s_waitcnt vmcnt(6)
	v_mov_b32_e32 v46, v184
	v_mov_b32_e32 v47, v185
	v_lshl_add_u64 v[48:49], v[28:29], 0, v[34:35]
	ds_read_b128 v[34:37], v0
	v_mov_b32_e32 v38, v180
	v_mov_b32_e32 v39, v181
	v_mov_b32_e32 v40, v182
	v_mov_b32_e32 v41, v183
	s_nop 0
	v_mov_b32_e32 v42, v192
	v_mov_b32_e32 v43, v193
	v_mov_b32_e32 v44, v194
	v_mov_b32_e32 v45, v195
	v_and_b32_e32 v51, 0xffff0000, v46
	v_lshlrev_b32_e32 v50, 16, v46
	v_pk_add_f32 v[42:43], v[42:43], v[50:51]
	s_waitcnt lgkmcnt(0)
	v_pk_fma_f32 v[34:35], v[34:35], v[38:39], v[42:43]
	v_and_b32_e32 v39, 0xffff0000, v47
	v_lshlrev_b32_e32 v38, 16, v47
	v_pk_add_f32 v[38:39], v[44:45], v[38:39]
	s_nop 0
	v_pk_fma_f32 v[36:37], v[36:37], v[40:41], v[38:39]
	global_store_dwordx4 v[48:49], v[34:37], off
	s_nop 1
	v_or_b32_e32 v36, 8, v52
	v_lshlrev_b32_e32 v34, 12, v36
	v_lshlrev_b32_e32 v36, 11, v36
	v_mov_b32_e32 v37, v1
	v_mov_b32_e32 v35, v1
	v_lshl_add_u64 v[36:37], v[30:31], 0, v[36:37]
	v_lshl_add_u64 v[42:43], v[32:33], 0, v[34:35]
	s_waitcnt vmcnt(5)
	v_mov_b32_e32 v46, v186
	v_mov_b32_e32 v47, v187
	v_lshl_add_u64 v[48:49], v[28:29], 0, v[34:35]
	ds_read_b128 v[34:37], v0 offset:1152
	v_mov_b32_e32 v38, v180
	v_mov_b32_e32 v39, v181
	v_mov_b32_e32 v40, v182
	v_mov_b32_e32 v41, v183
	s_nop 0
	v_mov_b32_e32 v42, v200
	v_mov_b32_e32 v43, v201
	v_mov_b32_e32 v44, v202
	v_mov_b32_e32 v45, v203
	v_and_b32_e32 v51, 0xffff0000, v46
	v_lshlrev_b32_e32 v50, 16, v46
	v_pk_add_f32 v[42:43], v[42:43], v[50:51]
	s_waitcnt lgkmcnt(0)
	v_pk_fma_f32 v[34:35], v[34:35], v[38:39], v[42:43]
	v_and_b32_e32 v39, 0xffff0000, v47
	v_lshlrev_b32_e32 v38, 16, v47
	v_pk_add_f32 v[38:39], v[44:45], v[38:39]
	s_nop 0
	v_pk_fma_f32 v[36:37], v[36:37], v[40:41], v[38:39]
	global_store_dwordx4 v[48:49], v[34:37], off
	s_nop 1
	v_or_b32_e32 v36, 16, v52
	v_lshlrev_b32_e32 v34, 12, v36
	v_lshlrev_b32_e32 v36, 11, v36
	v_mov_b32_e32 v37, v1
	v_mov_b32_e32 v35, v1
	v_lshl_add_u64 v[36:37], v[30:31], 0, v[36:37]
	v_lshl_add_u64 v[42:43], v[32:33], 0, v[34:35]
	s_waitcnt vmcnt(4)
	v_mov_b32_e32 v46, v188
	v_mov_b32_e32 v47, v189
	v_lshl_add_u64 v[48:49], v[28:29], 0, v[34:35]
	ds_read_b128 v[34:37], v0 offset:2304
	v_mov_b32_e32 v38, v180
	v_mov_b32_e32 v39, v181
	v_mov_b32_e32 v40, v182
	v_mov_b32_e32 v41, v183
	s_nop 0
	v_mov_b32_e32 v42, v204
	v_mov_b32_e32 v43, v205
	v_mov_b32_e32 v44, v206
	v_mov_b32_e32 v45, v207
	v_and_b32_e32 v51, 0xffff0000, v46
	v_lshlrev_b32_e32 v50, 16, v46
	v_pk_add_f32 v[42:43], v[42:43], v[50:51]
	s_waitcnt lgkmcnt(0)
	v_pk_fma_f32 v[34:35], v[34:35], v[38:39], v[42:43]
	v_and_b32_e32 v39, 0xffff0000, v47
	v_lshlrev_b32_e32 v38, 16, v47
	v_pk_add_f32 v[38:39], v[44:45], v[38:39]
	s_nop 0
	v_pk_fma_f32 v[36:37], v[36:37], v[40:41], v[38:39]
	v_or_b32_e32 v38, 24, v52
	global_store_dwordx4 v[48:49], v[34:37], off
	s_nop 1
	v_lshlrev_b32_e32 v34, 12, v38
	v_mov_b32_e32 v35, v1
	v_lshl_add_u64 v[36:37], v[32:33], 0, v[34:35]
	v_lshlrev_b32_e32 v32, 11, v38
	v_mov_b32_e32 v33, v1
	v_lshl_add_u64 v[30:31], v[30:31], 0, v[32:33]
	s_waitcnt vmcnt(3)
	v_mov_b32_e32 v40, v190
	v_mov_b32_e32 v41, v191
	v_lshl_add_u64 v[42:43], v[28:29], 0, v[34:35]
	ds_read_b128 v[28:31], v0 offset:3456
	v_mov_b32_e32 v32, v180
	v_mov_b32_e32 v33, v181
	v_mov_b32_e32 v34, v182
	v_mov_b32_e32 v35, v183
	s_nop 0
	v_mov_b32_e32 v36, v208
	v_mov_b32_e32 v37, v209
	v_mov_b32_e32 v38, v210
	v_mov_b32_e32 v39, v211
	v_and_b32_e32 v27, 0xffff0000, v40
	v_lshlrev_b32_e32 v26, 16, v40
	v_pk_add_f32 v[26:27], v[36:37], v[26:27]
	s_waitcnt lgkmcnt(0)
	v_pk_fma_f32 v[26:27], v[28:29], v[32:33], v[26:27]
	v_and_b32_e32 v29, 0xffff0000, v41
	v_lshlrev_b32_e32 v28, 16, v41
	v_pk_add_f32 v[28:29], v[38:39], v[28:29]
	s_nop 0
	v_pk_fma_f32 v[28:29], v[30:31], v[34:35], v[28:29]
	global_store_dwordx4 v[42:43], v[26:29], off
	v_mov_b32_e32 v0, v179
	s_nop 0
	v_and_b32_e32 v26, 31, v0
	v_bfe_u32 v27, v0, 5, 1
	v_mul_u32_u24_e32 v27, 0x240, v27
	v_lshlrev_b32_e32 v26, 2, v26
	v_add3_u32 v26, v151, v27, v26
	ds_write2_b32 v26, v2, v3 offset1:36
	ds_write2_b32 v26, v4, v5 offset0:72 offset1:108
	v_add_u32_e32 v2, 0x400, v26
	ds_write2_b32 v2, v6, v7 offset0:32 offset1:68
	ds_write2_b32 v2, v8, v9 offset0:104 offset1:140
	v_add_u32_e32 v2, 0x800, v26
	ds_write2_b32 v2, v10, v11 offset0:64 offset1:100
	ds_write2_b32 v2, v12, v13 offset0:136 offset1:172
	v_add_u32_e32 v2, 0xc00, v26
	ds_write2_b32 v2, v14, v15 offset0:96 offset1:132
	ds_write2_b32 v2, v16, v17 offset0:168 offset1:204
	v_lshlrev_b32_e32 v2, 2, v0
	v_and_b32_e32 v4, 28, v2
	v_lshlrev_b32_e32 v10, 2, v4
	v_lshlrev_b32_e32 v4, 1, v4
	v_mov_b32_e32 v5, v1
	v_bfe_u32 v28, v0, 3, 3
	v_mov_b32_e32 v11, v1
	v_lshl_add_u64 v[6:7], v[18:19], 0, v[4:5]
	v_mul_u32_u24_e32 v0, 0x90, v28
	v_lshlrev_b32_e32 v12, 11, v28
	v_mov_b32_e32 v13, v1
	s_waitcnt lgkmcnt(0)
	v_lshl_add_u64 v[2:3], v[20:21], 0, v[10:11]
	v_lshl_add_u64 v[8:9], v[24:25], 0, v[10:11]
	v_lshl_add_u64 v[4:5], v[22:23], 0, v[10:11]
	v_add3_u32 v0, v151, v10, v0
	v_lshlrev_b32_e32 v10, 12, v28
	v_lshl_add_u64 v[12:13], v[6:7], 0, v[12:13]
	v_lshl_add_u64 v[2:3], v[2:3], 0, v[98:99]
	v_lshl_add_u64 v[18:19], v[8:9], 0, v[10:11]
	global_load_dwordx4 v[180:183], v[2:3], off
	v_mov_b32_e32 v212, v28
	v_lshlrev_b32_e32 v184, 11, v212
	v_mov_b32_e32 v185, v1
	v_lshl_add_u64 v[184:185], v[6:7], 0, v[184:185]
	global_load_dwordx2 v[184:185], v[184:185], off offset:64
	v_lshlrev_b32_e32 v192, 12, v212
	v_mov_b32_e32 v193, v1
	v_lshl_add_u64 v[192:193], v[8:9], 0, v[192:193]
	global_load_dwordx4 v[192:195], v[192:193], off offset:128
	v_or_b32_e32 v212, 8, v28
	v_lshlrev_b32_e32 v186, 11, v212
	v_mov_b32_e32 v187, v1
	v_lshl_add_u64 v[186:187], v[6:7], 0, v[186:187]
	global_load_dwordx2 v[186:187], v[186:187], off offset:64
	v_lshlrev_b32_e32 v200, 12, v212
	v_mov_b32_e32 v201, v1
	v_lshl_add_u64 v[200:201], v[8:9], 0, v[200:201]
	global_load_dwordx4 v[200:203], v[200:201], off offset:128
	v_or_b32_e32 v212, 16, v28
	v_lshlrev_b32_e32 v188, 11, v212
	v_mov_b32_e32 v189, v1
	v_lshl_add_u64 v[188:189], v[6:7], 0, v[188:189]
	global_load_dwordx2 v[188:189], v[188:189], off offset:64
	v_lshlrev_b32_e32 v204, 12, v212
	v_mov_b32_e32 v205, v1
	v_lshl_add_u64 v[204:205], v[8:9], 0, v[204:205]
	global_load_dwordx4 v[204:207], v[204:205], off offset:128
	v_or_b32_e32 v212, 24, v28
	v_lshlrev_b32_e32 v190, 11, v212
	v_mov_b32_e32 v191, v1
	v_lshl_add_u64 v[190:191], v[6:7], 0, v[190:191]
	global_load_dwordx2 v[190:191], v[190:191], off offset:64
	v_lshlrev_b32_e32 v208, 12, v212
	v_mov_b32_e32 v209, v1
	v_lshl_add_u64 v[208:209], v[8:9], 0, v[208:209]
	global_load_dwordx4 v[208:211], v[208:209], off offset:128
	s_waitcnt vmcnt(6)
	v_mov_b32_e32 v22, v184
	v_mov_b32_e32 v23, v185
	v_lshl_add_u64 v[24:25], v[4:5], 0, v[10:11]
	ds_read_b128 v[10:13], v0
	v_mov_b32_e32 v14, v180
	v_mov_b32_e32 v15, v181
	v_mov_b32_e32 v16, v182
	v_mov_b32_e32 v17, v183
	s_nop 0
	v_mov_b32_e32 v18, v192
	v_mov_b32_e32 v19, v193
	v_mov_b32_e32 v20, v194
	v_mov_b32_e32 v21, v195
	v_and_b32_e32 v27, 0xffff0000, v22
	v_lshlrev_b32_e32 v26, 16, v22
	v_pk_add_f32 v[18:19], v[18:19], v[26:27]
	s_waitcnt lgkmcnt(0)
	v_pk_fma_f32 v[10:11], v[10:11], v[14:15], v[18:19]
	v_and_b32_e32 v15, 0xffff0000, v23
	v_lshlrev_b32_e32 v14, 16, v23
	v_pk_add_f32 v[14:15], v[20:21], v[14:15]
	s_nop 0
	v_pk_fma_f32 v[12:13], v[12:13], v[16:17], v[14:15]
	global_store_dwordx4 v[24:25], v[10:13], off offset:128
	s_nop 1
	v_or_b32_e32 v12, 8, v28
	v_lshlrev_b32_e32 v10, 12, v12
	v_lshlrev_b32_e32 v12, 11, v12
	v_mov_b32_e32 v13, v1
	v_mov_b32_e32 v11, v1
	v_lshl_add_u64 v[12:13], v[6:7], 0, v[12:13]
	v_lshl_add_u64 v[18:19], v[8:9], 0, v[10:11]
	s_waitcnt vmcnt(5)
	v_mov_b32_e32 v22, v186
	v_mov_b32_e32 v23, v187
	v_lshl_add_u64 v[24:25], v[4:5], 0, v[10:11]
	ds_read_b128 v[10:13], v0 offset:1152
	v_mov_b32_e32 v14, v180
	v_mov_b32_e32 v15, v181
	v_mov_b32_e32 v16, v182
	v_mov_b32_e32 v17, v183
	s_nop 0
	v_mov_b32_e32 v18, v200
	v_mov_b32_e32 v19, v201
	v_mov_b32_e32 v20, v202
	v_mov_b32_e32 v21, v203
	v_and_b32_e32 v27, 0xffff0000, v22
	v_lshlrev_b32_e32 v26, 16, v22
	v_pk_add_f32 v[18:19], v[18:19], v[26:27]
	s_waitcnt lgkmcnt(0)
	v_pk_fma_f32 v[10:11], v[10:11], v[14:15], v[18:19]
	v_and_b32_e32 v15, 0xffff0000, v23
	v_lshlrev_b32_e32 v14, 16, v23
	v_pk_add_f32 v[14:15], v[20:21], v[14:15]
	s_nop 0
	v_pk_fma_f32 v[12:13], v[12:13], v[16:17], v[14:15]
	global_store_dwordx4 v[24:25], v[10:13], off offset:128
	s_nop 1
	v_or_b32_e32 v12, 16, v28
	v_lshlrev_b32_e32 v10, 12, v12
	v_lshlrev_b32_e32 v12, 11, v12
	v_mov_b32_e32 v13, v1
	v_mov_b32_e32 v11, v1
	v_lshl_add_u64 v[12:13], v[6:7], 0, v[12:13]
	v_lshl_add_u64 v[18:19], v[8:9], 0, v[10:11]
	s_waitcnt vmcnt(4)
	v_mov_b32_e32 v22, v188
	v_mov_b32_e32 v23, v189
	v_lshl_add_u64 v[24:25], v[4:5], 0, v[10:11]
	ds_read_b128 v[10:13], v0 offset:2304
	v_mov_b32_e32 v14, v180
	v_mov_b32_e32 v15, v181
	v_mov_b32_e32 v16, v182
	v_mov_b32_e32 v17, v183
	s_nop 0
	v_mov_b32_e32 v18, v204
	v_mov_b32_e32 v19, v205
	v_mov_b32_e32 v20, v206
	v_mov_b32_e32 v21, v207
	v_and_b32_e32 v27, 0xffff0000, v22
	v_lshlrev_b32_e32 v26, 16, v22
	v_pk_add_f32 v[18:19], v[18:19], v[26:27]
	s_waitcnt lgkmcnt(0)
	v_pk_fma_f32 v[10:11], v[10:11], v[14:15], v[18:19]
	v_and_b32_e32 v15, 0xffff0000, v23
	v_lshlrev_b32_e32 v14, 16, v23
	v_pk_add_f32 v[14:15], v[20:21], v[14:15]
	s_nop 0
	v_pk_fma_f32 v[12:13], v[12:13], v[16:17], v[14:15]
	v_or_b32_e32 v14, 24, v28
	global_store_dwordx4 v[24:25], v[10:13], off offset:128
	s_nop 1
	v_lshlrev_b32_e32 v10, 12, v14
	v_mov_b32_e32 v11, v1
	v_lshl_add_u64 v[12:13], v[8:9], 0, v[10:11]
	v_lshlrev_b32_e32 v8, 11, v14
	v_mov_b32_e32 v9, v1
	v_lshl_add_u64 v[6:7], v[6:7], 0, v[8:9]
	s_waitcnt vmcnt(3)
	v_mov_b32_e32 v16, v190
	v_mov_b32_e32 v17, v191
	v_lshl_add_u64 v[18:19], v[4:5], 0, v[10:11]
	ds_read_b128 v[4:7], v0 offset:3456
	v_mov_b32_e32 v8, v180
	v_mov_b32_e32 v9, v181
	v_mov_b32_e32 v10, v182
	v_mov_b32_e32 v11, v183
	s_nop 0
	v_mov_b32_e32 v12, v208
	v_mov_b32_e32 v13, v209
	v_mov_b32_e32 v14, v210
	v_mov_b32_e32 v15, v211
	v_and_b32_e32 v3, 0xffff0000, v16
	v_lshlrev_b32_e32 v2, 16, v16
	v_pk_add_f32 v[2:3], v[12:13], v[2:3]
	s_waitcnt lgkmcnt(0)
	v_pk_fma_f32 v[2:3], v[4:5], v[8:9], v[2:3]
	v_and_b32_e32 v5, 0xffff0000, v17
	v_lshlrev_b32_e32 v4, 16, v17
	v_pk_add_f32 v[4:5], v[14:15], v[4:5]
	s_nop 0
	v_pk_fma_f32 v[4:5], v[6:7], v[10:11], v[4:5]
	global_store_dwordx4 v[18:19], v[2:5], off offset:128
	s_add_i32 s7, s7, s6
	s_cmpk_gt_i32 s7, 0x1ff
	v_readlane_b32 s64, v254, 55
	v_readlane_b32 s38, v254, 57
	v_readlane_b32 s42, v254, 59
	s_cselect_b64 s[0:1], -1, 0
	v_readlane_b32 s65, v254, 56
	v_readlane_b32 s39, v254, 58
	v_readlane_b32 s43, v254, 60
	s_mov_b32 s51, s27
	s_movk_i32 s37, 0x1000
	s_movk_i32 s36, 0x1ff
	s_mov_b32 s47, 0x7f800000
	s_mov_b32 s49, 0x20000
	s_mov_b32 s46, 0x4081e0d3
	s_mov_b32 s48, 0xc09de9e6
	s_mov_b64 s[44:45], 0x800
	s_branch .LBB0_21

.LBB0_293:
	s_add_i32 s2, s11, s12
	s_cmpk_gt_i32 s2, 0xcb1
	s_mov_b64 s[0:1], -1
	s_cbranch_scc1 .LBB0_292
	s_mul_hi_i32 s0, s2, 0x51eb851f
	s_lshr_b32 s1, s0, 31
	s_ashr_i32 s0, s0, 6
	s_add_i32 s0, s0, s1
	s_lshl_b32 s1, s0, 3
	s_sub_i32 s3, 0x82, s1
	s_min_u32 s3, s3, 8
	v_cvt_f32_ubyte0_e32 v0, s3
	v_rcp_iflag_f32_e32 v0, v0
	s_sub_i32 s5, 0, s3
	s_mulk_i32 s0, 0xff38
	s_add_i32 s0, s0, s2
	v_mul_f32_e32 v0, 0x4f7ffffe, v0
	v_cvt_u32_f32_e32 v0, v0
	s_abs_i32 s4, s0
	s_ashr_i32 s2, s0, 31
	v_readlane_b32 s16, v251, 2
	v_readfirstlane_b32 s7, v0
	s_mul_i32 s5, s5, s7
	s_mul_hi_u32 s5, s7, s5
	s_add_i32 s7, s7, s5
	s_mul_hi_u32 s5, s4, s7
	s_mul_i32 s7, s5, s3
	s_sub_i32 s4, s4, s7
	s_add_i32 s7, s5, 1
	s_sub_i32 s8, s4, s3
	s_cmp_ge_u32 s4, s3
	s_cselect_b32 s5, s7, s5
	s_cselect_b32 s4, s8, s4
	s_add_i32 s7, s5, 1
	s_cmp_ge_u32 s4, s3
	s_cselect_b32 s4, s7, s5
	s_xor_b32 s4, s4, s2
	s_sub_i32 s4, s4, s2
	s_mul_i32 s2, s4, s3
	s_sub_i32 s0, s0, s2
	s_add_i32 s0, s0, s1
	s_lshl_b32 s0, s0, 8
	s_lshl_b32 s4, s4, 8
	s_ashr_i32 s1, s0, 31
	s_ashr_i32 s5, s4, 31
	s_lshl_b64 s[2:3], s[0:1], 11
	s_lshl_b64 s[8:9], s[4:5], 11
	v_readlane_b32 s28, v251, 14
	v_readlane_b32 s29, v251, 15
	s_add_u32 s14, s28, s2
	v_mov_b32_e32 v0, v142
	s_addc_u32 s15, s29, s3
	s_waitcnt vmcnt(63) expcnt(7) lgkmcnt(15)
	s_barrier
	v_readlane_b32 s17, v251, 3
	v_lshl_add_u64 v[2:3], v[0:1], 1, s[14:15]
	v_add_u32_e32 v0, 32, v143
	v_readlane_b32 s16, v251, 42
	v_readfirstlane_b32 s1, v0
	s_mov_b32 m0, s1
	v_mov_b32_e32 v0, v144
	global_load_lds_dwordx4 v[2:3], off
	v_readlane_b32 s17, v251, 43
	v_lshl_add_u64 v[2:3], v[0:1], 1, s[14:15]
	v_add_u32_e32 v0, 32, v145
	s_add_u32 s16, s16, s8
	v_readfirstlane_b32 s1, v0
	s_mov_b32 m0, s1
	v_mov_b32_e32 v0, v146
	global_load_lds_dwordx4 v[2:3], off
	s_addc_u32 s17, s17, s9
	v_lshl_add_u64 v[2:3], v[0:1], 1, s[14:15]
	v_add_u32_e32 v0, 32, v147
	v_readlane_b32 s5, v254, 3
	v_readfirstlane_b32 s1, v0
	s_mov_b32 m0, s1
	v_mov_b32_e32 v0, v148
	global_load_lds_dwordx4 v[2:3], off
	s_mov_b32 s6, 0
	v_lshl_add_u64 v[2:3], v[0:1], 1, s[14:15]
	v_add_u32_e32 v0, 32, v149
	v_readlane_b32 s18, v251, 4
	v_readfirstlane_b32 s1, v0
	s_mov_b32 m0, s1
	v_mov_b32_e32 v0, v142
	global_load_lds_dwordx4 v[2:3], off
	v_readlane_b32 s19, v251, 5
	v_lshl_add_u64 v[2:3], v[0:1], 1, s[16:17]
	v_add_u32_e32 v0, s5, v143
	v_readlane_b32 s20, v251, 6
	v_readfirstlane_b32 s1, v0
	s_mov_b32 m0, s1
	v_mov_b32_e32 v0, v144
	global_load_lds_dwordx4 v[2:3], off
	v_readlane_b32 s21, v251, 7
	v_lshl_add_u64 v[2:3], v[0:1], 1, s[16:17]
	v_add_u32_e32 v0, s5, v145
	v_readlane_b32 s22, v251, 8
	v_readfirstlane_b32 s1, v0
	s_mov_b32 m0, s1
	v_mov_b32_e32 v0, v146
	global_load_lds_dwordx4 v[2:3], off
	v_readlane_b32 s23, v251, 9
	v_lshl_add_u64 v[2:3], v[0:1], 1, s[16:17]
	v_add_u32_e32 v0, s5, v147
	v_readlane_b32 s24, v251, 10
	v_readfirstlane_b32 s1, v0
	s_mov_b32 m0, s1
	v_mov_b32_e32 v0, v148
	global_load_lds_dwordx4 v[2:3], off
	v_readlane_b32 s25, v251, 11
	v_lshl_add_u64 v[2:3], v[0:1], 1, s[16:17]
	v_add_u32_e32 v0, s5, v149
	v_readlane_b32 s26, v251, 12
	v_readfirstlane_b32 s1, v0
	s_mov_b32 m0, s1
	v_readlane_b32 s1, v253, 29
	global_load_lds_dwordx4 v[2:3], off
	s_add_u32 s1, s1, s2
	v_readlane_b32 s2, v253, 30
	s_waitcnt vmcnt(0)
	s_addc_u32 s5, s2, s3
	v_readlane_b32 s2, v253, 31
	s_add_u32 s7, s2, s8
	v_readlane_b32 s2, v253, 32
	v_mov_b32_e32 v2, 0
	s_addc_u32 s8, s2, s9
	s_mov_b64 s[2:3], 0
	v_mov_b32_e32 v3, v2
	v_mov_b32_e32 v4, v2
	v_mov_b32_e32 v5, v2
	v_mov_b32_e32 v6, v2
	v_mov_b32_e32 v7, v2
	v_mov_b32_e32 v8, v2
	v_mov_b32_e32 v9, v2
	v_mov_b32_e32 v10, v2
	v_mov_b32_e32 v11, v2
	v_mov_b32_e32 v12, v2
	v_mov_b32_e32 v13, v2
	s_waitcnt vmcnt(0)
	v_mov_b32_e32 v14, v2
	v_mov_b32_e32 v15, v2
	v_mov_b32_e32 v16, v2
	v_mov_b32_e32 v17, v2
	v_mov_b32_e32 v18, v2
	v_mov_b32_e32 v19, v2
	v_mov_b32_e32 v20, v2
	v_mov_b32_e32 v21, v2
	v_mov_b32_e32 v22, v2
	v_mov_b32_e32 v23, v2
	v_mov_b32_e32 v24, v2
	v_mov_b32_e32 v25, v2
	v_mov_b32_e32 v26, v2
	v_mov_b32_e32 v27, v2
	v_mov_b32_e32 v28, v2
	v_mov_b32_e32 v29, v2
	v_mov_b32_e32 v30, v2
	v_mov_b32_e32 v31, v2
	v_mov_b32_e32 v32, v2
	v_mov_b32_e32 v33, v2
	v_mov_b32_e32 v34, v2
	v_mov_b32_e32 v35, v2
	v_mov_b32_e32 v36, v2
	v_mov_b32_e32 v37, v2
	v_mov_b32_e32 v38, v2
	v_mov_b32_e32 v39, v2
	v_mov_b32_e32 v40, v2
	v_mov_b32_e32 v41, v2
	v_mov_b32_e32 v42, v2
	v_mov_b32_e32 v43, v2
	v_mov_b32_e32 v44, v2
	v_mov_b32_e32 v45, v2
	v_mov_b32_e32 v46, v2
	v_mov_b32_e32 v47, v2
	v_mov_b32_e32 v48, v2
	v_mov_b32_e32 v49, v2
	v_mov_b32_e32 v50, v2
	v_mov_b32_e32 v51, v2
	v_mov_b32_e32 v52, v2
	v_mov_b32_e32 v53, v2
	v_mov_b32_e32 v54, v2
	v_mov_b32_e32 v55, v2
	v_mov_b32_e32 v56, v2
	v_mov_b32_e32 v57, v2
	v_mov_b32_e32 v58, v2
	v_mov_b32_e32 v59, v2
	v_mov_b32_e32 v60, v2
	v_mov_b32_e32 v61, v2
	v_mov_b32_e32 v62, v2
	v_mov_b32_e32 v63, v2
	v_mov_b32_e32 v64, v2
	v_mov_b32_e32 v65, v2
	v_mov_b32_e32 v66, v2
	v_mov_b32_e32 v67, v2
	v_mov_b32_e32 v68, v2
	v_mov_b32_e32 v69, v2
	v_mov_b32_e32 v70, v2
	v_mov_b32_e32 v71, v2
	v_mov_b32_e32 v72, v2
	v_mov_b32_e32 v73, v2
	v_mov_b32_e32 v74, v2
	v_mov_b32_e32 v75, v2
	v_mov_b32_e32 v76, v2
	v_mov_b32_e32 v77, v2
	v_mov_b32_e32 v78, v2
	v_mov_b32_e32 v79, v2
	v_mov_b32_e32 v80, v2
	v_mov_b32_e32 v81, v2
	v_mov_b32_e32 v82, v2
	v_mov_b32_e32 v83, v2
	v_mov_b32_e32 v84, v2
	v_mov_b32_e32 v85, v2
	v_mov_b32_e32 v86, v2
	v_mov_b32_e32 v87, v2
	v_mov_b32_e32 v88, v2
	v_mov_b32_e32 v89, v2
	v_mov_b32_e32 v90, v2
	v_mov_b32_e32 v91, v2
	v_mov_b32_e32 v92, v2
	v_mov_b32_e32 v93, v2
	v_mov_b32_e32 v94, v2
	v_mov_b32_e32 v95, v2
	v_mov_b32_e32 v96, v2
	v_mov_b32_e32 v97, v2
	v_mov_b32_e32 v98, v2
	v_mov_b32_e32 v99, v2
	v_mov_b32_e32 v100, v2
	v_mov_b32_e32 v101, v2
	v_mov_b32_e32 v102, v2
	v_mov_b32_e32 v103, v2
	v_mov_b32_e32 v104, v2
	v_mov_b32_e32 v105, v2
	v_mov_b32_e32 v106, v2
	v_mov_b32_e32 v107, v2
	v_mov_b32_e32 v108, v2
	v_mov_b32_e32 v109, v2
	v_mov_b32_e32 v110, v2
	v_mov_b32_e32 v111, v2
	v_mov_b32_e32 v112, v2
	v_mov_b32_e32 v113, v2
	v_mov_b32_e32 v114, v2
	v_mov_b32_e32 v115, v2
	v_mov_b32_e32 v116, v2
	v_mov_b32_e32 v117, v2
	v_mov_b32_e32 v118, v2
	v_mov_b32_e32 v119, v2
	v_mov_b32_e32 v120, v2
	v_mov_b32_e32 v121, v2
	v_mov_b32_e32 v122, v2
	v_mov_b32_e32 v123, v2
	v_mov_b32_e32 v124, v2
	v_mov_b32_e32 v125, v2
	v_mov_b32_e32 v126, v2
	v_mov_b32_e32 v127, v2
	v_mov_b32_e32 v128, v2
	v_mov_b32_e32 v129, v2
	v_readlane_b32 s27, v251, 13
	v_readlane_b32 s30, v251, 16
	v_readlane_b32 s31, v251, 17
	s_waitcnt lgkmcnt(0)
	s_barrier
	v_lshlrev_b32_e32 v159, 1, v142
	v_readfirstlane_b32 s9, v143
	v_add_u32_e32 v177, v150, v152
	v_add_u32_e32 v207, v151, v152
	v_add_u32_e32 v204, v150, v156
	v_add_u32_e32 v208, v151, v156
	v_add_u32_e32 v205, v150, v157
	v_add_u32_e32 v209, v151, v157
	v_add_u32_e32 v206, v150, v158
	v_add_u32_e32 v210, v151, v158
	s_mov_b32 s6, 7
	v_readfirstlane_b32 s66, v179
	s_cmp_ge_u32 s66, 0x100
	s_cbranch_scc0 .Lg295_np
	s_setprio 1
.Lg295_np:
	s_add_u32 m0, s9, 0x8020
	s_add_u32 s14, s1, s2
	s_addc_u32 s15, s5, s3
	global_load_lds_dwordx4 v159, s[14:15]
	s_add_u32 m0, s9, 0xa020
	s_add_u32 s14, s14, 0x20000
	s_addc_u32 s15, s15, 0
	global_load_lds_dwordx4 v159, s[14:15]
	s_add_u32 m0, s9, 0xc020
	s_add_u32 s14, s14, 0x20000
	s_addc_u32 s15, s15, 0
	global_load_lds_dwordx4 v159, s[14:15]
	s_add_u32 m0, s9, 0xe020
	s_add_u32 s14, s14, 0x20000
	s_addc_u32 s15, s15, 0
	global_load_lds_dwordx4 v159, s[14:15]
	s_add_u32 m0, s9, 0x18020
	s_add_u32 s14, s7, s2
	s_addc_u32 s15, s8, s3
	global_load_lds_dwordx4 v159, s[14:15]
	ds_read_b128 v[130:133], v177 offset:0
	ds_read_b128 v[164:167], v207 offset:0
	ds_read_b128 v[168:171], v207 offset:4096
	ds_read_b128 v[134:137], v177 offset:4096
	ds_read_b128 v[138:141], v177 offset:8192
	ds_read_b128 v[160:163], v177 offset:12288
.Lg295_loop:
	s_waitcnt lgkmcnt(4)
	v_mfma_f32_32x32x16_bf16 v[114:129], v[130:133], v[164:167], v[114:129]
	ds_read_b128 v[172:175], v204 offset:0
	s_waitcnt lgkmcnt(4)
	v_mfma_f32_32x32x16_bf16 v[98:113], v[130:133], v[168:171], v[98:113]
	ds_read_b128 v[192:195], v208 offset:0
	s_add_u32 m0, s9, 0x1a020
	s_add_u32 s14, s14, 0x20000
	s_addc_u32 s15, s15, 0
	global_load_lds_dwordx4 v159, s[14:15]
	s_waitcnt lgkmcnt(4)
	v_mfma_f32_32x32x16_bf16 v[82:97], v[134:137], v[164:167], v[82:97]
	ds_read_b128 v[200:203], v208 offset:4096
	v_mfma_f32_32x32x16_bf16 v[66:81], v[134:137], v[168:171], v[66:81]
	ds_read_b128 v[180:183], v204 offset:4096
	s_add_u32 m0, s9, 0x1c020
	s_add_u32 s14, s14, 0x20000
	s_addc_u32 s15, s15, 0
	global_load_lds_dwordx4 v159, s[14:15]
	s_waitcnt lgkmcnt(5)
	v_mfma_f32_32x32x16_bf16 v[50:65], v[138:141], v[164:167], v[50:65]
	ds_read_b128 v[184:187], v204 offset:8192
	v_mfma_f32_32x32x16_bf16 v[34:49], v[138:141], v[168:171], v[34:49]
	ds_read_b128 v[188:191], v204 offset:12288
	s_add_u32 m0, s9, 0x1e020
	s_add_u32 s14, s14, 0x20000
	s_addc_u32 s15, s15, 0
	global_load_lds_dwordx4 v159, s[14:15]
	s_add_u32 s2, s2, 0x80
	s_addc_u32 s3, s3, 0
	s_waitcnt lgkmcnt(6)
	v_mfma_f32_32x32x16_bf16 v[18:33], v[160:163], v[164:167], v[18:33]
	v_mfma_f32_32x32x16_bf16 v[2:17], v[160:163], v[168:171], v[2:17]
	s_waitcnt lgkmcnt(4)
	v_mfma_f32_32x32x16_bf16 v[114:129], v[172:175], v[192:195], v[114:129]
	ds_read_b128 v[130:133], v205 offset:0
	s_waitcnt lgkmcnt(4)
	v_mfma_f32_32x32x16_bf16 v[98:113], v[172:175], v[200:203], v[98:113]
	ds_read_b128 v[164:167], v209 offset:0
	s_waitcnt lgkmcnt(4)
	v_mfma_f32_32x32x16_bf16 v[82:97], v[180:183], v[192:195], v[82:97]
	ds_read_b128 v[168:171], v209 offset:4096
	v_mfma_f32_32x32x16_bf16 v[66:81], v[180:183], v[200:203], v[66:81]
	ds_read_b128 v[134:137], v205 offset:4096
	s_waitcnt lgkmcnt(5)
	v_mfma_f32_32x32x16_bf16 v[50:65], v[184:187], v[192:195], v[50:65]
	ds_read_b128 v[138:141], v205 offset:8192
	v_mfma_f32_32x32x16_bf16 v[34:49], v[184:187], v[200:203], v[34:49]
	ds_read_b128 v[160:163], v205 offset:12288
	s_waitcnt lgkmcnt(6)
	v_mfma_f32_32x32x16_bf16 v[18:33], v[188:191], v[192:195], v[18:33]
	v_mfma_f32_32x32x16_bf16 v[2:17], v[188:191], v[200:203], v[2:17]
	s_waitcnt lgkmcnt(4)
	v_mfma_f32_32x32x16_bf16 v[114:129], v[130:133], v[164:167], v[114:129]
	ds_read_b128 v[172:175], v206 offset:0
	ds_read_b128 v[192:195], v210 offset:0
	s_waitcnt lgkmcnt(5)
	v_mfma_f32_32x32x16_bf16 v[98:113], v[130:133], v[168:171], v[98:113]
	ds_read_b128 v[200:203], v210 offset:4096
	ds_read_b128 v[180:183], v206 offset:4096
	s_waitcnt lgkmcnt(6)
	v_mfma_f32_32x32x16_bf16 v[82:97], v[134:137], v[164:167], v[82:97]
	ds_read_b128 v[184:187], v206 offset:8192
	ds_read_b128 v[188:191], v206 offset:12288
	v_mfma_f32_32x32x16_bf16 v[66:81], v[134:137], v[168:171], v[66:81]
	s_waitcnt lgkmcnt(7)
	v_mfma_f32_32x32x16_bf16 v[50:65], v[138:141], v[164:167], v[50:65]
	v_mfma_f32_32x32x16_bf16 v[34:49], v[138:141], v[168:171], v[34:49]
	s_waitcnt lgkmcnt(6)
	v_mfma_f32_32x32x16_bf16 v[18:33], v[160:163], v[164:167], v[18:33]
	v_mfma_f32_32x32x16_bf16 v[2:17], v[160:163], v[168:171], v[2:17]
	s_waitcnt vmcnt(0) lgkmcnt(0)
	s_barrier
	v_mfma_f32_32x32x16_bf16 v[114:129], v[172:175], v[192:195], v[114:129]
	ds_read_b128 v[130:133], v177 offset:32768
	s_add_u32 m0, s9, 0x20
	s_add_u32 s14, s1, s2
	s_addc_u32 s15, s5, s3
	global_load_lds_dwordx4 v159, s[14:15]
	v_mfma_f32_32x32x16_bf16 v[98:113], v[172:175], v[200:203], v[98:113]
	ds_read_b128 v[164:167], v207 offset:32768
	s_add_u32 m0, s9, 0x2020
	s_add_u32 s14, s14, 0x20000
	s_addc_u32 s15, s15, 0
	global_load_lds_dwordx4 v159, s[14:15]
	v_mfma_f32_32x32x16_bf16 v[82:97], v[180:183], v[192:195], v[82:97]
	ds_read_b128 v[168:171], v207 offset:36864
	s_add_u32 m0, s9, 0x4020
	s_add_u32 s14, s14, 0x20000
	s_addc_u32 s15, s15, 0
	global_load_lds_dwordx4 v159, s[14:15]
	v_mfma_f32_32x32x16_bf16 v[66:81], v[180:183], v[200:203], v[66:81]
	ds_read_b128 v[134:137], v177 offset:36864
	s_add_u32 m0, s9, 0x6020
	s_add_u32 s14, s14, 0x20000
	s_addc_u32 s15, s15, 0
	global_load_lds_dwordx4 v159, s[14:15]
	v_mfma_f32_32x32x16_bf16 v[50:65], v[184:187], v[192:195], v[50:65]
	ds_read_b128 v[138:141], v177 offset:40960
	s_add_u32 m0, s9, 0x10020
	s_add_u32 s14, s7, s2
	s_addc_u32 s15, s8, s3
	global_load_lds_dwordx4 v159, s[14:15]
	v_mfma_f32_32x32x16_bf16 v[34:49], v[184:187], v[200:203], v[34:49]
	ds_read_b128 v[160:163], v177 offset:45056
	v_mfma_f32_32x32x16_bf16 v[18:33], v[188:191], v[192:195], v[18:33]
	v_mfma_f32_32x32x16_bf16 v[2:17], v[188:191], v[200:203], v[2:17]
	s_waitcnt lgkmcnt(4)
	v_mfma_f32_32x32x16_bf16 v[114:129], v[130:133], v[164:167], v[114:129]
	ds_read_b128 v[172:175], v204 offset:32768
	s_waitcnt lgkmcnt(4)
	v_mfma_f32_32x32x16_bf16 v[98:113], v[130:133], v[168:171], v[98:113]
	ds_read_b128 v[192:195], v208 offset:32768
	s_add_u32 m0, s9, 0x12020
	s_add_u32 s14, s14, 0x20000
	s_addc_u32 s15, s15, 0
	global_load_lds_dwordx4 v159, s[14:15]
	s_waitcnt lgkmcnt(4)
	v_mfma_f32_32x32x16_bf16 v[82:97], v[134:137], v[164:167], v[82:97]
	ds_read_b128 v[200:203], v208 offset:36864
	v_mfma_f32_32x32x16_bf16 v[66:81], v[134:137], v[168:171], v[66:81]
	ds_read_b128 v[180:183], v204 offset:36864
	s_add_u32 m0, s9, 0x14020
	s_add_u32 s14, s14, 0x20000
	s_addc_u32 s15, s15, 0
	global_load_lds_dwordx4 v159, s[14:15]
	s_waitcnt lgkmcnt(5)
	v_mfma_f32_32x32x16_bf16 v[50:65], v[138:141], v[164:167], v[50:65]
	ds_read_b128 v[184:187], v204 offset:40960
	v_mfma_f32_32x32x16_bf16 v[34:49], v[138:141], v[168:171], v[34:49]
	ds_read_b128 v[188:191], v204 offset:45056
	s_add_u32 m0, s9, 0x16020
	s_add_u32 s14, s14, 0x20000
	s_addc_u32 s15, s15, 0
	global_load_lds_dwordx4 v159, s[14:15]
	s_add_u32 s2, s2, 0x80
	s_addc_u32 s3, s3, 0
	s_waitcnt lgkmcnt(6)
	v_mfma_f32_32x32x16_bf16 v[18:33], v[160:163], v[164:167], v[18:33]
	v_mfma_f32_32x32x16_bf16 v[2:17], v[160:163], v[168:171], v[2:17]
	s_waitcnt lgkmcnt(4)
	v_mfma_f32_32x32x16_bf16 v[114:129], v[172:175], v[192:195], v[114:129]
	ds_read_b128 v[130:133], v205 offset:32768
	s_waitcnt lgkmcnt(4)
	v_mfma_f32_32x32x16_bf16 v[98:113], v[172:175], v[200:203], v[98:113]
	ds_read_b128 v[164:167], v209 offset:32768
	s_waitcnt lgkmcnt(4)
	v_mfma_f32_32x32x16_bf16 v[82:97], v[180:183], v[192:195], v[82:97]
	ds_read_b128 v[168:171], v209 offset:36864
	v_mfma_f32_32x32x16_bf16 v[66:81], v[180:183], v[200:203], v[66:81]
	ds_read_b128 v[134:137], v205 offset:36864
	s_waitcnt lgkmcnt(5)
	v_mfma_f32_32x32x16_bf16 v[50:65], v[184:187], v[192:195], v[50:65]
	ds_read_b128 v[138:141], v205 offset:40960
	v_mfma_f32_32x32x16_bf16 v[34:49], v[184:187], v[200:203], v[34:49]
	ds_read_b128 v[160:163], v205 offset:45056
	s_waitcnt lgkmcnt(6)
	v_mfma_f32_32x32x16_bf16 v[18:33], v[188:191], v[192:195], v[18:33]
	v_mfma_f32_32x32x16_bf16 v[2:17], v[188:191], v[200:203], v[2:17]
	s_waitcnt lgkmcnt(4)
	v_mfma_f32_32x32x16_bf16 v[114:129], v[130:133], v[164:167], v[114:129]
	ds_read_b128 v[172:175], v206 offset:32768
	ds_read_b128 v[192:195], v210 offset:32768
	s_waitcnt lgkmcnt(5)
	v_mfma_f32_32x32x16_bf16 v[98:113], v[130:133], v[168:171], v[98:113]
	ds_read_b128 v[200:203], v210 offset:36864
	ds_read_b128 v[180:183], v206 offset:36864
	s_waitcnt lgkmcnt(6)
	v_mfma_f32_32x32x16_bf16 v[82:97], v[134:137], v[164:167], v[82:97]
	ds_read_b128 v[184:187], v206 offset:40960
	ds_read_b128 v[188:191], v206 offset:45056
	v_mfma_f32_32x32x16_bf16 v[66:81], v[134:137], v[168:171], v[66:81]
	s_waitcnt lgkmcnt(7)
	v_mfma_f32_32x32x16_bf16 v[50:65], v[138:141], v[164:167], v[50:65]
	v_mfma_f32_32x32x16_bf16 v[34:49], v[138:141], v[168:171], v[34:49]
	s_waitcnt lgkmcnt(6)
	v_mfma_f32_32x32x16_bf16 v[18:33], v[160:163], v[164:167], v[18:33]
	v_mfma_f32_32x32x16_bf16 v[2:17], v[160:163], v[168:171], v[2:17]
	s_waitcnt vmcnt(0) lgkmcnt(0)
	s_barrier
	v_mfma_f32_32x32x16_bf16 v[114:129], v[172:175], v[192:195], v[114:129]
	ds_read_b128 v[130:133], v177 offset:0
	s_add_u32 m0, s9, 0x8020
	s_add_u32 s14, s1, s2
	s_addc_u32 s15, s5, s3
	global_load_lds_dwordx4 v159, s[14:15]
	v_mfma_f32_32x32x16_bf16 v[98:113], v[172:175], v[200:203], v[98:113]
	ds_read_b128 v[164:167], v207 offset:0
	s_add_u32 m0, s9, 0xa020
	s_add_u32 s14, s14, 0x20000
	s_addc_u32 s15, s15, 0
	global_load_lds_dwordx4 v159, s[14:15]
	v_mfma_f32_32x32x16_bf16 v[82:97], v[180:183], v[192:195], v[82:97]
	ds_read_b128 v[168:171], v207 offset:4096
	s_add_u32 m0, s9, 0xc020
	s_add_u32 s14, s14, 0x20000
	s_addc_u32 s15, s15, 0
	global_load_lds_dwordx4 v159, s[14:15]
	v_mfma_f32_32x32x16_bf16 v[66:81], v[180:183], v[200:203], v[66:81]
	ds_read_b128 v[134:137], v177 offset:4096
	s_add_u32 m0, s9, 0xe020
	s_add_u32 s14, s14, 0x20000
	s_addc_u32 s15, s15, 0
	global_load_lds_dwordx4 v159, s[14:15]
	v_mfma_f32_32x32x16_bf16 v[50:65], v[184:187], v[192:195], v[50:65]
	ds_read_b128 v[138:141], v177 offset:8192
	s_add_u32 m0, s9, 0x18020
	s_add_u32 s14, s7, s2
	s_addc_u32 s15, s8, s3
	global_load_lds_dwordx4 v159, s[14:15]
	v_mfma_f32_32x32x16_bf16 v[34:49], v[184:187], v[200:203], v[34:49]
	ds_read_b128 v[160:163], v177 offset:12288
	v_mfma_f32_32x32x16_bf16 v[18:33], v[188:191], v[192:195], v[18:33]
	v_mfma_f32_32x32x16_bf16 v[2:17], v[188:191], v[200:203], v[2:17]
	s_sub_u32 s6, s6, 1
	s_cmp_lg_u32 s6, 0
	s_cbranch_scc1 .Lg295_loop
	s_waitcnt lgkmcnt(4)
	v_mfma_f32_32x32x16_bf16 v[114:129], v[130:133], v[164:167], v[114:129]
	ds_read_b128 v[172:175], v204 offset:0
	s_waitcnt lgkmcnt(4)
	v_mfma_f32_32x32x16_bf16 v[98:113], v[130:133], v[168:171], v[98:113]
	ds_read_b128 v[192:195], v208 offset:0
	s_add_u32 m0, s9, 0x1a020
	s_add_u32 s14, s14, 0x20000
	s_addc_u32 s15, s15, 0
	global_load_lds_dwordx4 v159, s[14:15]
	s_waitcnt lgkmcnt(4)
	v_mfma_f32_32x32x16_bf16 v[82:97], v[134:137], v[164:167], v[82:97]
	ds_read_b128 v[200:203], v208 offset:4096
	v_mfma_f32_32x32x16_bf16 v[66:81], v[134:137], v[168:171], v[66:81]
	ds_read_b128 v[180:183], v204 offset:4096
	s_add_u32 m0, s9, 0x1c020
	s_add_u32 s14, s14, 0x20000
	s_addc_u32 s15, s15, 0
	global_load_lds_dwordx4 v159, s[14:15]
	s_waitcnt lgkmcnt(5)
	v_mfma_f32_32x32x16_bf16 v[50:65], v[138:141], v[164:167], v[50:65]
	ds_read_b128 v[184:187], v204 offset:8192
	v_mfma_f32_32x32x16_bf16 v[34:49], v[138:141], v[168:171], v[34:49]
	ds_read_b128 v[188:191], v204 offset:12288
	s_add_u32 m0, s9, 0x1e020
	s_add_u32 s14, s14, 0x20000
	s_addc_u32 s15, s15, 0
	global_load_lds_dwordx4 v159, s[14:15]
	s_add_u32 s2, s2, 0x80
	s_addc_u32 s3, s3, 0
	s_waitcnt lgkmcnt(6)
	v_mfma_f32_32x32x16_bf16 v[18:33], v[160:163], v[164:167], v[18:33]
	v_mfma_f32_32x32x16_bf16 v[2:17], v[160:163], v[168:171], v[2:17]
	s_waitcnt lgkmcnt(4)
	v_mfma_f32_32x32x16_bf16 v[114:129], v[172:175], v[192:195], v[114:129]
	ds_read_b128 v[130:133], v205 offset:0
	s_waitcnt lgkmcnt(4)
	v_mfma_f32_32x32x16_bf16 v[98:113], v[172:175], v[200:203], v[98:113]
	ds_read_b128 v[164:167], v209 offset:0
	s_waitcnt lgkmcnt(4)
	v_mfma_f32_32x32x16_bf16 v[82:97], v[180:183], v[192:195], v[82:97]
	ds_read_b128 v[168:171], v209 offset:4096
	v_mfma_f32_32x32x16_bf16 v[66:81], v[180:183], v[200:203], v[66:81]
	ds_read_b128 v[134:137], v205 offset:4096
	s_waitcnt lgkmcnt(5)
	v_mfma_f32_32x32x16_bf16 v[50:65], v[184:187], v[192:195], v[50:65]
	ds_read_b128 v[138:141], v205 offset:8192
	v_mfma_f32_32x32x16_bf16 v[34:49], v[184:187], v[200:203], v[34:49]
	ds_read_b128 v[160:163], v205 offset:12288
	s_waitcnt lgkmcnt(6)
	v_mfma_f32_32x32x16_bf16 v[18:33], v[188:191], v[192:195], v[18:33]
	v_mfma_f32_32x32x16_bf16 v[2:17], v[188:191], v[200:203], v[2:17]
	s_waitcnt lgkmcnt(4)
	v_mfma_f32_32x32x16_bf16 v[114:129], v[130:133], v[164:167], v[114:129]
	ds_read_b128 v[172:175], v206 offset:0
	ds_read_b128 v[192:195], v210 offset:0
	s_waitcnt lgkmcnt(5)
	v_mfma_f32_32x32x16_bf16 v[98:113], v[130:133], v[168:171], v[98:113]
	ds_read_b128 v[200:203], v210 offset:4096
	ds_read_b128 v[180:183], v206 offset:4096
	s_waitcnt lgkmcnt(6)
	v_mfma_f32_32x32x16_bf16 v[82:97], v[134:137], v[164:167], v[82:97]
	ds_read_b128 v[184:187], v206 offset:8192
	ds_read_b128 v[188:191], v206 offset:12288
	v_mfma_f32_32x32x16_bf16 v[66:81], v[134:137], v[168:171], v[66:81]
	s_waitcnt lgkmcnt(7)
	v_mfma_f32_32x32x16_bf16 v[50:65], v[138:141], v[164:167], v[50:65]
	v_mfma_f32_32x32x16_bf16 v[34:49], v[138:141], v[168:171], v[34:49]
	s_waitcnt lgkmcnt(6)
	v_mfma_f32_32x32x16_bf16 v[18:33], v[160:163], v[164:167], v[18:33]
	v_mfma_f32_32x32x16_bf16 v[2:17], v[160:163], v[168:171], v[2:17]
	s_waitcnt vmcnt(0) lgkmcnt(0)
	s_barrier
	v_mfma_f32_32x32x16_bf16 v[114:129], v[172:175], v[192:195], v[114:129]
	ds_read_b128 v[130:133], v177 offset:32768
	v_mfma_f32_32x32x16_bf16 v[98:113], v[172:175], v[200:203], v[98:113]
	ds_read_b128 v[164:167], v207 offset:32768
	v_mfma_f32_32x32x16_bf16 v[82:97], v[180:183], v[192:195], v[82:97]
	ds_read_b128 v[168:171], v207 offset:36864
	v_mfma_f32_32x32x16_bf16 v[66:81], v[180:183], v[200:203], v[66:81]
	ds_read_b128 v[134:137], v177 offset:36864
	v_mfma_f32_32x32x16_bf16 v[50:65], v[184:187], v[192:195], v[50:65]
	ds_read_b128 v[138:141], v177 offset:40960
	v_mfma_f32_32x32x16_bf16 v[34:49], v[184:187], v[200:203], v[34:49]
	ds_read_b128 v[160:163], v177 offset:45056
	v_mfma_f32_32x32x16_bf16 v[18:33], v[188:191], v[192:195], v[18:33]
	v_mfma_f32_32x32x16_bf16 v[2:17], v[188:191], v[200:203], v[2:17]
	s_waitcnt lgkmcnt(4)
	v_mfma_f32_32x32x16_bf16 v[114:129], v[130:133], v[164:167], v[114:129]
	ds_read_b128 v[172:175], v204 offset:32768
	s_waitcnt lgkmcnt(4)
	v_mfma_f32_32x32x16_bf16 v[98:113], v[130:133], v[168:171], v[98:113]
	ds_read_b128 v[192:195], v208 offset:32768
	s_waitcnt lgkmcnt(4)
	v_mfma_f32_32x32x16_bf16 v[82:97], v[134:137], v[164:167], v[82:97]
	ds_read_b128 v[200:203], v208 offset:36864
	v_mfma_f32_32x32x16_bf16 v[66:81], v[134:137], v[168:171], v[66:81]
	ds_read_b128 v[180:183], v204 offset:36864
	s_waitcnt lgkmcnt(5)
	v_mfma_f32_32x32x16_bf16 v[50:65], v[138:141], v[164:167], v[50:65]
	ds_read_b128 v[184:187], v204 offset:40960
	v_mfma_f32_32x32x16_bf16 v[34:49], v[138:141], v[168:171], v[34:49]
	ds_read_b128 v[188:191], v204 offset:45056
	s_waitcnt lgkmcnt(6)
	v_mfma_f32_32x32x16_bf16 v[18:33], v[160:163], v[164:167], v[18:33]
	v_mfma_f32_32x32x16_bf16 v[2:17], v[160:163], v[168:171], v[2:17]
	s_waitcnt lgkmcnt(4)
	v_mfma_f32_32x32x16_bf16 v[114:129], v[172:175], v[192:195], v[114:129]
	ds_read_b128 v[130:133], v205 offset:32768
	s_waitcnt lgkmcnt(4)
	v_mfma_f32_32x32x16_bf16 v[98:113], v[172:175], v[200:203], v[98:113]
	ds_read_b128 v[164:167], v209 offset:32768
	s_waitcnt lgkmcnt(4)
	v_mfma_f32_32x32x16_bf16 v[82:97], v[180:183], v[192:195], v[82:97]
	ds_read_b128 v[168:171], v209 offset:36864
	v_mfma_f32_32x32x16_bf16 v[66:81], v[180:183], v[200:203], v[66:81]
	ds_read_b128 v[134:137], v205 offset:36864
	s_waitcnt lgkmcnt(5)
	v_mfma_f32_32x32x16_bf16 v[50:65], v[184:187], v[192:195], v[50:65]
	ds_read_b128 v[138:141], v205 offset:40960
	v_mfma_f32_32x32x16_bf16 v[34:49], v[184:187], v[200:203], v[34:49]
	ds_read_b128 v[160:163], v205 offset:45056
	s_waitcnt lgkmcnt(6)
	v_mfma_f32_32x32x16_bf16 v[18:33], v[188:191], v[192:195], v[18:33]
	v_mfma_f32_32x32x16_bf16 v[2:17], v[188:191], v[200:203], v[2:17]
	s_waitcnt lgkmcnt(4)
	v_mfma_f32_32x32x16_bf16 v[114:129], v[130:133], v[164:167], v[114:129]
	ds_read_b128 v[172:175], v206 offset:32768
	ds_read_b128 v[192:195], v210 offset:32768
	s_waitcnt lgkmcnt(5)
	v_mfma_f32_32x32x16_bf16 v[98:113], v[130:133], v[168:171], v[98:113]
	ds_read_b128 v[200:203], v210 offset:36864
	ds_read_b128 v[180:183], v206 offset:36864
	s_waitcnt lgkmcnt(6)
	v_mfma_f32_32x32x16_bf16 v[82:97], v[134:137], v[164:167], v[82:97]
	ds_read_b128 v[184:187], v206 offset:40960
	ds_read_b128 v[188:191], v206 offset:45056
	v_mfma_f32_32x32x16_bf16 v[66:81], v[134:137], v[168:171], v[66:81]
	s_waitcnt lgkmcnt(7)
	v_mfma_f32_32x32x16_bf16 v[50:65], v[138:141], v[164:167], v[50:65]
	v_mfma_f32_32x32x16_bf16 v[34:49], v[138:141], v[168:171], v[34:49]
	s_waitcnt lgkmcnt(6)
	v_mfma_f32_32x32x16_bf16 v[18:33], v[160:163], v[164:167], v[18:33]
	v_mfma_f32_32x32x16_bf16 v[2:17], v[160:163], v[168:171], v[2:17]
	s_waitcnt vmcnt(0) lgkmcnt(0)
	s_barrier
	v_mfma_f32_32x32x16_bf16 v[114:129], v[172:175], v[192:195], v[114:129]
	v_mfma_f32_32x32x16_bf16 v[98:113], v[172:175], v[200:203], v[98:113]
	v_mfma_f32_32x32x16_bf16 v[82:97], v[180:183], v[192:195], v[82:97]
	v_mfma_f32_32x32x16_bf16 v[66:81], v[180:183], v[200:203], v[66:81]
	v_mfma_f32_32x32x16_bf16 v[50:65], v[184:187], v[192:195], v[50:65]
	v_mfma_f32_32x32x16_bf16 v[34:49], v[184:187], v[200:203], v[34:49]
	v_mfma_f32_32x32x16_bf16 v[18:33], v[188:191], v[192:195], v[18:33]
	v_mfma_f32_32x32x16_bf16 v[2:17], v[188:191], v[200:203], v[2:17]
	s_setprio 0
	v_add_u32_e32 v159, s0, v153
	s_mov_b32 s0, 0x7e07e07f
	v_mul_hi_i32 v0, v159, s0
	v_lshrrev_b32_e32 v133, 31, v0
	v_ashrrev_i32_e32 v0, 13, v0
	v_add_u32_e32 v134, v0, v133
	v_mul_i32_i24_e32 v0, 0x4100, v134
	v_sub_u32_e32 v136, v159, v0
	s_movk_i32 s0, 0x100
	v_cmp_gt_i32_e64 s[56:57], s0, v136
	v_ashrrev_i32_e32 v137, 31, v136
	s_mov_b32 s0, 0xfff00000
	s_waitcnt vmcnt(0)
	v_ashrrev_i32_e32 v130, 7, v159
	v_lshlrev_b64 v[136:137], 12, v[136:137]
	s_mov_b32 s1, -1
	v_or_b32_e32 v132, s4, v154
	v_ashrrev_i32_e32 v131, 31, v130
	v_ashrrev_i32_e32 v135, 31, v134
	v_lshl_add_u64 v[136:137], v[136:137], 0, s[0:1]
	s_movk_i32 s0, 0x1840
	v_lshlrev_b64 v[130:131], 14, v[130:131]
	v_lshlrev_b64 v[134:135], 26, v[134:135]
	v_mov_b32_e32 v161, v179
	v_cmp_gt_i32_e64 s[54:55], s0, v132
	s_barrier
	s_and_saveexec_b64 s[2:3], s[54:55]
	s_cbranch_execz .LBB0_371
	s_movk_i32 s0, 0x7ff
	v_cmp_lt_i32_e32 vcc, s0, v132
	s_xor_b64 s[0:1], s[56:57], -1
	s_or_b64 s[0:1], vcc, s[0:1]
	s_and_b64 exec, exec, s[0:1]
	s_cbranch_execz .LBB0_371
	v_bfe_u32 v0, v161, 5, 1
	v_mul_u32_u24_e32 v0, 0x90, v0
	v_lshlrev_b32_e32 v133, 2, v161
	v_lshlrev_b32_e32 v0, 2, v0
	v_and_b32_e32 v133, 0x7c, v133
	v_add3_u32 v138, v155, v0, v133
	v_add3_u32 v0, v155, v133, v0
	ds_write_b32 v138, v114
	v_add_u32_e32 v114, 0x100, v0
	ds_write2_b32 v114, v117, v118 offset0:44 offset1:224
	v_add_u32_e32 v114, 0x400, v0
	ds_write2_b32 v114, v119, v120 offset0:68 offset1:104
	v_add_u32_e32 v114, 0x600, v0
	ds_write2_b32 v114, v121, v122 offset0:12 offset1:192
	v_add_u32_e32 v114, 0x800, v0
	ds_write2_b32 v114, v123, v124 offset0:100 offset1:136
	v_add_u32_e32 v114, 0xa00, v0
	ds_write2_b32 v114, v125, v126 offset0:44 offset1:224
	v_add_u32_e32 v114, 0xc00, v0
	ds_write2_b32 v0, v115, v116 offset0:36 offset1:72
	ds_write2_b32 v114, v127, v128 offset0:132 offset1:168
	ds_write_b32 v0, v129 offset:3888
	s_waitcnt lgkmcnt(0)
	v_and_b32_e32 v160, 63, v161
	s_and_saveexec_b64 s[0:1], vcc
	s_xor_b64 s[6:7], exec, s[0:1]
	s_cbranch_execz .LBB0_369
	s_cmpk_gt_u32 s4, 0x17ff
	s_mov_b64 s[0:1], -1
	s_cbranch_scc0 .LBB0_365
	v_readlane_b32 s16, v251, 2
	v_lshlrev_b32_e32 v116, 3, v161
	v_add_u32_e32 v0, 0xffffe800, v132
	v_readlane_b32 s17, v251, 3
	v_and_b32_e32 v116, 24, v116
	v_lshlrev_b32_e32 v140, 2, v116
	v_lshl_add_u64 v[114:115], v[0:1], 2, s[16:17]
	v_mov_b32_e32 v141, v1
	v_lshl_add_u64 v[138:139], v[114:115], 0, v[140:141]
	global_load_dwordx4 v[122:125], v[138:139], off
	global_load_dwordx4 v[114:117], v[138:139], off offset:16
	v_add_u32_e32 v162, v155, v140
	v_lshrrev_b32_e32 v133, 2, v160
	s_movk_i32 s0, 0x90
	v_mad_u32_u24 v118, v133, s0, v162
	ds_read_b128 v[126:129], v118
	ds_read_b128 v[118:121], v118 offset:16
	s_mov_b32 s0, 0xbfb8aa3b
	v_readlane_b32 s18, v251, 4
	v_readlane_b32 s19, v251, 5
	v_readlane_b32 s20, v251, 6
	v_readlane_b32 s21, v251, 7
	v_readlane_b32 s22, v251, 8
	v_readlane_b32 s23, v251, 9
	v_readlane_b32 s24, v251, 10
	v_readlane_b32 s25, v251, 11
	v_readlane_b32 s26, v251, 12
	v_readlane_b32 s27, v251, 13
	v_readlane_b32 s28, v251, 14
	v_readlane_b32 s29, v251, 15
	v_readlane_b32 s30, v251, 16
	v_readlane_b32 s31, v251, 17
	s_waitcnt vmcnt(1) lgkmcnt(1)
	v_add_f32_e32 v122, v126, v122
	v_mul_f32_e64 v126, |v122|, s0
	v_exp_f32_e32 v141, v126
	s_mov_b32 s0, 0x3c23d70a
	v_cmp_ngt_f32_e32 vcc, s0, v141
	s_and_saveexec_b64 s[0:1], vcc
	s_xor_b64 s[8:9], exec, s[0:1]
	s_cbranch_execz .LBB0_302
	v_add_f32_e32 v126, 1.0, v141
	s_mov_b32 s0, 0x800000
	v_cmp_gt_f32_e32 vcc, s0, v126
	s_mov_b32 s0, 0x3f317217
	s_nop 0
	v_cndmask_b32_e64 v141, 0, 32, vcc
	v_ldexp_f32 v126, v126, v141
	v_log_f32_e32 v126, v126
	s_nop 0
	v_mul_f32_e32 v141, 0x3f317217, v126
	v_fma_f32 v141, v126, s0, -v141
	v_fmac_f32_e32 v141, 0x3377d1cf, v126
	v_fmac_f32_e32 v141, 0x3f317217, v126
	v_cmp_lt_f32_e64 s[0:1], |v126|, s47
	s_nop 1
	v_cndmask_b32_e64 v126, v126, v141, s[0:1]
	v_cndmask_b32_e32 v141, 0, v238, vcc
	v_sub_f32_e32 v126, v126, v141

.LBB0_908:
	s_add_i32 s2, s7, s8
	s_cmpk_gt_i32 s2, 0x207
	s_mov_b64 s[0:1], -1
	s_cbranch_scc1 .LBB0_907
	s_ashr_i32 s0, s2, 31
	s_lshr_b32 s0, s0, 27
	s_add_i32 s0, s2, s0
	s_ashr_i32 s1, s0, 5
	s_lshl_b32 s1, s1, 3
	s_sub_i32 s3, 0x82, s1
	s_min_u32 s3, s3, 8
	v_cvt_f32_ubyte0_e32 v0, s3
	v_rcp_iflag_f32_e32 v0, v0
	s_sub_i32 s5, 0, s3
	s_andn2_b32 s0, s0, 31
	s_sub_i32 s0, s2, s0
	v_mul_f32_e32 v0, 0x4f7ffffe, v0
	v_cvt_u32_f32_e32 v0, v0
	s_abs_i32 s4, s0
	s_ashr_i32 s2, s0, 31
	s_waitcnt vmcnt(63) expcnt(7) lgkmcnt(15)
	v_readfirstlane_b32 s10, v0
	s_mul_i32 s5, s5, s10
	s_mul_hi_u32 s5, s10, s5
	s_add_i32 s10, s10, s5
	s_mul_hi_u32 s5, s4, s10
	s_mul_i32 s10, s5, s3
	s_sub_i32 s4, s4, s10
	s_add_i32 s10, s5, 1
	s_sub_i32 s11, s4, s3
	s_cmp_ge_u32 s4, s3
	s_cselect_b32 s5, s10, s5
	s_cselect_b32 s4, s11, s4
	s_add_i32 s10, s5, 1
	s_cmp_ge_u32 s4, s3
	s_cselect_b32 s4, s10, s5
	s_xor_b32 s4, s4, s2
	s_sub_i32 s2, s4, s2
	s_mul_i32 s3, s2, s3
	s_sub_i32 s0, s0, s3
	s_add_i32 s0, s0, s1
	s_lshl_b32 s0, s0, 8
	s_lshl_b32 s2, s2, 8
	s_ashr_i32 s1, s0, 31
	s_ashr_i32 s3, s2, 31
	s_lshl_b64 s[4:5], s[0:1], 11
	s_lshl_b64 s[10:11], s[2:3], 11
	s_add_u32 s12, s64, s4
	v_mov_b32_e32 v0, v132
	s_addc_u32 s13, s65, s5
	s_barrier
	v_readlane_b32 s14, v251, 50
	v_lshl_add_u64 v[2:3], v[0:1], 1, s[12:13]
	v_add_u32_e32 v0, 32, v133
	v_readlane_b32 s15, v251, 51
	v_readfirstlane_b32 s1, v0
	s_mov_b32 m0, s1
	v_mov_b32_e32 v0, v134
	global_load_lds_dwordx4 v[2:3], off
	s_add_u32 s14, s14, s10
	v_lshl_add_u64 v[2:3], v[0:1], 1, s[12:13]
	v_add_u32_e32 v0, 32, v135
	s_addc_u32 s15, s15, s11
	v_readfirstlane_b32 s1, v0
	s_mov_b32 m0, s1
	v_mov_b32_e32 v0, v136
	global_load_lds_dwordx4 v[2:3], off
	v_readlane_b32 s3, v254, 3
	v_lshl_add_u64 v[2:3], v[0:1], 1, s[12:13]
	v_add_u32_e32 v0, 32, v137
	s_mov_b32 s9, 0
	v_readfirstlane_b32 s1, v0
	s_mov_b32 m0, s1
	v_mov_b32_e32 v0, v138
	global_load_lds_dwordx4 v[2:3], off
	s_nop 0
	v_lshl_add_u64 v[2:3], v[0:1], 1, s[12:13]
	v_add_u32_e32 v0, 32, v139
	s_nop 0
	v_readfirstlane_b32 s1, v0
	s_mov_b32 m0, s1
	v_mov_b32_e32 v0, v132
	global_load_lds_dwordx4 v[2:3], off
	s_nop 0
	v_lshl_add_u64 v[2:3], v[0:1], 1, s[14:15]
	v_add_u32_e32 v0, s3, v133
	s_nop 0
	v_readfirstlane_b32 s1, v0
	s_mov_b32 m0, s1
	v_mov_b32_e32 v0, v134
	global_load_lds_dwordx4 v[2:3], off
	s_nop 0
	v_lshl_add_u64 v[2:3], v[0:1], 1, s[14:15]
	v_add_u32_e32 v0, s3, v135
	s_nop 0
	v_readfirstlane_b32 s1, v0
	s_mov_b32 m0, s1
	v_mov_b32_e32 v0, v136
	global_load_lds_dwordx4 v[2:3], off
	s_nop 0
	v_lshl_add_u64 v[2:3], v[0:1], 1, s[14:15]
	v_add_u32_e32 v0, s3, v137
	s_nop 0
	v_readfirstlane_b32 s1, v0
	s_mov_b32 m0, s1
	v_mov_b32_e32 v0, v138
	global_load_lds_dwordx4 v[2:3], off
	s_nop 0
	v_lshl_add_u64 v[2:3], v[0:1], 1, s[14:15]
	v_add_u32_e32 v0, s3, v139
	v_readlane_b32 s3, v253, 26
	v_readfirstlane_b32 s1, v0
	s_mov_b32 m0, s1
	v_readlane_b32 s1, v253, 25
	global_load_lds_dwordx4 v[2:3], off
	s_add_u32 s1, s1, s4
	s_waitcnt vmcnt(0)
	s_addc_u32 s3, s3, s5
	v_readlane_b32 s4, v253, 34
	s_add_u32 s10, s4, s10
	v_readlane_b32 s4, v253, 35
	v_mov_b32_e32 v2, 0
	s_addc_u32 s11, s4, s11
	s_mov_b64 s[4:5], 0
	v_mov_b32_e32 v3, v2
	v_mov_b32_e32 v4, v2
	v_mov_b32_e32 v5, v2
	v_mov_b32_e32 v6, v2
	v_mov_b32_e32 v7, v2
	v_mov_b32_e32 v8, v2
	v_mov_b32_e32 v9, v2
	v_mov_b32_e32 v10, v2
	v_mov_b32_e32 v11, v2
	v_mov_b32_e32 v12, v2
	v_mov_b32_e32 v13, v2
	s_waitcnt vmcnt(0)
	v_mov_b32_e32 v14, v2
	v_mov_b32_e32 v15, v2
	v_mov_b32_e32 v16, v2
	v_mov_b32_e32 v17, v2
	v_mov_b32_e32 v18, v2
	v_mov_b32_e32 v19, v2
	v_mov_b32_e32 v20, v2
	v_mov_b32_e32 v21, v2
	v_mov_b32_e32 v22, v2
	v_mov_b32_e32 v23, v2
	v_mov_b32_e32 v24, v2
	v_mov_b32_e32 v25, v2
	v_mov_b32_e32 v26, v2
	v_mov_b32_e32 v27, v2
	v_mov_b32_e32 v28, v2
	v_mov_b32_e32 v29, v2
	v_mov_b32_e32 v30, v2
	v_mov_b32_e32 v31, v2
	v_mov_b32_e32 v32, v2
	v_mov_b32_e32 v33, v2
	v_mov_b32_e32 v34, v2
	v_mov_b32_e32 v35, v2
	v_mov_b32_e32 v36, v2
	v_mov_b32_e32 v37, v2
	v_mov_b32_e32 v38, v2
	v_mov_b32_e32 v39, v2
	v_mov_b32_e32 v40, v2
	v_mov_b32_e32 v41, v2
	v_mov_b32_e32 v42, v2
	v_mov_b32_e32 v43, v2
	v_mov_b32_e32 v44, v2
	v_mov_b32_e32 v45, v2
	v_mov_b32_e32 v46, v2
	v_mov_b32_e32 v47, v2
	v_mov_b32_e32 v48, v2
	v_mov_b32_e32 v49, v2
	v_mov_b32_e32 v50, v2
	v_mov_b32_e32 v51, v2
	v_mov_b32_e32 v52, v2
	v_mov_b32_e32 v53, v2
	v_mov_b32_e32 v54, v2
	v_mov_b32_e32 v55, v2
	v_mov_b32_e32 v56, v2
	v_mov_b32_e32 v57, v2
	v_mov_b32_e32 v58, v2
	v_mov_b32_e32 v59, v2
	v_mov_b32_e32 v60, v2
	v_mov_b32_e32 v61, v2
	v_mov_b32_e32 v62, v2
	v_mov_b32_e32 v63, v2
	v_mov_b32_e32 v64, v2
	v_mov_b32_e32 v65, v2
	v_mov_b32_e32 v66, v2
	v_mov_b32_e32 v67, v2
	v_mov_b32_e32 v68, v2
	v_mov_b32_e32 v69, v2
	v_mov_b32_e32 v70, v2
	v_mov_b32_e32 v71, v2
	v_mov_b32_e32 v72, v2
	v_mov_b32_e32 v73, v2
	v_mov_b32_e32 v74, v2
	v_mov_b32_e32 v75, v2
	v_mov_b32_e32 v76, v2
	v_mov_b32_e32 v77, v2
	v_mov_b32_e32 v78, v2
	v_mov_b32_e32 v79, v2
	v_mov_b32_e32 v80, v2
	v_mov_b32_e32 v81, v2
	v_mov_b32_e32 v82, v2
	v_mov_b32_e32 v83, v2
	v_mov_b32_e32 v84, v2
	v_mov_b32_e32 v85, v2
	v_mov_b32_e32 v86, v2
	v_mov_b32_e32 v87, v2
	v_mov_b32_e32 v88, v2
	v_mov_b32_e32 v89, v2
	v_mov_b32_e32 v90, v2
	v_mov_b32_e32 v91, v2
	v_mov_b32_e32 v92, v2
	v_mov_b32_e32 v93, v2
	v_mov_b32_e32 v94, v2
	v_mov_b32_e32 v95, v2
	v_mov_b32_e32 v96, v2
	v_mov_b32_e32 v97, v2
	v_mov_b32_e32 v98, v2
	v_mov_b32_e32 v99, v2
	v_mov_b32_e32 v100, v2
	v_mov_b32_e32 v101, v2
	v_mov_b32_e32 v102, v2
	v_mov_b32_e32 v103, v2
	v_mov_b32_e32 v104, v2
	v_mov_b32_e32 v105, v2
	v_mov_b32_e32 v106, v2
	v_mov_b32_e32 v107, v2
	v_mov_b32_e32 v108, v2
	v_mov_b32_e32 v109, v2
	v_mov_b32_e32 v110, v2
	v_mov_b32_e32 v111, v2
	v_mov_b32_e32 v112, v2
	v_mov_b32_e32 v113, v2
	v_mov_b32_e32 v114, v2
	v_mov_b32_e32 v115, v2
	v_mov_b32_e32 v116, v2
	v_mov_b32_e32 v117, v2
	v_mov_b32_e32 v118, v2
	v_mov_b32_e32 v119, v2
	v_mov_b32_e32 v120, v2
	v_mov_b32_e32 v121, v2
	v_mov_b32_e32 v122, v2
	v_mov_b32_e32 v123, v2
	v_mov_b32_e32 v124, v2
	v_mov_b32_e32 v125, v2
	v_mov_b32_e32 v126, v2
	v_mov_b32_e32 v127, v2
	v_mov_b32_e32 v128, v2
	v_mov_b32_e32 v129, v2
	s_waitcnt lgkmcnt(0)
	s_barrier
	v_lshlrev_b32_e32 v149, 1, v132
	v_readfirstlane_b32 s14, v133
	v_add_u32_e32 v205, v140, v142
	v_add_u32_e32 v209, v141, v142
	v_add_u32_e32 v206, v140, v146
	v_add_u32_e32 v210, v141, v146
	v_add_u32_e32 v207, v140, v147
	v_add_u32_e32 v211, v141, v147
	v_add_u32_e32 v208, v140, v148
	v_add_u32_e32 v212, v141, v148
	s_mov_b32 s9, 7
	v_readfirstlane_b32 s66, v179
	s_cmp_ge_u32 s66, 0x100
	s_cbranch_scc0 .Lg910_np
	s_setprio 1
.Lg910_np:
	s_add_u32 m0, s14, 0x8020
	s_add_u32 s12, s1, s4
	s_addc_u32 s13, s3, s5
	global_load_lds_dwordx4 v149, s[12:13]
	s_add_u32 m0, s14, 0xa020
	s_add_u32 s12, s12, 0x20000
	s_addc_u32 s13, s13, 0
	global_load_lds_dwordx4 v149, s[12:13]
	s_add_u32 m0, s14, 0xc020
	s_add_u32 s12, s12, 0x20000
	s_addc_u32 s13, s13, 0
	global_load_lds_dwordx4 v149, s[12:13]
	s_add_u32 m0, s14, 0xe020
	s_add_u32 s12, s12, 0x20000
	s_addc_u32 s13, s13, 0
	global_load_lds_dwordx4 v149, s[12:13]
	s_add_u32 m0, s14, 0x18020
	s_add_u32 s12, s10, s4
	s_addc_u32 s13, s11, s5
	global_load_lds_dwordx4 v149, s[12:13]
	ds_read_b128 v[150:153], v205 offset:0
	ds_read_b128 v[166:169], v209 offset:0
	ds_read_b128 v[170:173], v209 offset:4096
	ds_read_b128 v[154:157], v205 offset:4096
	ds_read_b128 v[158:161], v205 offset:8192
	ds_read_b128 v[162:165], v205 offset:12288
.Lg910_loop:
	s_waitcnt lgkmcnt(4)
	v_mfma_f32_32x32x16_bf16 v[114:129], v[150:153], v[166:169], v[114:129]
	ds_read_b128 v[174:177], v206 offset:0
	s_waitcnt lgkmcnt(4)
	v_mfma_f32_32x32x16_bf16 v[98:113], v[150:153], v[170:173], v[98:113]
	ds_read_b128 v[192:195], v210 offset:0
	s_add_u32 m0, s14, 0x1a020
	s_add_u32 s12, s12, 0x20000
	s_addc_u32 s13, s13, 0
	global_load_lds_dwordx4 v149, s[12:13]
	s_waitcnt lgkmcnt(4)
	v_mfma_f32_32x32x16_bf16 v[82:97], v[154:157], v[166:169], v[82:97]
	ds_read_b128 v[200:203], v210 offset:4096
	v_mfma_f32_32x32x16_bf16 v[66:81], v[154:157], v[170:173], v[66:81]
	ds_read_b128 v[180:183], v206 offset:4096
	s_add_u32 m0, s14, 0x1c020
	s_add_u32 s12, s12, 0x20000
	s_addc_u32 s13, s13, 0
	global_load_lds_dwordx4 v149, s[12:13]
	s_waitcnt lgkmcnt(5)
	v_mfma_f32_32x32x16_bf16 v[50:65], v[158:161], v[166:169], v[50:65]
	ds_read_b128 v[184:187], v206 offset:8192
	v_mfma_f32_32x32x16_bf16 v[34:49], v[158:161], v[170:173], v[34:49]
	ds_read_b128 v[188:191], v206 offset:12288
	s_add_u32 m0, s14, 0x1e020
	s_add_u32 s12, s12, 0x20000
	s_addc_u32 s13, s13, 0
	global_load_lds_dwordx4 v149, s[12:13]
	s_add_u32 s4, s4, 0x80
	s_addc_u32 s5, s5, 0
	s_waitcnt lgkmcnt(6)
	v_mfma_f32_32x32x16_bf16 v[18:33], v[162:165], v[166:169], v[18:33]
	v_mfma_f32_32x32x16_bf16 v[2:17], v[162:165], v[170:173], v[2:17]
	s_waitcnt lgkmcnt(4)
	v_mfma_f32_32x32x16_bf16 v[114:129], v[174:177], v[192:195], v[114:129]
	ds_read_b128 v[150:153], v207 offset:0
	s_waitcnt lgkmcnt(4)
	v_mfma_f32_32x32x16_bf16 v[98:113], v[174:177], v[200:203], v[98:113]
	ds_read_b128 v[166:169], v211 offset:0
	s_waitcnt lgkmcnt(4)
	v_mfma_f32_32x32x16_bf16 v[82:97], v[180:183], v[192:195], v[82:97]
	ds_read_b128 v[170:173], v211 offset:4096
	v_mfma_f32_32x32x16_bf16 v[66:81], v[180:183], v[200:203], v[66:81]
	ds_read_b128 v[154:157], v207 offset:4096
	s_waitcnt lgkmcnt(5)
	v_mfma_f32_32x32x16_bf16 v[50:65], v[184:187], v[192:195], v[50:65]
	ds_read_b128 v[158:161], v207 offset:8192
	v_mfma_f32_32x32x16_bf16 v[34:49], v[184:187], v[200:203], v[34:49]
	ds_read_b128 v[162:165], v207 offset:12288
	s_waitcnt lgkmcnt(6)
	v_mfma_f32_32x32x16_bf16 v[18:33], v[188:191], v[192:195], v[18:33]
	v_mfma_f32_32x32x16_bf16 v[2:17], v[188:191], v[200:203], v[2:17]
	s_waitcnt lgkmcnt(4)
	v_mfma_f32_32x32x16_bf16 v[114:129], v[150:153], v[166:169], v[114:129]
	ds_read_b128 v[174:177], v208 offset:0
	ds_read_b128 v[192:195], v212 offset:0
	s_waitcnt lgkmcnt(5)
	v_mfma_f32_32x32x16_bf16 v[98:113], v[150:153], v[170:173], v[98:113]
	ds_read_b128 v[200:203], v212 offset:4096
	ds_read_b128 v[180:183], v208 offset:4096
	s_waitcnt lgkmcnt(6)
	v_mfma_f32_32x32x16_bf16 v[82:97], v[154:157], v[166:169], v[82:97]
	ds_read_b128 v[184:187], v208 offset:8192
	ds_read_b128 v[188:191], v208 offset:12288
	v_mfma_f32_32x32x16_bf16 v[66:81], v[154:157], v[170:173], v[66:81]
	s_waitcnt lgkmcnt(7)
	v_mfma_f32_32x32x16_bf16 v[50:65], v[158:161], v[166:169], v[50:65]
	v_mfma_f32_32x32x16_bf16 v[34:49], v[158:161], v[170:173], v[34:49]
	s_waitcnt lgkmcnt(6)
	v_mfma_f32_32x32x16_bf16 v[18:33], v[162:165], v[166:169], v[18:33]
	v_mfma_f32_32x32x16_bf16 v[2:17], v[162:165], v[170:173], v[2:17]
	s_waitcnt vmcnt(0) lgkmcnt(0)
	s_barrier
	v_mfma_f32_32x32x16_bf16 v[114:129], v[174:177], v[192:195], v[114:129]
	ds_read_b128 v[150:153], v205 offset:32768
	s_add_u32 m0, s14, 0x20
	s_add_u32 s12, s1, s4
	s_addc_u32 s13, s3, s5
	global_load_lds_dwordx4 v149, s[12:13]
	v_mfma_f32_32x32x16_bf16 v[98:113], v[174:177], v[200:203], v[98:113]
	ds_read_b128 v[166:169], v209 offset:32768
	s_add_u32 m0, s14, 0x2020
	s_add_u32 s12, s12, 0x20000
	s_addc_u32 s13, s13, 0
	global_load_lds_dwordx4 v149, s[12:13]
	v_mfma_f32_32x32x16_bf16 v[82:97], v[180:183], v[192:195], v[82:97]
	ds_read_b128 v[170:173], v209 offset:36864
	s_add_u32 m0, s14, 0x4020
	s_add_u32 s12, s12, 0x20000
	s_addc_u32 s13, s13, 0
	global_load_lds_dwordx4 v149, s[12:13]
	v_mfma_f32_32x32x16_bf16 v[66:81], v[180:183], v[200:203], v[66:81]
	ds_read_b128 v[154:157], v205 offset:36864
	s_add_u32 m0, s14, 0x6020
	s_add_u32 s12, s12, 0x20000
	s_addc_u32 s13, s13, 0
	global_load_lds_dwordx4 v149, s[12:13]
	v_mfma_f32_32x32x16_bf16 v[50:65], v[184:187], v[192:195], v[50:65]
	ds_read_b128 v[158:161], v205 offset:40960
	s_add_u32 m0, s14, 0x10020
	s_add_u32 s12, s10, s4
	s_addc_u32 s13, s11, s5
	global_load_lds_dwordx4 v149, s[12:13]
	v_mfma_f32_32x32x16_bf16 v[34:49], v[184:187], v[200:203], v[34:49]
	ds_read_b128 v[162:165], v205 offset:45056
	v_mfma_f32_32x32x16_bf16 v[18:33], v[188:191], v[192:195], v[18:33]
	v_mfma_f32_32x32x16_bf16 v[2:17], v[188:191], v[200:203], v[2:17]
	s_waitcnt lgkmcnt(4)
	v_mfma_f32_32x32x16_bf16 v[114:129], v[150:153], v[166:169], v[114:129]
	ds_read_b128 v[174:177], v206 offset:32768
	s_waitcnt lgkmcnt(4)
	v_mfma_f32_32x32x16_bf16 v[98:113], v[150:153], v[170:173], v[98:113]
	ds_read_b128 v[192:195], v210 offset:32768
	s_add_u32 m0, s14, 0x12020
	s_add_u32 s12, s12, 0x20000
	s_addc_u32 s13, s13, 0
	global_load_lds_dwordx4 v149, s[12:13]
	s_waitcnt lgkmcnt(4)
	v_mfma_f32_32x32x16_bf16 v[82:97], v[154:157], v[166:169], v[82:97]
	ds_read_b128 v[200:203], v210 offset:36864
	v_mfma_f32_32x32x16_bf16 v[66:81], v[154:157], v[170:173], v[66:81]
	ds_read_b128 v[180:183], v206 offset:36864
	s_add_u32 m0, s14, 0x14020
	s_add_u32 s12, s12, 0x20000
	s_addc_u32 s13, s13, 0
	global_load_lds_dwordx4 v149, s[12:13]
	s_waitcnt lgkmcnt(5)
	v_mfma_f32_32x32x16_bf16 v[50:65], v[158:161], v[166:169], v[50:65]
	ds_read_b128 v[184:187], v206 offset:40960
	v_mfma_f32_32x32x16_bf16 v[34:49], v[158:161], v[170:173], v[34:49]
	ds_read_b128 v[188:191], v206 offset:45056
	s_add_u32 m0, s14, 0x16020
	s_add_u32 s12, s12, 0x20000
	s_addc_u32 s13, s13, 0
	global_load_lds_dwordx4 v149, s[12:13]
	s_add_u32 s4, s4, 0x80
	s_addc_u32 s5, s5, 0
	s_waitcnt lgkmcnt(6)
	v_mfma_f32_32x32x16_bf16 v[18:33], v[162:165], v[166:169], v[18:33]
	v_mfma_f32_32x32x16_bf16 v[2:17], v[162:165], v[170:173], v[2:17]
	s_waitcnt lgkmcnt(4)
	v_mfma_f32_32x32x16_bf16 v[114:129], v[174:177], v[192:195], v[114:129]
	ds_read_b128 v[150:153], v207 offset:32768
	s_waitcnt lgkmcnt(4)
	v_mfma_f32_32x32x16_bf16 v[98:113], v[174:177], v[200:203], v[98:113]
	ds_read_b128 v[166:169], v211 offset:32768
	s_waitcnt lgkmcnt(4)
	v_mfma_f32_32x32x16_bf16 v[82:97], v[180:183], v[192:195], v[82:97]
	ds_read_b128 v[170:173], v211 offset:36864
	v_mfma_f32_32x32x16_bf16 v[66:81], v[180:183], v[200:203], v[66:81]
	ds_read_b128 v[154:157], v207 offset:36864
	s_waitcnt lgkmcnt(5)
	v_mfma_f32_32x32x16_bf16 v[50:65], v[184:187], v[192:195], v[50:65]
	ds_read_b128 v[158:161], v207 offset:40960
	v_mfma_f32_32x32x16_bf16 v[34:49], v[184:187], v[200:203], v[34:49]
	ds_read_b128 v[162:165], v207 offset:45056
	s_waitcnt lgkmcnt(6)
	v_mfma_f32_32x32x16_bf16 v[18:33], v[188:191], v[192:195], v[18:33]
	v_mfma_f32_32x32x16_bf16 v[2:17], v[188:191], v[200:203], v[2:17]
	s_waitcnt lgkmcnt(4)
	v_mfma_f32_32x32x16_bf16 v[114:129], v[150:153], v[166:169], v[114:129]
	ds_read_b128 v[174:177], v208 offset:32768
	ds_read_b128 v[192:195], v212 offset:32768
	s_waitcnt lgkmcnt(5)
	v_mfma_f32_32x32x16_bf16 v[98:113], v[150:153], v[170:173], v[98:113]
	ds_read_b128 v[200:203], v212 offset:36864
	ds_read_b128 v[180:183], v208 offset:36864
	s_waitcnt lgkmcnt(6)
	v_mfma_f32_32x32x16_bf16 v[82:97], v[154:157], v[166:169], v[82:97]
	ds_read_b128 v[184:187], v208 offset:40960
	ds_read_b128 v[188:191], v208 offset:45056
	v_mfma_f32_32x32x16_bf16 v[66:81], v[154:157], v[170:173], v[66:81]
	s_waitcnt lgkmcnt(7)
	v_mfma_f32_32x32x16_bf16 v[50:65], v[158:161], v[166:169], v[50:65]
	v_mfma_f32_32x32x16_bf16 v[34:49], v[158:161], v[170:173], v[34:49]
	s_waitcnt lgkmcnt(6)
	v_mfma_f32_32x32x16_bf16 v[18:33], v[162:165], v[166:169], v[18:33]
	v_mfma_f32_32x32x16_bf16 v[2:17], v[162:165], v[170:173], v[2:17]
	s_waitcnt vmcnt(0) lgkmcnt(0)
	s_barrier
	v_mfma_f32_32x32x16_bf16 v[114:129], v[174:177], v[192:195], v[114:129]
	ds_read_b128 v[150:153], v205 offset:0
	s_add_u32 m0, s14, 0x8020
	s_add_u32 s12, s1, s4
	s_addc_u32 s13, s3, s5
	global_load_lds_dwordx4 v149, s[12:13]
	v_mfma_f32_32x32x16_bf16 v[98:113], v[174:177], v[200:203], v[98:113]
	ds_read_b128 v[166:169], v209 offset:0
	s_add_u32 m0, s14, 0xa020
	s_add_u32 s12, s12, 0x20000
	s_addc_u32 s13, s13, 0
	global_load_lds_dwordx4 v149, s[12:13]
	v_mfma_f32_32x32x16_bf16 v[82:97], v[180:183], v[192:195], v[82:97]
	ds_read_b128 v[170:173], v209 offset:4096
	s_add_u32 m0, s14, 0xc020
	s_add_u32 s12, s12, 0x20000
	s_addc_u32 s13, s13, 0
	global_load_lds_dwordx4 v149, s[12:13]
	v_mfma_f32_32x32x16_bf16 v[66:81], v[180:183], v[200:203], v[66:81]
	ds_read_b128 v[154:157], v205 offset:4096
	s_add_u32 m0, s14, 0xe020
	s_add_u32 s12, s12, 0x20000
	s_addc_u32 s13, s13, 0
	global_load_lds_dwordx4 v149, s[12:13]
	v_mfma_f32_32x32x16_bf16 v[50:65], v[184:187], v[192:195], v[50:65]
	ds_read_b128 v[158:161], v205 offset:8192
	s_add_u32 m0, s14, 0x18020
	s_add_u32 s12, s10, s4
	s_addc_u32 s13, s11, s5
	global_load_lds_dwordx4 v149, s[12:13]
	v_mfma_f32_32x32x16_bf16 v[34:49], v[184:187], v[200:203], v[34:49]
	ds_read_b128 v[162:165], v205 offset:12288
	v_mfma_f32_32x32x16_bf16 v[18:33], v[188:191], v[192:195], v[18:33]
	v_mfma_f32_32x32x16_bf16 v[2:17], v[188:191], v[200:203], v[2:17]
	s_sub_u32 s9, s9, 1
	s_cmp_lg_u32 s9, 0
	s_cbranch_scc1 .Lg910_loop
	s_waitcnt lgkmcnt(4)
	v_mfma_f32_32x32x16_bf16 v[114:129], v[150:153], v[166:169], v[114:129]
	ds_read_b128 v[174:177], v206 offset:0
	s_waitcnt lgkmcnt(4)
	v_mfma_f32_32x32x16_bf16 v[98:113], v[150:153], v[170:173], v[98:113]
	ds_read_b128 v[192:195], v210 offset:0
	s_add_u32 m0, s14, 0x1a020
	s_add_u32 s12, s12, 0x20000
	s_addc_u32 s13, s13, 0
	global_load_lds_dwordx4 v149, s[12:13]
	s_waitcnt lgkmcnt(4)
	v_mfma_f32_32x32x16_bf16 v[82:97], v[154:157], v[166:169], v[82:97]
	ds_read_b128 v[200:203], v210 offset:4096
	v_mfma_f32_32x32x16_bf16 v[66:81], v[154:157], v[170:173], v[66:81]
	ds_read_b128 v[180:183], v206 offset:4096
	s_add_u32 m0, s14, 0x1c020
	s_add_u32 s12, s12, 0x20000
	s_addc_u32 s13, s13, 0
	global_load_lds_dwordx4 v149, s[12:13]
	s_waitcnt lgkmcnt(5)
	v_mfma_f32_32x32x16_bf16 v[50:65], v[158:161], v[166:169], v[50:65]
	ds_read_b128 v[184:187], v206 offset:8192
	v_mfma_f32_32x32x16_bf16 v[34:49], v[158:161], v[170:173], v[34:49]
	ds_read_b128 v[188:191], v206 offset:12288
	s_add_u32 m0, s14, 0x1e020
	s_add_u32 s12, s12, 0x20000
	s_addc_u32 s13, s13, 0
	global_load_lds_dwordx4 v149, s[12:13]
	s_add_u32 s4, s4, 0x80
	s_addc_u32 s5, s5, 0
	s_waitcnt lgkmcnt(6)
	v_mfma_f32_32x32x16_bf16 v[18:33], v[162:165], v[166:169], v[18:33]
	v_mfma_f32_32x32x16_bf16 v[2:17], v[162:165], v[170:173], v[2:17]
	s_waitcnt lgkmcnt(4)
	v_mfma_f32_32x32x16_bf16 v[114:129], v[174:177], v[192:195], v[114:129]
	ds_read_b128 v[150:153], v207 offset:0
	s_waitcnt lgkmcnt(4)
	v_mfma_f32_32x32x16_bf16 v[98:113], v[174:177], v[200:203], v[98:113]
	ds_read_b128 v[166:169], v211 offset:0
	s_waitcnt lgkmcnt(4)
	v_mfma_f32_32x32x16_bf16 v[82:97], v[180:183], v[192:195], v[82:97]
	ds_read_b128 v[170:173], v211 offset:4096
	v_mfma_f32_32x32x16_bf16 v[66:81], v[180:183], v[200:203], v[66:81]
	ds_read_b128 v[154:157], v207 offset:4096
	s_waitcnt lgkmcnt(5)
	v_mfma_f32_32x32x16_bf16 v[50:65], v[184:187], v[192:195], v[50:65]
	ds_read_b128 v[158:161], v207 offset:8192
	v_mfma_f32_32x32x16_bf16 v[34:49], v[184:187], v[200:203], v[34:49]
	ds_read_b128 v[162:165], v207 offset:12288
	s_waitcnt lgkmcnt(6)
	v_mfma_f32_32x32x16_bf16 v[18:33], v[188:191], v[192:195], v[18:33]
	v_mfma_f32_32x32x16_bf16 v[2:17], v[188:191], v[200:203], v[2:17]
	s_waitcnt lgkmcnt(4)
	v_mfma_f32_32x32x16_bf16 v[114:129], v[150:153], v[166:169], v[114:129]
	ds_read_b128 v[174:177], v208 offset:0
	ds_read_b128 v[192:195], v212 offset:0
	s_waitcnt lgkmcnt(5)
	v_mfma_f32_32x32x16_bf16 v[98:113], v[150:153], v[170:173], v[98:113]
	ds_read_b128 v[200:203], v212 offset:4096
	ds_read_b128 v[180:183], v208 offset:4096
	s_waitcnt lgkmcnt(6)
	v_mfma_f32_32x32x16_bf16 v[82:97], v[154:157], v[166:169], v[82:97]
	ds_read_b128 v[184:187], v208 offset:8192
	ds_read_b128 v[188:191], v208 offset:12288
	v_mfma_f32_32x32x16_bf16 v[66:81], v[154:157], v[170:173], v[66:81]
	s_waitcnt lgkmcnt(7)
	v_mfma_f32_32x32x16_bf16 v[50:65], v[158:161], v[166:169], v[50:65]
	v_mfma_f32_32x32x16_bf16 v[34:49], v[158:161], v[170:173], v[34:49]
	s_waitcnt lgkmcnt(6)
	v_mfma_f32_32x32x16_bf16 v[18:33], v[162:165], v[166:169], v[18:33]
	v_mfma_f32_32x32x16_bf16 v[2:17], v[162:165], v[170:173], v[2:17]
	s_waitcnt vmcnt(0) lgkmcnt(0)
	s_barrier
	v_mfma_f32_32x32x16_bf16 v[114:129], v[174:177], v[192:195], v[114:129]
	ds_read_b128 v[150:153], v205 offset:32768
	v_mfma_f32_32x32x16_bf16 v[98:113], v[174:177], v[200:203], v[98:113]
	ds_read_b128 v[166:169], v209 offset:32768
	v_mfma_f32_32x32x16_bf16 v[82:97], v[180:183], v[192:195], v[82:97]
	ds_read_b128 v[170:173], v209 offset:36864
	v_mfma_f32_32x32x16_bf16 v[66:81], v[180:183], v[200:203], v[66:81]
	ds_read_b128 v[154:157], v205 offset:36864
	v_mfma_f32_32x32x16_bf16 v[50:65], v[184:187], v[192:195], v[50:65]
	ds_read_b128 v[158:161], v205 offset:40960
	v_mfma_f32_32x32x16_bf16 v[34:49], v[184:187], v[200:203], v[34:49]
	ds_read_b128 v[162:165], v205 offset:45056
	v_mfma_f32_32x32x16_bf16 v[18:33], v[188:191], v[192:195], v[18:33]
	v_mfma_f32_32x32x16_bf16 v[2:17], v[188:191], v[200:203], v[2:17]
	s_waitcnt lgkmcnt(4)
	v_mfma_f32_32x32x16_bf16 v[114:129], v[150:153], v[166:169], v[114:129]
	ds_read_b128 v[174:177], v206 offset:32768
	s_waitcnt lgkmcnt(4)
	v_mfma_f32_32x32x16_bf16 v[98:113], v[150:153], v[170:173], v[98:113]
	ds_read_b128 v[192:195], v210 offset:32768
	s_waitcnt lgkmcnt(4)
	v_mfma_f32_32x32x16_bf16 v[82:97], v[154:157], v[166:169], v[82:97]
	ds_read_b128 v[200:203], v210 offset:36864
	v_mfma_f32_32x32x16_bf16 v[66:81], v[154:157], v[170:173], v[66:81]
	ds_read_b128 v[180:183], v206 offset:36864
	s_waitcnt lgkmcnt(5)
	v_mfma_f32_32x32x16_bf16 v[50:65], v[158:161], v[166:169], v[50:65]
	ds_read_b128 v[184:187], v206 offset:40960
	v_mfma_f32_32x32x16_bf16 v[34:49], v[158:161], v[170:173], v[34:49]
	ds_read_b128 v[188:191], v206 offset:45056
	s_waitcnt lgkmcnt(6)
	v_mfma_f32_32x32x16_bf16 v[18:33], v[162:165], v[166:169], v[18:33]
	v_mfma_f32_32x32x16_bf16 v[2:17], v[162:165], v[170:173], v[2:17]
	s_waitcnt lgkmcnt(4)
	v_mfma_f32_32x32x16_bf16 v[114:129], v[174:177], v[192:195], v[114:129]
	ds_read_b128 v[150:153], v207 offset:32768
	s_waitcnt lgkmcnt(4)
	v_mfma_f32_32x32x16_bf16 v[98:113], v[174:177], v[200:203], v[98:113]
	ds_read_b128 v[166:169], v211 offset:32768
	s_waitcnt lgkmcnt(4)
	v_mfma_f32_32x32x16_bf16 v[82:97], v[180:183], v[192:195], v[82:97]
	ds_read_b128 v[170:173], v211 offset:36864
	v_mfma_f32_32x32x16_bf16 v[66:81], v[180:183], v[200:203], v[66:81]
	ds_read_b128 v[154:157], v207 offset:36864
	s_waitcnt lgkmcnt(5)
	v_mfma_f32_32x32x16_bf16 v[50:65], v[184:187], v[192:195], v[50:65]
	ds_read_b128 v[158:161], v207 offset:40960
	v_mfma_f32_32x32x16_bf16 v[34:49], v[184:187], v[200:203], v[34:49]
	ds_read_b128 v[162:165], v207 offset:45056
	s_waitcnt lgkmcnt(6)
	v_mfma_f32_32x32x16_bf16 v[18:33], v[188:191], v[192:195], v[18:33]
	v_mfma_f32_32x32x16_bf16 v[2:17], v[188:191], v[200:203], v[2:17]
	s_waitcnt lgkmcnt(4)
	v_mfma_f32_32x32x16_bf16 v[114:129], v[150:153], v[166:169], v[114:129]
	ds_read_b128 v[174:177], v208 offset:32768
	ds_read_b128 v[192:195], v212 offset:32768
	s_waitcnt lgkmcnt(5)
	v_mfma_f32_32x32x16_bf16 v[98:113], v[150:153], v[170:173], v[98:113]
	ds_read_b128 v[200:203], v212 offset:36864
	ds_read_b128 v[180:183], v208 offset:36864
	s_waitcnt lgkmcnt(6)
	v_mfma_f32_32x32x16_bf16 v[82:97], v[154:157], v[166:169], v[82:97]
	ds_read_b128 v[184:187], v208 offset:40960
	ds_read_b128 v[188:191], v208 offset:45056
	v_mfma_f32_32x32x16_bf16 v[66:81], v[154:157], v[170:173], v[66:81]
	s_waitcnt lgkmcnt(7)
	v_mfma_f32_32x32x16_bf16 v[50:65], v[158:161], v[166:169], v[50:65]
	v_mfma_f32_32x32x16_bf16 v[34:49], v[158:161], v[170:173], v[34:49]
	s_waitcnt lgkmcnt(6)
	v_mfma_f32_32x32x16_bf16 v[18:33], v[162:165], v[166:169], v[18:33]
	v_mfma_f32_32x32x16_bf16 v[2:17], v[162:165], v[170:173], v[2:17]
	s_waitcnt vmcnt(0) lgkmcnt(0)
	s_barrier
	v_mfma_f32_32x32x16_bf16 v[114:129], v[174:177], v[192:195], v[114:129]
	v_mfma_f32_32x32x16_bf16 v[98:113], v[174:177], v[200:203], v[98:113]
	v_mfma_f32_32x32x16_bf16 v[82:97], v[180:183], v[192:195], v[82:97]
	v_mfma_f32_32x32x16_bf16 v[66:81], v[180:183], v[200:203], v[66:81]
	v_mfma_f32_32x32x16_bf16 v[50:65], v[184:187], v[192:195], v[50:65]
	v_mfma_f32_32x32x16_bf16 v[34:49], v[184:187], v[200:203], v[34:49]
	v_mfma_f32_32x32x16_bf16 v[18:33], v[188:191], v[192:195], v[18:33]
	v_mfma_f32_32x32x16_bf16 v[2:17], v[188:191], v[200:203], v[2:17]
	s_setprio 0
	v_add_u32_e32 v149, s0, v143
	v_or_b32_e32 v130, s2, v144
	s_mov_b32 s2, 0x7e07e07f
	v_mul_hi_i32 v0, v149, s2
	v_lshrrev_b32_e32 v131, 31, v0
	v_ashrrev_i32_e32 v0, 13, v0
	v_add_u32_e32 v0, v0, v131
	v_mul_i32_i24_e32 v131, 0x4100, v0
	v_sub_u32_e32 v131, v149, v131
	s_movk_i32 s3, 0xff
	v_mul_i32_i24_e32 v0, 0xc00, v0
	v_cmp_lt_i32_e32 vcc, s3, v131
	v_mov_b32_e32 v162, 0x1800
	v_mov_b32_e32 v152, v179
	s_waitcnt vmcnt(0)
	s_barrier
	v_cndmask_b32_e32 v150, v162, v0, vcc
	v_readlane_b32 s12, v251, 2
	v_and_b32_e32 v0, 31, v152
	v_bfe_u32 v131, v152, 5, 1
	v_mul_u32_u24_e32 v131, 0x240, v131
	v_lshlrev_b32_e32 v0, 2, v0
	v_add3_u32 v0, v145, v131, v0
	ds_write2_b32 v0, v114, v115 offset1:36
	ds_write2_b32 v0, v116, v117 offset0:72 offset1:108
	v_add_u32_e32 v114, 0x400, v0
	v_ashrrev_i32_e32 v151, 31, v150
	ds_write2_b32 v114, v118, v119 offset0:32 offset1:68
	ds_write2_b32 v114, v120, v121 offset0:104 offset1:140
	v_add_u32_e32 v114, 0x800, v0
	v_add_u32_e32 v0, 0xc00, v0
	v_readlane_b32 s26, v251, 16
	v_readlane_b32 s27, v251, 17
	ds_write2_b32 v114, v122, v123 offset0:64 offset1:100
	ds_write2_b32 v114, v124, v125 offset0:136 offset1:172
	ds_write2_b32 v0, v126, v127 offset0:96 offset1:132
	ds_write2_b32 v0, v128, v129 offset0:168 offset1:204
	v_lshl_add_u64 v[114:115], v[150:151], 2, s[26:27]
	s_mov_b64 s[4:5], 0x1b02000
	v_ashrrev_i32_e32 v131, 31, v130
	v_readlane_b32 s0, v251, 26
	v_lshlrev_b32_e32 v0, 3, v152
	v_lshl_add_u64 v[118:119], v[114:115], 0, s[4:5]
	v_lshlrev_b64 v[116:117], 2, v[130:131]
	v_readlane_b32 s1, v251, 27
	v_and_b32_e32 v122, 24, v0
	v_lshl_add_u64 v[120:121], v[118:119], 0, v[116:117]
	v_lshl_add_u64 v[114:115], v[130:131], 1, s[0:1]
	v_lshlrev_b32_e32 v0, 2, v122
	v_bfe_u32 v131, v152, 2, 4
	v_lshl_add_u64 v[158:159], v[120:121], 0, v[0:1]
	v_lshlrev_b32_e32 v120, 1, v122
	v_mul_u32_u24_e32 v122, 0x90, v131
	s_waitcnt lgkmcnt(0)
	v_add3_u32 v0, v145, v0, v122
	ds_read_b128 v[122:125], v0
	ds_read_b128 v[126:129], v0 offset:16
	global_load_dwordx4 v[150:153], v[158:159], off offset:16
	global_load_dwordx4 v[154:157], v[158:159], off
	v_or_b32_e32 v160, v131, v149
	v_mov_b32_e32 v121, v1
	v_ashrrev_i32_e32 v161, 31, v160
	v_lshl_add_u64 v[120:121], v[114:115], 0, v[120:121]
	v_readlane_b32 s13, v251, 3
	v_readlane_b32 s14, v251, 4
	v_readlane_b32 s15, v251, 5
	v_readlane_b32 s16, v251, 6
	v_readlane_b32 s17, v251, 7
	v_readlane_b32 s18, v251, 8
	v_readlane_b32 s19, v251, 9
	v_readlane_b32 s20, v251, 10
	v_readlane_b32 s21, v251, 11
	v_readlane_b32 s22, v251, 12
	v_readlane_b32 s23, v251, 13
	v_readlane_b32 s24, v251, 14
	v_readlane_b32 s25, v251, 15
	s_waitcnt vmcnt(1) lgkmcnt(0)
	v_pk_mul_f32 v[126:127], v[126:127], v[150:151]
	s_waitcnt vmcnt(0)
	v_pk_mul_f32 v[122:123], v[122:123], v[154:155]
	v_pk_mul_f32 v[124:125], v[124:125], v[156:157]
	v_pk_mul_f32 v[128:129], v[128:129], v[152:153]
	v_cvt_pk_bf16_f32 v122, v122, v123
	v_cvt_pk_bf16_f32 v123, v124, v125
	v_cvt_pk_bf16_f32 v124, v126, v127
	v_lshlrev_b64 v[126:127], 11, v[160:161]
	v_cvt_pk_bf16_f32 v125, v128, v129
	v_lshl_add_u64 v[126:127], v[120:121], 0, v[126:127]
	global_store_dwordx4 v[126:127], v[122:125], off
	ds_read_b128 v[122:125], v0 offset:2304
	ds_read_b128 v[126:129], v0 offset:2320
	global_load_dwordx4 v[150:153], v[158:159], off offset:16
	global_load_dwordx4 v[154:157], v[158:159], off
	s_waitcnt vmcnt(1) lgkmcnt(0)
	v_pk_mul_f32 v[126:127], v[126:127], v[150:151]
	s_waitcnt vmcnt(0)
	v_pk_mul_f32 v[122:123], v[122:123], v[154:155]
	v_pk_mul_f32 v[124:125], v[124:125], v[156:157]
	v_cvt_pk_bf16_f32 v122, v122, v123
	v_cvt_pk_bf16_f32 v123, v124, v125
	v_cvt_pk_bf16_f32 v124, v126, v127
	v_or_b32_e32 v126, 16, v160
	v_ashrrev_i32_e32 v127, 31, v126
	v_pk_mul_f32 v[128:129], v[128:129], v[152:153]
	v_lshlrev_b64 v[126:127], 11, v[126:127]
	v_cvt_pk_bf16_f32 v125, v128, v129
	v_lshl_add_u64 v[120:121], v[120:121], 0, v[126:127]
	global_store_dwordx4 v[120:121], v[122:125], off
	v_mov_b32_e32 v120, v179
	v_or_b32_e32 v126, 32, v130
	v_and_b32_e32 v0, 31, v120
	v_bfe_u32 v121, v120, 5, 1
	v_mul_u32_u24_e32 v121, 0x240, v121
	v_lshlrev_b32_e32 v0, 2, v0
	v_add3_u32 v0, v145, v121, v0
	ds_write2_b32 v0, v98, v99 offset1:36
	ds_write2_b32 v0, v100, v101 offset0:72 offset1:108
	v_add_u32_e32 v98, 0x400, v0
	ds_write2_b32 v98, v102, v103 offset0:32 offset1:68
	ds_write2_b32 v98, v104, v105 offset0:104 offset1:140
	v_add_u32_e32 v98, 0x800, v0
	v_add_u32_e32 v0, 0xc00, v0
	ds_write2_b32 v98, v106, v107 offset0:64 offset1:100
	ds_write2_b32 v98, v108, v109 offset0:136 offset1:172
	ds_write2_b32 v0, v110, v111 offset0:96 offset1:132
	ds_write2_b32 v0, v112, v113 offset0:168 offset1:204
	v_lshlrev_b32_e32 v0, 3, v120
	v_and_b32_e32 v102, 24, v0
	v_ashrrev_i32_e32 v127, 31, v126
	v_lshlrev_b32_e32 v0, 2, v102
	v_lshl_add_u64 v[98:99], v[118:119], 0, v[0:1]
	v_lshlrev_b64 v[100:101], 2, v[126:127]
	v_lshl_add_u64 v[112:113], v[98:99], 0, v[100:101]
	v_lshlrev_b32_e32 v98, 1, v102
	v_mov_b32_e32 v99, v1
	v_bfe_u32 v128, v120, 2, 4
	v_lshl_add_u64 v[102:103], s[0:1], 0, v[98:99]
	v_mul_u32_u24_e32 v98, 0x90, v128
	s_waitcnt lgkmcnt(0)
	v_add3_u32 v0, v145, v0, v98
	ds_read_b128 v[104:107], v0
	ds_read_b128 v[108:111], v0 offset:16
	global_load_dwordx4 v[118:121], v[112:113], off offset:16
	global_load_dwordx4 v[122:125], v[112:113], off
	v_or_b32_e32 v128, v128, v149
	v_ashrrev_i32_e32 v129, 31, v128
	s_waitcnt vmcnt(1) lgkmcnt(0)
	v_pk_mul_f32 v[108:109], v[108:109], v[118:119]
	s_waitcnt vmcnt(0)
	v_pk_mul_f32 v[98:99], v[104:105], v[122:123]
	v_pk_mul_f32 v[106:107], v[106:107], v[124:125]
	v_cvt_pk_bf16_f32 v104, v98, v99
	v_lshlrev_b64 v[98:99], 11, v[128:129]
	v_pk_mul_f32 v[110:111], v[110:111], v[120:121]
	v_cvt_pk_bf16_f32 v105, v106, v107
	v_cvt_pk_bf16_f32 v106, v108, v109
	v_lshl_add_u64 v[108:109], v[102:103], 0, v[98:99]
	v_lshlrev_b64 v[98:99], 1, v[126:127]
	v_cvt_pk_bf16_f32 v107, v110, v111
	v_lshl_add_u64 v[108:109], v[108:109], 0, v[98:99]
	global_store_dwordx4 v[108:109], v[104:107], off
	ds_read_b128 v[104:107], v0 offset:2304
	ds_read_b128 v[108:111], v0 offset:2320
	global_load_dwordx4 v[118:121], v[112:113], off offset:16
	global_load_dwordx4 v[122:125], v[112:113], off
	s_waitcnt vmcnt(1) lgkmcnt(0)
	v_pk_mul_f32 v[108:109], v[108:109], v[118:119]
	s_waitcnt vmcnt(0)
	v_pk_mul_f32 v[104:105], v[104:105], v[122:123]
	v_pk_mul_f32 v[106:107], v[106:107], v[124:125]
	v_cvt_pk_bf16_f32 v104, v104, v105
	v_cvt_pk_bf16_f32 v105, v106, v107
	v_cvt_pk_bf16_f32 v106, v108, v109
	v_or_b32_e32 v108, 16, v128
	v_ashrrev_i32_e32 v109, 31, v108
	v_lshlrev_b64 v[108:109], 11, v[108:109]
	v_pk_mul_f32 v[110:111], v[110:111], v[120:121]
	v_lshl_add_u64 v[102:103], v[102:103], 0, v[108:109]
	v_cvt_pk_bf16_f32 v107, v110, v111
	v_lshl_add_u64 v[102:103], v[102:103], 0, v[98:99]
	global_store_dwordx4 v[102:103], v[104:107], off
	v_or_b32_e32 v110, 32, v149
	v_mul_hi_i32 v0, v110, s2
	v_lshrrev_b32_e32 v102, 31, v0
	v_ashrrev_i32_e32 v0, 13, v0
	v_add_u32_e32 v0, v0, v102
	v_mul_i32_i24_e32 v102, 0x4100, v0
	v_sub_u32_e32 v102, v110, v102
	v_mul_i32_i24_e32 v0, 0xc00, v0
	v_cmp_lt_i32_e32 vcc, s3, v102
	v_mov_b32_e32 v104, v179
	s_nop 0
	v_cndmask_b32_e32 v102, v162, v0, vcc
	v_and_b32_e32 v0, 31, v104
	v_bfe_u32 v105, v104, 5, 1
	v_mul_u32_u24_e32 v105, 0x240, v105
	v_lshlrev_b32_e32 v0, 2, v0
	v_add3_u32 v0, v145, v105, v0
	ds_write2_b32 v0, v82, v83 offset1:36
	ds_write2_b32 v0, v84, v85 offset0:72 offset1:108
	v_add_u32_e32 v82, 0x400, v0
	v_ashrrev_i32_e32 v103, 31, v102
	ds_write2_b32 v82, v86, v87 offset0:32 offset1:68
	ds_write2_b32 v82, v88, v89 offset0:104 offset1:140
	v_add_u32_e32 v82, 0x800, v0
	v_add_u32_e32 v0, 0xc00, v0
	ds_write2_b32 v82, v90, v91 offset0:64 offset1:100
	ds_write2_b32 v82, v92, v93 offset0:136 offset1:172
	ds_write2_b32 v0, v94, v95 offset0:96 offset1:132
	ds_write2_b32 v0, v96, v97 offset0:168 offset1:204
	v_lshl_add_u64 v[82:83], v[102:103], 2, s[26:27]
	v_lshlrev_b32_e32 v0, 3, v104
	v_lshl_add_u64 v[82:83], v[82:83], 0, s[4:5]
	v_and_b32_e32 v86, 24, v0
	v_lshl_add_u64 v[84:85], v[82:83], 0, v[116:117]
	v_lshlrev_b32_e32 v0, 2, v86
	v_bfe_u32 v108, v104, 2, 4
	v_lshl_add_u64 v[106:107], v[84:85], 0, v[0:1]
	v_lshlrev_b32_e32 v84, 1, v86
	v_mul_u32_u24_e32 v86, 0x90, v108
	s_waitcnt lgkmcnt(0)
	v_add3_u32 v0, v145, v0, v86
	ds_read_b128 v[86:89], v0
	ds_read_b128 v[90:93], v0 offset:16
	global_load_dwordx4 v[94:97], v[106:107], off offset:16
	global_load_dwordx4 v[102:105], v[106:107], off
	v_or_b32_e32 v108, v108, v110
	v_mov_b32_e32 v85, v1
	v_ashrrev_i32_e32 v109, 31, v108
	v_lshl_add_u64 v[84:85], v[114:115], 0, v[84:85]
	s_waitcnt vmcnt(1) lgkmcnt(0)
	v_pk_mul_f32 v[90:91], v[90:91], v[94:95]
	s_waitcnt vmcnt(0)
	v_pk_mul_f32 v[86:87], v[86:87], v[102:103]
	v_pk_mul_f32 v[88:89], v[88:89], v[104:105]
	v_pk_mul_f32 v[92:93], v[92:93], v[96:97]
	v_cvt_pk_bf16_f32 v86, v86, v87
	v_cvt_pk_bf16_f32 v87, v88, v89
	v_cvt_pk_bf16_f32 v88, v90, v91
	v_lshlrev_b64 v[90:91], 11, v[108:109]
	v_cvt_pk_bf16_f32 v89, v92, v93
	v_lshl_add_u64 v[90:91], v[84:85], 0, v[90:91]
	global_store_dwordx4 v[90:91], v[86:89], off
	ds_read_b128 v[86:89], v0 offset:2304
	ds_read_b128 v[90:93], v0 offset:2320
	global_load_dwordx4 v[94:97], v[106:107], off offset:16
	global_load_dwordx4 v[102:105], v[106:107], off
	s_waitcnt vmcnt(1) lgkmcnt(0)
	v_pk_mul_f32 v[90:91], v[90:91], v[94:95]
	s_waitcnt vmcnt(0)
	v_pk_mul_f32 v[86:87], v[86:87], v[102:103]
	v_pk_mul_f32 v[88:89], v[88:89], v[104:105]
	v_cvt_pk_bf16_f32 v86, v86, v87
	v_cvt_pk_bf16_f32 v87, v88, v89
	v_cvt_pk_bf16_f32 v88, v90, v91
	v_or_b32_e32 v90, 16, v108
	v_ashrrev_i32_e32 v91, 31, v90
	v_pk_mul_f32 v[92:93], v[92:93], v[96:97]
	v_lshlrev_b64 v[90:91], 11, v[90:91]
	v_cvt_pk_bf16_f32 v89, v92, v93
	v_lshl_add_u64 v[84:85], v[84:85], 0, v[90:91]
	global_store_dwordx4 v[84:85], v[86:89], off
	s_nop 1
	v_mov_b32_e32 v86, v179
	s_nop 0
	v_and_b32_e32 v0, 31, v86
	v_bfe_u32 v84, v86, 5, 1
	v_mul_u32_u24_e32 v84, 0x240, v84
	v_lshlrev_b32_e32 v0, 2, v0
	v_add3_u32 v0, v145, v84, v0
	ds_write2_b32 v0, v66, v67 offset1:36
	ds_write2_b32 v0, v68, v69 offset0:72 offset1:108
	v_add_u32_e32 v66, 0x400, v0
	ds_write2_b32 v66, v70, v71 offset0:32 offset1:68
	ds_write2_b32 v66, v72, v73 offset0:104 offset1:140
	v_add_u32_e32 v66, 0x800, v0
	v_add_u32_e32 v0, 0xc00, v0
	ds_write2_b32 v66, v74, v75 offset0:64 offset1:100
	ds_write2_b32 v66, v76, v77 offset0:136 offset1:172
	ds_write2_b32 v0, v78, v79 offset0:96 offset1:132
	ds_write2_b32 v0, v80, v81 offset0:168 offset1:204
	v_lshlrev_b32_e32 v0, 3, v86
	v_and_b32_e32 v68, 24, v0
	v_lshlrev_b32_e32 v0, 2, v68
	v_lshl_add_u64 v[66:67], v[82:83], 0, v[0:1]
	v_bfe_u32 v86, v86, 2, 4
	v_lshl_add_u64 v[84:85], v[66:67], 0, v[100:101]
	v_lshlrev_b32_e32 v66, 1, v68
	v_mul_u32_u24_e32 v68, 0x90, v86
	s_waitcnt lgkmcnt(0)
	v_add3_u32 v0, v145, v0, v68
	ds_read_b128 v[68:71], v0
	ds_read_b128 v[72:75], v0 offset:16
	global_load_dwordx4 v[76:79], v[84:85], off offset:16
	global_load_dwordx4 v[80:83], v[84:85], off
	v_or_b32_e32 v86, v86, v110
	v_mov_b32_e32 v67, v1
	v_ashrrev_i32_e32 v87, 31, v86
	v_lshl_add_u64 v[66:67], s[0:1], 0, v[66:67]
	s_waitcnt vmcnt(1) lgkmcnt(0)
	v_pk_mul_f32 v[72:73], v[72:73], v[76:77]
	s_waitcnt vmcnt(0)
	v_pk_mul_f32 v[68:69], v[68:69], v[80:81]
	v_pk_mul_f32 v[70:71], v[70:71], v[82:83]
	v_cvt_pk_bf16_f32 v68, v68, v69
	v_cvt_pk_bf16_f32 v69, v70, v71
	v_cvt_pk_bf16_f32 v70, v72, v73
	v_lshlrev_b64 v[72:73], 11, v[86:87]
	v_pk_mul_f32 v[74:75], v[74:75], v[78:79]
	v_lshl_add_u64 v[72:73], v[66:67], 0, v[72:73]
	v_cvt_pk_bf16_f32 v71, v74, v75
	v_lshl_add_u64 v[72:73], v[72:73], 0, v[98:99]
	global_store_dwordx4 v[72:73], v[68:71], off
	ds_read_b128 v[68:71], v0 offset:2304
	ds_read_b128 v[72:75], v0 offset:2320
	global_load_dwordx4 v[76:79], v[84:85], off offset:16
	global_load_dwordx4 v[80:83], v[84:85], off
	s_waitcnt vmcnt(1) lgkmcnt(0)
	v_pk_mul_f32 v[72:73], v[72:73], v[76:77]
	s_waitcnt vmcnt(0)
	v_pk_mul_f32 v[68:69], v[68:69], v[80:81]
	v_pk_mul_f32 v[70:71], v[70:71], v[82:83]
	v_cvt_pk_bf16_f32 v68, v68, v69
	v_cvt_pk_bf16_f32 v69, v70, v71
	v_cvt_pk_bf16_f32 v70, v72, v73
	v_or_b32_e32 v72, 16, v86
	v_ashrrev_i32_e32 v73, 31, v72
	v_lshlrev_b64 v[72:73], 11, v[72:73]
	v_pk_mul_f32 v[74:75], v[74:75], v[78:79]
	v_lshl_add_u64 v[66:67], v[66:67], 0, v[72:73]
	v_cvt_pk_bf16_f32 v71, v74, v75
	v_lshl_add_u64 v[66:67], v[66:67], 0, v[98:99]
	global_store_dwordx4 v[66:67], v[68:71], off
	v_or_b32_e32 v74, 64, v149
	v_mul_hi_i32 v0, v74, s2
	v_lshrrev_b32_e32 v66, 31, v0
	v_ashrrev_i32_e32 v0, 13, v0
	v_add_u32_e32 v0, v0, v66
	v_mul_i32_i24_e32 v66, 0x4100, v0
	v_sub_u32_e32 v66, v74, v66
	v_mul_i32_i24_e32 v0, 0xc00, v0
	v_cmp_lt_i32_e32 vcc, s3, v66
	v_mov_b32_e32 v68, v179
	s_nop 0
	v_cndmask_b32_e32 v66, v162, v0, vcc
	v_and_b32_e32 v0, 31, v68
	v_bfe_u32 v69, v68, 5, 1
	v_mul_u32_u24_e32 v69, 0x240, v69
	v_lshlrev_b32_e32 v0, 2, v0
	v_add3_u32 v0, v145, v69, v0
	ds_write2_b32 v0, v50, v51 offset1:36
	ds_write2_b32 v0, v52, v53 offset0:72 offset1:108
	v_add_u32_e32 v50, 0x400, v0
	v_ashrrev_i32_e32 v67, 31, v66
	ds_write2_b32 v50, v54, v55 offset0:32 offset1:68
	ds_write2_b32 v50, v56, v57 offset0:104 offset1:140
	v_add_u32_e32 v50, 0x800, v0
	v_add_u32_e32 v0, 0xc00, v0
	ds_write2_b32 v50, v58, v59 offset0:64 offset1:100
	ds_write2_b32 v50, v60, v61 offset0:136 offset1:172
	ds_write2_b32 v0, v62, v63 offset0:96 offset1:132
	ds_write2_b32 v0, v64, v65 offset0:168 offset1:204
	v_lshl_add_u64 v[50:51], v[66:67], 2, s[26:27]
	v_lshlrev_b32_e32 v0, 3, v68
	v_lshl_add_u64 v[50:51], v[50:51], 0, s[4:5]
	v_and_b32_e32 v54, 24, v0
	v_lshl_add_u64 v[52:53], v[50:51], 0, v[116:117]
	v_lshlrev_b32_e32 v0, 2, v54
	v_bfe_u32 v72, v68, 2, 4
	v_lshl_add_u64 v[70:71], v[52:53], 0, v[0:1]
	v_lshlrev_b32_e32 v52, 1, v54
	v_mul_u32_u24_e32 v54, 0x90, v72
	s_waitcnt lgkmcnt(0)
	v_add3_u32 v0, v145, v0, v54
	ds_read_b128 v[54:57], v0
	ds_read_b128 v[58:61], v0 offset:16
	global_load_dwordx4 v[62:65], v[70:71], off offset:16
	global_load_dwordx4 v[66:69], v[70:71], off
	v_or_b32_e32 v72, v72, v74
	v_mov_b32_e32 v53, v1
	v_ashrrev_i32_e32 v73, 31, v72
	v_lshl_add_u64 v[52:53], v[114:115], 0, v[52:53]
	s_waitcnt vmcnt(1) lgkmcnt(0)
	v_pk_mul_f32 v[58:59], v[58:59], v[62:63]
	s_waitcnt vmcnt(0)
	v_pk_mul_f32 v[54:55], v[54:55], v[66:67]
	v_pk_mul_f32 v[56:57], v[56:57], v[68:69]
	v_pk_mul_f32 v[60:61], v[60:61], v[64:65]
	v_cvt_pk_bf16_f32 v54, v54, v55
	v_cvt_pk_bf16_f32 v55, v56, v57
	v_cvt_pk_bf16_f32 v56, v58, v59
	v_lshlrev_b64 v[58:59], 11, v[72:73]
	v_cvt_pk_bf16_f32 v57, v60, v61
	v_lshl_add_u64 v[58:59], v[52:53], 0, v[58:59]
	global_store_dwordx4 v[58:59], v[54:57], off
	ds_read_b128 v[54:57], v0 offset:2304
	ds_read_b128 v[58:61], v0 offset:2320
	global_load_dwordx4 v[62:65], v[70:71], off offset:16
	global_load_dwordx4 v[66:69], v[70:71], off
	s_waitcnt vmcnt(1) lgkmcnt(0)
	v_pk_mul_f32 v[58:59], v[58:59], v[62:63]
	s_waitcnt vmcnt(0)
	v_pk_mul_f32 v[54:55], v[54:55], v[66:67]
	v_pk_mul_f32 v[56:57], v[56:57], v[68:69]
	v_cvt_pk_bf16_f32 v54, v54, v55
	v_cvt_pk_bf16_f32 v55, v56, v57
	v_cvt_pk_bf16_f32 v56, v58, v59
	v_or_b32_e32 v58, 16, v72
	v_ashrrev_i32_e32 v59, 31, v58
	v_pk_mul_f32 v[60:61], v[60:61], v[64:65]
	v_lshlrev_b64 v[58:59], 11, v[58:59]
	v_cvt_pk_bf16_f32 v57, v60, v61
	v_lshl_add_u64 v[52:53], v[52:53], 0, v[58:59]
	global_store_dwordx4 v[52:53], v[54:57], off
	s_nop 1
	v_mov_b32_e32 v54, v179
	s_nop 0
	v_and_b32_e32 v0, 31, v54
	v_bfe_u32 v52, v54, 5, 1
	v_mul_u32_u24_e32 v52, 0x240, v52
	v_lshlrev_b32_e32 v0, 2, v0
	v_add3_u32 v0, v145, v52, v0
	ds_write2_b32 v0, v34, v35 offset1:36
	ds_write2_b32 v0, v36, v37 offset0:72 offset1:108
	v_add_u32_e32 v34, 0x400, v0
	ds_write2_b32 v34, v38, v39 offset0:32 offset1:68
	ds_write2_b32 v34, v40, v41 offset0:104 offset1:140
	v_add_u32_e32 v34, 0x800, v0
	v_add_u32_e32 v0, 0xc00, v0
	ds_write2_b32 v34, v42, v43 offset0:64 offset1:100
	ds_write2_b32 v34, v44, v45 offset0:136 offset1:172
	ds_write2_b32 v0, v46, v47 offset0:96 offset1:132
	ds_write2_b32 v0, v48, v49 offset0:168 offset1:204
	v_lshlrev_b32_e32 v0, 3, v54
	v_and_b32_e32 v36, 24, v0
	v_lshlrev_b32_e32 v0, 2, v36
	v_lshl_add_u64 v[34:35], v[50:51], 0, v[0:1]
	v_bfe_u32 v54, v54, 2, 4
	v_lshl_add_u64 v[52:53], v[34:35], 0, v[100:101]
	v_lshlrev_b32_e32 v34, 1, v36
	v_mul_u32_u24_e32 v36, 0x90, v54
	s_waitcnt lgkmcnt(0)
	v_add3_u32 v0, v145, v0, v36
	ds_read_b128 v[36:39], v0
	ds_read_b128 v[40:43], v0 offset:16
	global_load_dwordx4 v[44:47], v[52:53], off offset:16
	global_load_dwordx4 v[48:51], v[52:53], off
	v_or_b32_e32 v54, v54, v74
	v_mov_b32_e32 v35, v1
	v_ashrrev_i32_e32 v55, 31, v54
	v_lshl_add_u64 v[34:35], s[0:1], 0, v[34:35]
	s_waitcnt vmcnt(1) lgkmcnt(0)
	v_pk_mul_f32 v[40:41], v[40:41], v[44:45]
	s_waitcnt vmcnt(0)
	v_pk_mul_f32 v[36:37], v[36:37], v[48:49]
	v_pk_mul_f32 v[38:39], v[38:39], v[50:51]
	v_cvt_pk_bf16_f32 v36, v36, v37
	v_cvt_pk_bf16_f32 v37, v38, v39
	v_cvt_pk_bf16_f32 v38, v40, v41
	v_lshlrev_b64 v[40:41], 11, v[54:55]
	v_pk_mul_f32 v[42:43], v[42:43], v[46:47]
	v_lshl_add_u64 v[40:41], v[34:35], 0, v[40:41]
	v_cvt_pk_bf16_f32 v39, v42, v43
	v_lshl_add_u64 v[40:41], v[40:41], 0, v[98:99]
	global_store_dwordx4 v[40:41], v[36:39], off
	ds_read_b128 v[36:39], v0 offset:2304
	ds_read_b128 v[40:43], v0 offset:2320
	global_load_dwordx4 v[44:47], v[52:53], off offset:16
	global_load_dwordx4 v[48:51], v[52:53], off
	s_waitcnt vmcnt(1) lgkmcnt(0)
	v_pk_mul_f32 v[40:41], v[40:41], v[44:45]
	s_waitcnt vmcnt(0)
	v_pk_mul_f32 v[36:37], v[36:37], v[48:49]
	v_pk_mul_f32 v[38:39], v[38:39], v[50:51]
	v_cvt_pk_bf16_f32 v36, v36, v37
	v_cvt_pk_bf16_f32 v37, v38, v39
	v_cvt_pk_bf16_f32 v38, v40, v41
	v_or_b32_e32 v40, 16, v54
	v_ashrrev_i32_e32 v41, 31, v40
	v_lshlrev_b64 v[40:41], 11, v[40:41]
	v_pk_mul_f32 v[42:43], v[42:43], v[46:47]
	v_lshl_add_u64 v[34:35], v[34:35], 0, v[40:41]
	v_cvt_pk_bf16_f32 v39, v42, v43
	v_lshl_add_u64 v[34:35], v[34:35], 0, v[98:99]
	global_store_dwordx4 v[34:35], v[36:39], off
	v_or_b32_e32 v42, 0x60, v149
	v_mul_hi_i32 v0, v42, s2
	v_lshrrev_b32_e32 v34, 31, v0
	v_ashrrev_i32_e32 v0, 13, v0
	v_add_u32_e32 v0, v0, v34
	v_mul_i32_i24_e32 v34, 0x4100, v0
	v_sub_u32_e32 v34, v42, v34
	v_mul_i32_i24_e32 v0, 0xc00, v0
	v_cmp_lt_i32_e32 vcc, s3, v34
	v_mov_b32_e32 v36, v179
	s_nop 0
	v_cndmask_b32_e32 v34, v162, v0, vcc
	v_and_b32_e32 v0, 31, v36
	v_bfe_u32 v37, v36, 5, 1
	v_mul_u32_u24_e32 v37, 0x240, v37
	v_lshlrev_b32_e32 v0, 2, v0
	v_add3_u32 v0, v145, v37, v0
	ds_write2_b32 v0, v18, v19 offset1:36
	ds_write2_b32 v0, v20, v21 offset0:72 offset1:108
	v_add_u32_e32 v18, 0x400, v0
	v_ashrrev_i32_e32 v35, 31, v34
	ds_write2_b32 v18, v22, v23 offset0:32 offset1:68
	ds_write2_b32 v18, v24, v25 offset0:104 offset1:140
	v_add_u32_e32 v18, 0x800, v0
	v_add_u32_e32 v0, 0xc00, v0
	ds_write2_b32 v18, v26, v27 offset0:64 offset1:100
	ds_write2_b32 v18, v28, v29 offset0:136 offset1:172
	ds_write2_b32 v0, v30, v31 offset0:96 offset1:132
	ds_write2_b32 v0, v32, v33 offset0:168 offset1:204
	v_lshl_add_u64 v[18:19], v[34:35], 2, s[26:27]
	v_lshlrev_b32_e32 v0, 3, v36
	v_lshl_add_u64 v[18:19], v[18:19], 0, s[4:5]
	v_and_b32_e32 v22, 24, v0
	v_lshl_add_u64 v[20:21], v[18:19], 0, v[116:117]
	v_lshlrev_b32_e32 v0, 2, v22
	v_bfe_u32 v40, v36, 2, 4
	v_lshl_add_u64 v[38:39], v[20:21], 0, v[0:1]
	v_lshlrev_b32_e32 v20, 1, v22
	v_mul_u32_u24_e32 v22, 0x90, v40
	s_waitcnt lgkmcnt(0)
	v_add3_u32 v0, v145, v0, v22
	ds_read_b128 v[22:25], v0
	ds_read_b128 v[26:29], v0 offset:16
	global_load_dwordx4 v[30:33], v[38:39], off offset:16
	global_load_dwordx4 v[34:37], v[38:39], off
	v_or_b32_e32 v40, v40, v42
	v_mov_b32_e32 v21, v1
	v_ashrrev_i32_e32 v41, 31, v40
	v_lshl_add_u64 v[20:21], v[114:115], 0, v[20:21]
	s_waitcnt vmcnt(1) lgkmcnt(0)
	v_pk_mul_f32 v[26:27], v[26:27], v[30:31]
	s_waitcnt vmcnt(0)
	v_pk_mul_f32 v[22:23], v[22:23], v[34:35]
	v_pk_mul_f32 v[24:25], v[24:25], v[36:37]
	v_pk_mul_f32 v[28:29], v[28:29], v[32:33]
	v_cvt_pk_bf16_f32 v22, v22, v23
	v_cvt_pk_bf16_f32 v23, v24, v25
	v_cvt_pk_bf16_f32 v24, v26, v27
	v_lshlrev_b64 v[26:27], 11, v[40:41]
	v_cvt_pk_bf16_f32 v25, v28, v29
	v_lshl_add_u64 v[26:27], v[20:21], 0, v[26:27]
	global_store_dwordx4 v[26:27], v[22:25], off
	ds_read_b128 v[22:25], v0 offset:2304
	ds_read_b128 v[26:29], v0 offset:2320
	global_load_dwordx4 v[30:33], v[38:39], off offset:16
	global_load_dwordx4 v[34:37], v[38:39], off
	s_waitcnt vmcnt(1) lgkmcnt(0)
	v_pk_mul_f32 v[26:27], v[26:27], v[30:31]
	s_waitcnt vmcnt(0)
	v_pk_mul_f32 v[22:23], v[22:23], v[34:35]
	v_pk_mul_f32 v[24:25], v[24:25], v[36:37]
	v_cvt_pk_bf16_f32 v22, v22, v23
	v_cvt_pk_bf16_f32 v23, v24, v25
	v_cvt_pk_bf16_f32 v24, v26, v27
	v_or_b32_e32 v26, 16, v40
	v_ashrrev_i32_e32 v27, 31, v26
	v_pk_mul_f32 v[28:29], v[28:29], v[32:33]
	v_lshlrev_b64 v[26:27], 11, v[26:27]
	v_cvt_pk_bf16_f32 v25, v28, v29
	v_lshl_add_u64 v[20:21], v[20:21], 0, v[26:27]
	global_store_dwordx4 v[20:21], v[22:25], off
	s_nop 1
	v_mov_b32_e32 v22, v179
	s_nop 0
	v_and_b32_e32 v0, 31, v22
	v_bfe_u32 v20, v22, 5, 1
	v_mul_u32_u24_e32 v20, 0x240, v20
	v_lshlrev_b32_e32 v0, 2, v0
	v_add3_u32 v0, v145, v20, v0
	ds_write2_b32 v0, v2, v3 offset1:36
	ds_write2_b32 v0, v4, v5 offset0:72 offset1:108
	v_add_u32_e32 v2, 0x400, v0
	ds_write2_b32 v2, v6, v7 offset0:32 offset1:68
	ds_write2_b32 v2, v8, v9 offset0:104 offset1:140
	v_add_u32_e32 v2, 0x800, v0
	v_add_u32_e32 v0, 0xc00, v0
	ds_write2_b32 v2, v10, v11 offset0:64 offset1:100
	ds_write2_b32 v2, v12, v13 offset0:136 offset1:172
	ds_write2_b32 v0, v14, v15 offset0:96 offset1:132
	ds_write2_b32 v0, v16, v17 offset0:168 offset1:204
	v_lshlrev_b32_e32 v0, 3, v22
	v_and_b32_e32 v4, 24, v0
	v_lshlrev_b32_e32 v0, 2, v4
	v_lshl_add_u64 v[2:3], v[18:19], 0, v[0:1]
	v_bfe_u32 v22, v22, 2, 4
	v_lshl_add_u64 v[20:21], v[2:3], 0, v[100:101]
	v_lshlrev_b32_e32 v2, 1, v4
	v_mul_u32_u24_e32 v4, 0x90, v22
	s_waitcnt lgkmcnt(0)
	v_add3_u32 v0, v145, v0, v4
	ds_read_b128 v[4:7], v0
	ds_read_b128 v[8:11], v0 offset:16
	global_load_dwordx4 v[12:15], v[20:21], off offset:16
	global_load_dwordx4 v[16:19], v[20:21], off
	v_or_b32_e32 v22, v22, v42
	v_mov_b32_e32 v3, v1
	v_ashrrev_i32_e32 v23, 31, v22
	v_lshl_add_u64 v[2:3], s[0:1], 0, v[2:3]
	s_waitcnt vmcnt(1) lgkmcnt(0)
	v_pk_mul_f32 v[8:9], v[8:9], v[12:13]
	s_waitcnt vmcnt(0)
	v_pk_mul_f32 v[4:5], v[4:5], v[16:17]
	v_pk_mul_f32 v[6:7], v[6:7], v[18:19]
	v_cvt_pk_bf16_f32 v4, v4, v5
	v_cvt_pk_bf16_f32 v5, v6, v7
	v_cvt_pk_bf16_f32 v6, v8, v9
	v_lshlrev_b64 v[8:9], 11, v[22:23]
	v_pk_mul_f32 v[10:11], v[10:11], v[14:15]
	v_lshl_add_u64 v[8:9], v[2:3], 0, v[8:9]
	v_cvt_pk_bf16_f32 v7, v10, v11
	v_lshl_add_u64 v[8:9], v[8:9], 0, v[98:99]
	global_store_dwordx4 v[8:9], v[4:7], off
	ds_read_b128 v[4:7], v0 offset:2304
	ds_read_b128 v[8:11], v0 offset:2320
	global_load_dwordx4 v[12:15], v[20:21], off offset:16
	global_load_dwordx4 v[16:19], v[20:21], off
	s_waitcnt vmcnt(1) lgkmcnt(0)
	v_pk_mul_f32 v[8:9], v[8:9], v[12:13]
	s_waitcnt vmcnt(0)
	v_pk_mul_f32 v[4:5], v[4:5], v[16:17]
	v_pk_mul_f32 v[6:7], v[6:7], v[18:19]
	v_cvt_pk_bf16_f32 v4, v4, v5
	v_cvt_pk_bf16_f32 v5, v6, v7
	v_cvt_pk_bf16_f32 v6, v8, v9
	v_or_b32_e32 v8, 16, v22
	v_ashrrev_i32_e32 v9, 31, v8
	v_lshlrev_b64 v[8:9], 11, v[8:9]
	v_pk_mul_f32 v[10:11], v[10:11], v[14:15]
	v_lshl_add_u64 v[2:3], v[2:3], 0, v[8:9]
	v_cvt_pk_bf16_f32 v7, v10, v11
	v_lshl_add_u64 v[2:3], v[2:3], 0, v[98:99]
	global_store_dwordx4 v[2:3], v[4:7], off
	s_add_i32 s7, s7, s6
	s_cmpk_gt_i32 s7, 0x207
	s_cselect_b64 s[0:1], -1, 0
	s_branch .LBB0_907

.LBB0_1120:
	s_add_i32 s2, s13, s14
	s_cmpk_gt_i32 s2, 0x81f
	s_mov_b64 s[0:1], -1
	s_cbranch_scc1 .LBB0_1119
	s_ashr_i32 s0, s2, 31
	s_lshr_b32 s0, s0, 25
	s_add_i32 s0, s2, s0
	s_ashr_i32 s1, s0, 7
	s_lshl_b32 s1, s1, 3
	s_sub_i32 s3, 0x82, s1
	s_min_u32 s3, s3, 8
	v_cvt_f32_ubyte0_e32 v0, s3
	v_rcp_iflag_f32_e32 v0, v0
	s_sub_i32 s6, 0, s3
	s_and_b32 s0, s0, 0xffffff80
	s_sub_i32 s0, s2, s0
	v_mul_f32_e32 v0, 0x4f7ffffe, v0
	v_cvt_u32_f32_e32 v0, v0
	s_abs_i32 s4, s0
	s_ashr_i32 s2, s0, 31
	s_waitcnt vmcnt(63) expcnt(7) lgkmcnt(15)
	v_readfirstlane_b32 s7, v0
	s_mul_i32 s6, s6, s7
	s_mul_hi_u32 s6, s7, s6
	s_add_i32 s7, s7, s6
	s_mul_hi_u32 s6, s4, s7
	s_mul_i32 s7, s6, s3
	s_sub_i32 s4, s4, s7
	s_add_i32 s7, s6, 1
	s_sub_i32 s8, s4, s3
	s_cmp_ge_u32 s4, s3
	s_cselect_b32 s6, s7, s6
	s_cselect_b32 s4, s8, s4
	s_add_i32 s7, s6, 1
	s_cmp_ge_u32 s4, s3
	s_cselect_b32 s4, s7, s6
	s_xor_b32 s4, s4, s2
	s_sub_i32 s4, s4, s2
	s_mul_i32 s2, s4, s3
	s_sub_i32 s0, s0, s2
	s_add_i32 s0, s0, s1
	s_lshl_b32 s0, s0, 8
	s_lshl_b32 s6, s4, 8
	s_ashr_i32 s1, s0, 31
	s_ashr_i32 s7, s6, 31
	s_lshl_b64 s[2:3], s[0:1], 11
	s_lshl_b64 s[8:9], s[6:7], 11
	s_add_u32 s10, s64, s2
	v_mov_b32_e32 v0, v143
	s_addc_u32 s11, s65, s3
	s_barrier
	v_readlane_b32 s16, v251, 2
	v_lshl_add_u64 v[2:3], v[0:1], 1, s[10:11]
	v_add_u32_e32 v0, 32, v158
	v_readlane_b32 s30, v251, 16
	v_readfirstlane_b32 s1, v0
	s_mov_b32 m0, s1
	v_mov_b32_e32 v0, v159
	global_load_lds_dwordx4 v[2:3], off
	v_readlane_b32 s17, v251, 3
	v_lshl_add_u64 v[2:3], v[0:1], 1, s[10:11]
	v_add_u32_e32 v0, 32, v160
	v_readlane_b32 s31, v251, 17
	v_readfirstlane_b32 s1, v0
	s_mov_b32 m0, s1
	v_mov_b32_e32 v0, v161
	global_load_lds_dwordx4 v[2:3], off
	s_add_u32 s16, s30, s8
	v_lshl_add_u64 v[2:3], v[0:1], 1, s[10:11]
	v_add_u32_e32 v0, 32, v162
	s_addc_u32 s17, s31, s9
	v_readfirstlane_b32 s1, v0
	s_mov_b32 m0, s1
	v_mov_b32_e32 v0, v163
	global_load_lds_dwordx4 v[2:3], off
	v_readlane_b32 s7, v254, 3
	v_lshl_add_u64 v[2:3], v[0:1], 1, s[10:11]
	v_add_u32_e32 v0, 32, v164
	s_mov_b32 s5, 0
	v_readfirstlane_b32 s1, v0
	s_mov_b32 m0, s1
	v_mov_b32_e32 v0, v143
	global_load_lds_dwordx4 v[2:3], off
	v_readlane_b32 s18, v251, 4
	v_lshl_add_u64 v[2:3], v[0:1], 1, s[16:17]
	v_add_u32_e32 v0, s7, v158
	v_readlane_b32 s19, v251, 5
	v_readfirstlane_b32 s1, v0
	s_mov_b32 m0, s1
	v_mov_b32_e32 v0, v159
	global_load_lds_dwordx4 v[2:3], off
	v_readlane_b32 s20, v251, 6
	v_lshl_add_u64 v[2:3], v[0:1], 1, s[16:17]
	v_add_u32_e32 v0, s7, v160
	v_readlane_b32 s21, v251, 7
	v_readfirstlane_b32 s1, v0
	s_mov_b32 m0, s1
	v_mov_b32_e32 v0, v161
	global_load_lds_dwordx4 v[2:3], off
	v_readlane_b32 s22, v251, 8
	v_lshl_add_u64 v[2:3], v[0:1], 1, s[16:17]
	v_add_u32_e32 v0, s7, v162
	v_readlane_b32 s23, v251, 9
	v_readfirstlane_b32 s1, v0
	s_mov_b32 m0, s1
	v_mov_b32_e32 v0, v163
	global_load_lds_dwordx4 v[2:3], off
	v_readlane_b32 s24, v251, 10
	v_lshl_add_u64 v[2:3], v[0:1], 1, s[16:17]
	v_add_u32_e32 v0, s7, v164
	v_readlane_b32 s25, v251, 11
	v_readfirstlane_b32 s1, v0
	s_mov_b32 m0, s1
	v_readlane_b32 s1, v253, 25
	global_load_lds_dwordx4 v[2:3], off
	s_add_u32 s1, s1, s2
	v_readlane_b32 s2, v253, 26
	s_waitcnt vmcnt(0)
	s_addc_u32 s7, s2, s3
	v_readlane_b32 s2, v253, 45
	s_add_u32 s8, s2, s8
	v_readlane_b32 s2, v253, 46
	v_mov_b32_e32 v2, 0
	s_addc_u32 s9, s2, s9
	s_mov_b64 s[2:3], 0
	v_mov_b32_e32 v3, v2
	v_mov_b32_e32 v4, v2
	v_mov_b32_e32 v5, v2
	v_mov_b32_e32 v6, v2
	v_mov_b32_e32 v7, v2
	v_mov_b32_e32 v8, v2
	v_mov_b32_e32 v9, v2
	v_mov_b32_e32 v10, v2
	v_mov_b32_e32 v11, v2
	v_mov_b32_e32 v12, v2
	v_mov_b32_e32 v13, v2
	s_waitcnt vmcnt(0)
	v_mov_b32_e32 v14, v2
	v_mov_b32_e32 v15, v2
	v_mov_b32_e32 v16, v2
	v_mov_b32_e32 v17, v2
	v_mov_b32_e32 v18, v2
	v_mov_b32_e32 v19, v2
	v_mov_b32_e32 v20, v2
	v_mov_b32_e32 v21, v2
	v_mov_b32_e32 v22, v2
	v_mov_b32_e32 v23, v2
	v_mov_b32_e32 v24, v2
	v_mov_b32_e32 v25, v2
	v_mov_b32_e32 v26, v2
	v_mov_b32_e32 v27, v2
	v_mov_b32_e32 v28, v2
	v_mov_b32_e32 v29, v2
	v_mov_b32_e32 v30, v2
	v_mov_b32_e32 v31, v2
	v_mov_b32_e32 v32, v2
	v_mov_b32_e32 v33, v2
	v_mov_b32_e32 v34, v2
	v_mov_b32_e32 v35, v2
	v_mov_b32_e32 v36, v2
	v_mov_b32_e32 v37, v2
	v_mov_b32_e32 v38, v2
	v_mov_b32_e32 v39, v2
	v_mov_b32_e32 v40, v2
	v_mov_b32_e32 v41, v2
	v_mov_b32_e32 v42, v2
	v_mov_b32_e32 v43, v2
	v_mov_b32_e32 v44, v2
	v_mov_b32_e32 v45, v2
	v_mov_b32_e32 v46, v2
	v_mov_b32_e32 v47, v2
	v_mov_b32_e32 v48, v2
	v_mov_b32_e32 v49, v2
	v_mov_b32_e32 v50, v2
	v_mov_b32_e32 v51, v2
	v_mov_b32_e32 v52, v2
	v_mov_b32_e32 v53, v2
	v_mov_b32_e32 v54, v2
	v_mov_b32_e32 v55, v2
	v_mov_b32_e32 v56, v2
	v_mov_b32_e32 v57, v2
	v_mov_b32_e32 v58, v2
	v_mov_b32_e32 v59, v2
	v_mov_b32_e32 v60, v2
	v_mov_b32_e32 v61, v2
	v_mov_b32_e32 v62, v2
	v_mov_b32_e32 v63, v2
	v_mov_b32_e32 v64, v2
	v_mov_b32_e32 v65, v2
	v_mov_b32_e32 v66, v2
	v_mov_b32_e32 v67, v2
	v_mov_b32_e32 v68, v2
	v_mov_b32_e32 v69, v2
	v_mov_b32_e32 v70, v2
	v_mov_b32_e32 v71, v2
	v_mov_b32_e32 v72, v2
	v_mov_b32_e32 v73, v2
	v_mov_b32_e32 v74, v2
	v_mov_b32_e32 v75, v2
	v_mov_b32_e32 v76, v2
	v_mov_b32_e32 v77, v2
	v_mov_b32_e32 v78, v2
	v_mov_b32_e32 v79, v2
	v_mov_b32_e32 v80, v2
	v_mov_b32_e32 v81, v2
	v_mov_b32_e32 v82, v2
	v_mov_b32_e32 v83, v2
	v_mov_b32_e32 v84, v2
	v_mov_b32_e32 v85, v2
	v_mov_b32_e32 v86, v2
	v_mov_b32_e32 v87, v2
	v_mov_b32_e32 v88, v2
	v_mov_b32_e32 v89, v2
	v_mov_b32_e32 v90, v2
	v_mov_b32_e32 v91, v2
	v_mov_b32_e32 v92, v2
	v_mov_b32_e32 v93, v2
	v_mov_b32_e32 v94, v2
	v_mov_b32_e32 v95, v2
	v_mov_b32_e32 v96, v2
	v_mov_b32_e32 v97, v2
	v_mov_b32_e32 v98, v2
	v_mov_b32_e32 v99, v2
	v_mov_b32_e32 v100, v2
	v_mov_b32_e32 v101, v2
	v_mov_b32_e32 v102, v2
	v_mov_b32_e32 v103, v2
	v_mov_b32_e32 v104, v2
	v_mov_b32_e32 v105, v2
	v_mov_b32_e32 v106, v2
	v_mov_b32_e32 v107, v2
	v_mov_b32_e32 v108, v2
	v_mov_b32_e32 v109, v2
	v_mov_b32_e32 v110, v2
	v_mov_b32_e32 v111, v2
	v_mov_b32_e32 v112, v2
	v_mov_b32_e32 v113, v2
	v_mov_b32_e32 v114, v2
	v_mov_b32_e32 v115, v2
	v_mov_b32_e32 v116, v2
	v_mov_b32_e32 v117, v2
	v_mov_b32_e32 v118, v2
	v_mov_b32_e32 v119, v2
	v_mov_b32_e32 v120, v2
	v_mov_b32_e32 v121, v2
	v_mov_b32_e32 v122, v2
	v_mov_b32_e32 v123, v2
	v_mov_b32_e32 v124, v2
	v_mov_b32_e32 v125, v2
	v_mov_b32_e32 v126, v2
	v_mov_b32_e32 v127, v2
	v_mov_b32_e32 v128, v2
	v_mov_b32_e32 v129, v2
	v_readlane_b32 s26, v251, 12
	v_readlane_b32 s27, v251, 13
	v_readlane_b32 s28, v251, 14
	v_readlane_b32 s29, v251, 15
	s_waitcnt lgkmcnt(0)
	s_barrier
	v_lshlrev_b32_e32 v142, 1, v143
	v_readfirstlane_b32 s15, v158
	v_add_u32_e32 v156, v165, v167
	v_add_u32_e32 v195, v166, v167
	v_add_u32_e32 v157, v165, v172
	v_add_u32_e32 v200, v166, v172
	v_add_u32_e32 v193, v165, v173
	v_add_u32_e32 v201, v166, v173
	v_add_u32_e32 v194, v165, v174
	v_add_u32_e32 v202, v166, v174
	s_mov_b32 s5, 7
	v_readfirstlane_b32 s66, v179
	s_cmp_ge_u32 s66, 0x100
	s_cbranch_scc0 .Lg1122_np
	s_setprio 1
.Lg1122_np:
	s_add_u32 m0, s15, 0x8020
	s_add_u32 s10, s1, s2
	s_addc_u32 s11, s7, s3
	global_load_lds_dwordx4 v142, s[10:11]
	s_add_u32 m0, s15, 0xa020
	s_add_u32 s10, s10, 0x20000
	s_addc_u32 s11, s11, 0
	global_load_lds_dwordx4 v142, s[10:11]
	s_add_u32 m0, s15, 0xc020
	s_add_u32 s10, s10, 0x20000
	s_addc_u32 s11, s11, 0
	global_load_lds_dwordx4 v142, s[10:11]
	s_add_u32 m0, s15, 0xe020
	s_add_u32 s10, s10, 0x20000
	s_addc_u32 s11, s11, 0
	global_load_lds_dwordx4 v142, s[10:11]
	s_add_u32 m0, s15, 0x18020
	s_add_u32 s10, s8, s2
	s_addc_u32 s11, s9, s3
	global_load_lds_dwordx4 v142, s[10:11]
	ds_read_b128 v[130:133], v156 offset:0
	ds_read_b128 v[148:151], v195 offset:0
	ds_read_b128 v[152:155], v195 offset:4096
	ds_read_b128 v[134:137], v156 offset:4096
	ds_read_b128 v[138:141], v156 offset:8192
	ds_read_b128 v[144:147], v156 offset:12288
.Lg1122_loop:
	s_waitcnt lgkmcnt(4)
	v_mfma_f32_32x32x16_bf16 v[114:129], v[130:133], v[148:151], v[114:129]
	ds_read_b128 v[180:183], v157 offset:0
	s_waitcnt lgkmcnt(4)
	v_mfma_f32_32x32x16_bf16 v[98:113], v[130:133], v[152:155], v[98:113]
	ds_read_b128 v[226:229], v200 offset:0
	s_add_u32 m0, s15, 0x1a020
	s_add_u32 s10, s10, 0x20000
	s_addc_u32 s11, s11, 0
	global_load_lds_dwordx4 v142, s[10:11]
	s_waitcnt lgkmcnt(4)
	v_mfma_f32_32x32x16_bf16 v[82:97], v[134:137], v[148:151], v[82:97]
	ds_read_b128 v[230:233], v200 offset:4096
	v_mfma_f32_32x32x16_bf16 v[66:81], v[134:137], v[152:155], v[66:81]
	ds_read_b128 v[184:187], v157 offset:4096
	s_add_u32 m0, s15, 0x1c020
	s_add_u32 s10, s10, 0x20000
	s_addc_u32 s11, s11, 0
	global_load_lds_dwordx4 v142, s[10:11]
	s_waitcnt lgkmcnt(5)
	v_mfma_f32_32x32x16_bf16 v[50:65], v[138:141], v[148:151], v[50:65]
	ds_read_b128 v[188:191], v157 offset:8192
	v_mfma_f32_32x32x16_bf16 v[34:49], v[138:141], v[152:155], v[34:49]
	ds_read_b128 v[222:225], v157 offset:12288
	s_add_u32 m0, s15, 0x1e020
	s_add_u32 s10, s10, 0x20000
	s_addc_u32 s11, s11, 0
	global_load_lds_dwordx4 v142, s[10:11]
	s_add_u32 s2, s2, 0x80
	s_addc_u32 s3, s3, 0
	s_waitcnt lgkmcnt(6)
	v_mfma_f32_32x32x16_bf16 v[18:33], v[144:147], v[148:151], v[18:33]
	v_mfma_f32_32x32x16_bf16 v[2:17], v[144:147], v[152:155], v[2:17]
	s_waitcnt lgkmcnt(4)
	v_mfma_f32_32x32x16_bf16 v[114:129], v[180:183], v[226:229], v[114:129]
	ds_read_b128 v[130:133], v193 offset:0
	s_waitcnt lgkmcnt(4)
	v_mfma_f32_32x32x16_bf16 v[98:113], v[180:183], v[230:233], v[98:113]
	ds_read_b128 v[148:151], v201 offset:0
	s_waitcnt lgkmcnt(4)
	v_mfma_f32_32x32x16_bf16 v[82:97], v[184:187], v[226:229], v[82:97]
	ds_read_b128 v[152:155], v201 offset:4096
	v_mfma_f32_32x32x16_bf16 v[66:81], v[184:187], v[230:233], v[66:81]
	ds_read_b128 v[134:137], v193 offset:4096
	s_waitcnt lgkmcnt(5)
	v_mfma_f32_32x32x16_bf16 v[50:65], v[188:191], v[226:229], v[50:65]
	ds_read_b128 v[138:141], v193 offset:8192
	v_mfma_f32_32x32x16_bf16 v[34:49], v[188:191], v[230:233], v[34:49]
	ds_read_b128 v[144:147], v193 offset:12288
	s_waitcnt lgkmcnt(6)
	v_mfma_f32_32x32x16_bf16 v[18:33], v[222:225], v[226:229], v[18:33]
	v_mfma_f32_32x32x16_bf16 v[2:17], v[222:225], v[230:233], v[2:17]
	s_waitcnt lgkmcnt(4)
	v_mfma_f32_32x32x16_bf16 v[114:129], v[130:133], v[148:151], v[114:129]
	ds_read_b128 v[180:183], v194 offset:0
	ds_read_b128 v[226:229], v202 offset:0
	s_waitcnt lgkmcnt(5)
	v_mfma_f32_32x32x16_bf16 v[98:113], v[130:133], v[152:155], v[98:113]
	ds_read_b128 v[230:233], v202 offset:4096
	ds_read_b128 v[184:187], v194 offset:4096
	s_waitcnt lgkmcnt(6)
	v_mfma_f32_32x32x16_bf16 v[82:97], v[134:137], v[148:151], v[82:97]
	ds_read_b128 v[188:191], v194 offset:8192
	ds_read_b128 v[222:225], v194 offset:12288
	v_mfma_f32_32x32x16_bf16 v[66:81], v[134:137], v[152:155], v[66:81]
	s_waitcnt lgkmcnt(7)
	v_mfma_f32_32x32x16_bf16 v[50:65], v[138:141], v[148:151], v[50:65]
	v_mfma_f32_32x32x16_bf16 v[34:49], v[138:141], v[152:155], v[34:49]
	s_waitcnt lgkmcnt(6)
	v_mfma_f32_32x32x16_bf16 v[18:33], v[144:147], v[148:151], v[18:33]
	v_mfma_f32_32x32x16_bf16 v[2:17], v[144:147], v[152:155], v[2:17]
	s_waitcnt vmcnt(0) lgkmcnt(0)
	s_barrier
	v_mfma_f32_32x32x16_bf16 v[114:129], v[180:183], v[226:229], v[114:129]
	ds_read_b128 v[130:133], v156 offset:32768
	s_add_u32 m0, s15, 0x20
	s_add_u32 s10, s1, s2
	s_addc_u32 s11, s7, s3
	global_load_lds_dwordx4 v142, s[10:11]
	v_mfma_f32_32x32x16_bf16 v[98:113], v[180:183], v[230:233], v[98:113]
	ds_read_b128 v[148:151], v195 offset:32768
	s_add_u32 m0, s15, 0x2020
	s_add_u32 s10, s10, 0x20000
	s_addc_u32 s11, s11, 0
	global_load_lds_dwordx4 v142, s[10:11]
	v_mfma_f32_32x32x16_bf16 v[82:97], v[184:187], v[226:229], v[82:97]
	ds_read_b128 v[152:155], v195 offset:36864
	s_add_u32 m0, s15, 0x4020
	s_add_u32 s10, s10, 0x20000
	s_addc_u32 s11, s11, 0
	global_load_lds_dwordx4 v142, s[10:11]
	v_mfma_f32_32x32x16_bf16 v[66:81], v[184:187], v[230:233], v[66:81]
	ds_read_b128 v[134:137], v156 offset:36864
	s_add_u32 m0, s15, 0x6020
	s_add_u32 s10, s10, 0x20000
	s_addc_u32 s11, s11, 0
	global_load_lds_dwordx4 v142, s[10:11]
	v_mfma_f32_32x32x16_bf16 v[50:65], v[188:191], v[226:229], v[50:65]
	ds_read_b128 v[138:141], v156 offset:40960
	s_add_u32 m0, s15, 0x10020
	s_add_u32 s10, s8, s2
	s_addc_u32 s11, s9, s3
	global_load_lds_dwordx4 v142, s[10:11]
	v_mfma_f32_32x32x16_bf16 v[34:49], v[188:191], v[230:233], v[34:49]
	ds_read_b128 v[144:147], v156 offset:45056
	v_mfma_f32_32x32x16_bf16 v[18:33], v[222:225], v[226:229], v[18:33]
	v_mfma_f32_32x32x16_bf16 v[2:17], v[222:225], v[230:233], v[2:17]
	s_waitcnt lgkmcnt(4)
	v_mfma_f32_32x32x16_bf16 v[114:129], v[130:133], v[148:151], v[114:129]
	ds_read_b128 v[180:183], v157 offset:32768
	s_waitcnt lgkmcnt(4)
	v_mfma_f32_32x32x16_bf16 v[98:113], v[130:133], v[152:155], v[98:113]
	ds_read_b128 v[226:229], v200 offset:32768
	s_add_u32 m0, s15, 0x12020
	s_add_u32 s10, s10, 0x20000
	s_addc_u32 s11, s11, 0
	global_load_lds_dwordx4 v142, s[10:11]
	s_waitcnt lgkmcnt(4)
	v_mfma_f32_32x32x16_bf16 v[82:97], v[134:137], v[148:151], v[82:97]
	ds_read_b128 v[230:233], v200 offset:36864
	v_mfma_f32_32x32x16_bf16 v[66:81], v[134:137], v[152:155], v[66:81]
	ds_read_b128 v[184:187], v157 offset:36864
	s_add_u32 m0, s15, 0x14020
	s_add_u32 s10, s10, 0x20000
	s_addc_u32 s11, s11, 0
	global_load_lds_dwordx4 v142, s[10:11]
	s_waitcnt lgkmcnt(5)
	v_mfma_f32_32x32x16_bf16 v[50:65], v[138:141], v[148:151], v[50:65]
	ds_read_b128 v[188:191], v157 offset:40960
	v_mfma_f32_32x32x16_bf16 v[34:49], v[138:141], v[152:155], v[34:49]
	ds_read_b128 v[222:225], v157 offset:45056
	s_add_u32 m0, s15, 0x16020
	s_add_u32 s10, s10, 0x20000
	s_addc_u32 s11, s11, 0
	global_load_lds_dwordx4 v142, s[10:11]
	s_add_u32 s2, s2, 0x80
	s_addc_u32 s3, s3, 0
	s_waitcnt lgkmcnt(6)
	v_mfma_f32_32x32x16_bf16 v[18:33], v[144:147], v[148:151], v[18:33]
	v_mfma_f32_32x32x16_bf16 v[2:17], v[144:147], v[152:155], v[2:17]
	s_waitcnt lgkmcnt(4)
	v_mfma_f32_32x32x16_bf16 v[114:129], v[180:183], v[226:229], v[114:129]
	ds_read_b128 v[130:133], v193 offset:32768
	s_waitcnt lgkmcnt(4)
	v_mfma_f32_32x32x16_bf16 v[98:113], v[180:183], v[230:233], v[98:113]
	ds_read_b128 v[148:151], v201 offset:32768
	s_waitcnt lgkmcnt(4)
	v_mfma_f32_32x32x16_bf16 v[82:97], v[184:187], v[226:229], v[82:97]
	ds_read_b128 v[152:155], v201 offset:36864
	v_mfma_f32_32x32x16_bf16 v[66:81], v[184:187], v[230:233], v[66:81]
	ds_read_b128 v[134:137], v193 offset:36864
	s_waitcnt lgkmcnt(5)
	v_mfma_f32_32x32x16_bf16 v[50:65], v[188:191], v[226:229], v[50:65]
	ds_read_b128 v[138:141], v193 offset:40960
	v_mfma_f32_32x32x16_bf16 v[34:49], v[188:191], v[230:233], v[34:49]
	ds_read_b128 v[144:147], v193 offset:45056
	s_waitcnt lgkmcnt(6)
	v_mfma_f32_32x32x16_bf16 v[18:33], v[222:225], v[226:229], v[18:33]
	v_mfma_f32_32x32x16_bf16 v[2:17], v[222:225], v[230:233], v[2:17]
	s_waitcnt lgkmcnt(4)
	v_mfma_f32_32x32x16_bf16 v[114:129], v[130:133], v[148:151], v[114:129]
	ds_read_b128 v[180:183], v194 offset:32768
	ds_read_b128 v[226:229], v202 offset:32768
	s_waitcnt lgkmcnt(5)
	v_mfma_f32_32x32x16_bf16 v[98:113], v[130:133], v[152:155], v[98:113]
	ds_read_b128 v[230:233], v202 offset:36864
	ds_read_b128 v[184:187], v194 offset:36864
	s_waitcnt lgkmcnt(6)
	v_mfma_f32_32x32x16_bf16 v[82:97], v[134:137], v[148:151], v[82:97]
	ds_read_b128 v[188:191], v194 offset:40960
	ds_read_b128 v[222:225], v194 offset:45056
	v_mfma_f32_32x32x16_bf16 v[66:81], v[134:137], v[152:155], v[66:81]
	s_waitcnt lgkmcnt(7)
	v_mfma_f32_32x32x16_bf16 v[50:65], v[138:141], v[148:151], v[50:65]
	v_mfma_f32_32x32x16_bf16 v[34:49], v[138:141], v[152:155], v[34:49]
	s_waitcnt lgkmcnt(6)
	v_mfma_f32_32x32x16_bf16 v[18:33], v[144:147], v[148:151], v[18:33]
	v_mfma_f32_32x32x16_bf16 v[2:17], v[144:147], v[152:155], v[2:17]
	s_waitcnt vmcnt(0) lgkmcnt(0)
	s_barrier
	v_mfma_f32_32x32x16_bf16 v[114:129], v[180:183], v[226:229], v[114:129]
	ds_read_b128 v[130:133], v156 offset:0
	s_add_u32 m0, s15, 0x8020
	s_add_u32 s10, s1, s2
	s_addc_u32 s11, s7, s3
	global_load_lds_dwordx4 v142, s[10:11]
	v_mfma_f32_32x32x16_bf16 v[98:113], v[180:183], v[230:233], v[98:113]
	ds_read_b128 v[148:151], v195 offset:0
	s_add_u32 m0, s15, 0xa020
	s_add_u32 s10, s10, 0x20000
	s_addc_u32 s11, s11, 0
	global_load_lds_dwordx4 v142, s[10:11]
	v_mfma_f32_32x32x16_bf16 v[82:97], v[184:187], v[226:229], v[82:97]
	ds_read_b128 v[152:155], v195 offset:4096
	s_add_u32 m0, s15, 0xc020
	s_add_u32 s10, s10, 0x20000
	s_addc_u32 s11, s11, 0
	global_load_lds_dwordx4 v142, s[10:11]
	v_mfma_f32_32x32x16_bf16 v[66:81], v[184:187], v[230:233], v[66:81]
	ds_read_b128 v[134:137], v156 offset:4096
	s_add_u32 m0, s15, 0xe020
	s_add_u32 s10, s10, 0x20000
	s_addc_u32 s11, s11, 0
	global_load_lds_dwordx4 v142, s[10:11]
	v_mfma_f32_32x32x16_bf16 v[50:65], v[188:191], v[226:229], v[50:65]
	ds_read_b128 v[138:141], v156 offset:8192
	s_add_u32 m0, s15, 0x18020
	s_add_u32 s10, s8, s2
	s_addc_u32 s11, s9, s3
	global_load_lds_dwordx4 v142, s[10:11]
	v_mfma_f32_32x32x16_bf16 v[34:49], v[188:191], v[230:233], v[34:49]
	ds_read_b128 v[144:147], v156 offset:12288
	v_mfma_f32_32x32x16_bf16 v[18:33], v[222:225], v[226:229], v[18:33]
	v_mfma_f32_32x32x16_bf16 v[2:17], v[222:225], v[230:233], v[2:17]
	s_sub_u32 s5, s5, 1
	s_cmp_lg_u32 s5, 0
	s_cbranch_scc1 .Lg1122_loop
	s_waitcnt lgkmcnt(4)
	v_mfma_f32_32x32x16_bf16 v[114:129], v[130:133], v[148:151], v[114:129]
	ds_read_b128 v[180:183], v157 offset:0
	s_waitcnt lgkmcnt(4)
	v_mfma_f32_32x32x16_bf16 v[98:113], v[130:133], v[152:155], v[98:113]
	ds_read_b128 v[226:229], v200 offset:0
	s_add_u32 m0, s15, 0x1a020
	s_add_u32 s10, s10, 0x20000
	s_addc_u32 s11, s11, 0
	global_load_lds_dwordx4 v142, s[10:11]
	s_waitcnt lgkmcnt(4)
	v_mfma_f32_32x32x16_bf16 v[82:97], v[134:137], v[148:151], v[82:97]
	ds_read_b128 v[230:233], v200 offset:4096
	v_mfma_f32_32x32x16_bf16 v[66:81], v[134:137], v[152:155], v[66:81]
	ds_read_b128 v[184:187], v157 offset:4096
	s_add_u32 m0, s15, 0x1c020
	s_add_u32 s10, s10, 0x20000
	s_addc_u32 s11, s11, 0
	global_load_lds_dwordx4 v142, s[10:11]
	s_waitcnt lgkmcnt(5)
	v_mfma_f32_32x32x16_bf16 v[50:65], v[138:141], v[148:151], v[50:65]
	ds_read_b128 v[188:191], v157 offset:8192
	v_mfma_f32_32x32x16_bf16 v[34:49], v[138:141], v[152:155], v[34:49]
	ds_read_b128 v[222:225], v157 offset:12288
	s_add_u32 m0, s15, 0x1e020
	s_add_u32 s10, s10, 0x20000
	s_addc_u32 s11, s11, 0
	global_load_lds_dwordx4 v142, s[10:11]
	s_add_u32 s2, s2, 0x80
	s_addc_u32 s3, s3, 0
	s_waitcnt lgkmcnt(6)
	v_mfma_f32_32x32x16_bf16 v[18:33], v[144:147], v[148:151], v[18:33]
	v_mfma_f32_32x32x16_bf16 v[2:17], v[144:147], v[152:155], v[2:17]
	s_waitcnt lgkmcnt(4)
	v_mfma_f32_32x32x16_bf16 v[114:129], v[180:183], v[226:229], v[114:129]
	ds_read_b128 v[130:133], v193 offset:0
	s_waitcnt lgkmcnt(4)
	v_mfma_f32_32x32x16_bf16 v[98:113], v[180:183], v[230:233], v[98:113]
	ds_read_b128 v[148:151], v201 offset:0
	s_waitcnt lgkmcnt(4)
	v_mfma_f32_32x32x16_bf16 v[82:97], v[184:187], v[226:229], v[82:97]
	ds_read_b128 v[152:155], v201 offset:4096
	v_mfma_f32_32x32x16_bf16 v[66:81], v[184:187], v[230:233], v[66:81]
	ds_read_b128 v[134:137], v193 offset:4096
	s_waitcnt lgkmcnt(5)
	v_mfma_f32_32x32x16_bf16 v[50:65], v[188:191], v[226:229], v[50:65]
	ds_read_b128 v[138:141], v193 offset:8192
	v_mfma_f32_32x32x16_bf16 v[34:49], v[188:191], v[230:233], v[34:49]
	ds_read_b128 v[144:147], v193 offset:12288
	s_waitcnt lgkmcnt(6)
	v_mfma_f32_32x32x16_bf16 v[18:33], v[222:225], v[226:229], v[18:33]
	v_mfma_f32_32x32x16_bf16 v[2:17], v[222:225], v[230:233], v[2:17]
	s_waitcnt lgkmcnt(4)
	v_mfma_f32_32x32x16_bf16 v[114:129], v[130:133], v[148:151], v[114:129]
	ds_read_b128 v[180:183], v194 offset:0
	ds_read_b128 v[226:229], v202 offset:0
	s_waitcnt lgkmcnt(5)
	v_mfma_f32_32x32x16_bf16 v[98:113], v[130:133], v[152:155], v[98:113]
	ds_read_b128 v[230:233], v202 offset:4096
	ds_read_b128 v[184:187], v194 offset:4096
	s_waitcnt lgkmcnt(6)
	v_mfma_f32_32x32x16_bf16 v[82:97], v[134:137], v[148:151], v[82:97]
	ds_read_b128 v[188:191], v194 offset:8192
	ds_read_b128 v[222:225], v194 offset:12288
	v_mfma_f32_32x32x16_bf16 v[66:81], v[134:137], v[152:155], v[66:81]
	s_waitcnt lgkmcnt(7)
	v_mfma_f32_32x32x16_bf16 v[50:65], v[138:141], v[148:151], v[50:65]
	v_mfma_f32_32x32x16_bf16 v[34:49], v[138:141], v[152:155], v[34:49]
	s_waitcnt lgkmcnt(6)
	v_mfma_f32_32x32x16_bf16 v[18:33], v[144:147], v[148:151], v[18:33]
	v_mfma_f32_32x32x16_bf16 v[2:17], v[144:147], v[152:155], v[2:17]
	s_waitcnt vmcnt(0) lgkmcnt(0)
	s_barrier
	v_mfma_f32_32x32x16_bf16 v[114:129], v[180:183], v[226:229], v[114:129]
	ds_read_b128 v[130:133], v156 offset:32768
	v_mfma_f32_32x32x16_bf16 v[98:113], v[180:183], v[230:233], v[98:113]
	ds_read_b128 v[148:151], v195 offset:32768
	v_mfma_f32_32x32x16_bf16 v[82:97], v[184:187], v[226:229], v[82:97]
	ds_read_b128 v[152:155], v195 offset:36864
	v_mfma_f32_32x32x16_bf16 v[66:81], v[184:187], v[230:233], v[66:81]
	ds_read_b128 v[134:137], v156 offset:36864
	v_mfma_f32_32x32x16_bf16 v[50:65], v[188:191], v[226:229], v[50:65]
	ds_read_b128 v[138:141], v156 offset:40960
	v_mfma_f32_32x32x16_bf16 v[34:49], v[188:191], v[230:233], v[34:49]
	ds_read_b128 v[144:147], v156 offset:45056
	v_mfma_f32_32x32x16_bf16 v[18:33], v[222:225], v[226:229], v[18:33]
	v_mfma_f32_32x32x16_bf16 v[2:17], v[222:225], v[230:233], v[2:17]
	s_waitcnt lgkmcnt(4)
	v_mfma_f32_32x32x16_bf16 v[114:129], v[130:133], v[148:151], v[114:129]
	ds_read_b128 v[180:183], v157 offset:32768
	s_waitcnt lgkmcnt(4)
	v_mfma_f32_32x32x16_bf16 v[98:113], v[130:133], v[152:155], v[98:113]
	ds_read_b128 v[226:229], v200 offset:32768
	s_waitcnt lgkmcnt(4)
	v_mfma_f32_32x32x16_bf16 v[82:97], v[134:137], v[148:151], v[82:97]
	ds_read_b128 v[230:233], v200 offset:36864
	v_mfma_f32_32x32x16_bf16 v[66:81], v[134:137], v[152:155], v[66:81]
	ds_read_b128 v[184:187], v157 offset:36864
	s_waitcnt lgkmcnt(5)
	v_mfma_f32_32x32x16_bf16 v[50:65], v[138:141], v[148:151], v[50:65]
	ds_read_b128 v[188:191], v157 offset:40960
	v_mfma_f32_32x32x16_bf16 v[34:49], v[138:141], v[152:155], v[34:49]
	ds_read_b128 v[222:225], v157 offset:45056
	s_waitcnt lgkmcnt(6)
	v_mfma_f32_32x32x16_bf16 v[18:33], v[144:147], v[148:151], v[18:33]
	v_mfma_f32_32x32x16_bf16 v[2:17], v[144:147], v[152:155], v[2:17]
	s_waitcnt lgkmcnt(4)
	v_mfma_f32_32x32x16_bf16 v[114:129], v[180:183], v[226:229], v[114:129]
	ds_read_b128 v[130:133], v193 offset:32768
	s_waitcnt lgkmcnt(4)
	v_mfma_f32_32x32x16_bf16 v[98:113], v[180:183], v[230:233], v[98:113]
	ds_read_b128 v[148:151], v201 offset:32768
	s_waitcnt lgkmcnt(4)
	v_mfma_f32_32x32x16_bf16 v[82:97], v[184:187], v[226:229], v[82:97]
	ds_read_b128 v[152:155], v201 offset:36864
	v_mfma_f32_32x32x16_bf16 v[66:81], v[184:187], v[230:233], v[66:81]
	ds_read_b128 v[134:137], v193 offset:36864
	s_waitcnt lgkmcnt(5)
	v_mfma_f32_32x32x16_bf16 v[50:65], v[188:191], v[226:229], v[50:65]
	ds_read_b128 v[138:141], v193 offset:40960
	v_mfma_f32_32x32x16_bf16 v[34:49], v[188:191], v[230:233], v[34:49]
	ds_read_b128 v[144:147], v193 offset:45056
	s_waitcnt lgkmcnt(6)
	v_mfma_f32_32x32x16_bf16 v[18:33], v[222:225], v[226:229], v[18:33]
	v_mfma_f32_32x32x16_bf16 v[2:17], v[222:225], v[230:233], v[2:17]
	s_waitcnt lgkmcnt(4)
	v_mfma_f32_32x32x16_bf16 v[114:129], v[130:133], v[148:151], v[114:129]
	ds_read_b128 v[180:183], v194 offset:32768
	ds_read_b128 v[226:229], v202 offset:32768
	s_waitcnt lgkmcnt(5)
	v_mfma_f32_32x32x16_bf16 v[98:113], v[130:133], v[152:155], v[98:113]
	ds_read_b128 v[230:233], v202 offset:36864
	ds_read_b128 v[184:187], v194 offset:36864
	s_waitcnt lgkmcnt(6)
	v_mfma_f32_32x32x16_bf16 v[82:97], v[134:137], v[148:151], v[82:97]
	ds_read_b128 v[188:191], v194 offset:40960
	ds_read_b128 v[222:225], v194 offset:45056
	v_mfma_f32_32x32x16_bf16 v[66:81], v[134:137], v[152:155], v[66:81]
	s_waitcnt lgkmcnt(7)
	v_mfma_f32_32x32x16_bf16 v[50:65], v[138:141], v[148:151], v[50:65]
	v_mfma_f32_32x32x16_bf16 v[34:49], v[138:141], v[152:155], v[34:49]
	s_waitcnt lgkmcnt(6)
	v_mfma_f32_32x32x16_bf16 v[18:33], v[144:147], v[148:151], v[18:33]
	v_mfma_f32_32x32x16_bf16 v[2:17], v[144:147], v[152:155], v[2:17]
	s_waitcnt vmcnt(0) lgkmcnt(0)
	s_barrier
	v_mfma_f32_32x32x16_bf16 v[114:129], v[180:183], v[226:229], v[114:129]
	v_mfma_f32_32x32x16_bf16 v[98:113], v[180:183], v[230:233], v[98:113]
	v_mfma_f32_32x32x16_bf16 v[82:97], v[184:187], v[226:229], v[82:97]
	v_mfma_f32_32x32x16_bf16 v[66:81], v[184:187], v[230:233], v[66:81]
	v_mfma_f32_32x32x16_bf16 v[50:65], v[188:191], v[226:229], v[50:65]
	v_mfma_f32_32x32x16_bf16 v[34:49], v[188:191], v[230:233], v[34:49]
	v_mfma_f32_32x32x16_bf16 v[18:33], v[222:225], v[226:229], v[18:33]
	v_mfma_f32_32x32x16_bf16 v[2:17], v[222:225], v[230:233], v[2:17]
	s_setprio 0
	v_add_u32_e32 v180, s0, v168
	s_and_b32 s0, s4, 0x7ffffe
	s_mov_b32 s4, 0x7e07e07f
	v_mul_hi_i32 v0, v180, s4
	v_lshrrev_b32_e32 v130, 31, v0
	v_ashrrev_i32_e32 v0, 13, v0
	s_cmp_eq_u32 s0, 12
	v_add_u32_e32 v182, v0, v130
	s_waitcnt vmcnt(0)
	s_cselect_b64 s[2:3], -1, 0
	s_cmp_lg_u32 s0, 12
	v_mul_i32_i24_e32 v0, 0x4100, v182
	v_or_b32_e32 v138, s6, v169
	s_movk_i32 s4, 0x5ff
	s_cselect_b64 s[0:1], -1, 0
	v_sub_u32_e32 v140, v180, v0
	v_mov_b32_e32 v184, v179
	v_cmp_lt_i32_e64 s[52:53], s4, v138
	s_barrier
	v_lshl_or_b32 v181, v182, 3, v171
	v_ashrrev_i32_e32 v141, 31, v140
	s_and_b64 s[10:11], s[0:1], s[52:53]
	v_and_b32_e32 v183, 63, v184
	v_and_b32_e32 v0, 31, v184
	v_bfe_u32 v133, v184, 5, 1
	s_and_saveexec_b64 s[0:1], s[10:11]
	s_xor_b64 s[8:9], exec, s[0:1]
	s_cbranch_execz .LBB0_1136
	s_add_i32 s4, s6, 0xfffff200
	v_mul_u32_u24_e32 v130, 0x90, v133
	s_mov_b64 s[0:1], -1
	s_cmp_gt_u32 s4, 0xfffff9ff
	v_lshlrev_b32_e32 v139, 2, v0
	v_lshlrev_b32_e32 v185, 2, v130
	s_cbranch_scc0 .LBB0_1134
	v_add3_u32 v0, v170, v185, v139
	ds_write_b32 v0, v114
	v_add3_u32 v0, v170, v139, v185
	v_add_u32_e32 v130, 0x100, v0
	ds_write2_b32 v130, v117, v118 offset0:44 offset1:224
	v_add_u32_e32 v130, 0x400, v0
	ds_write2_b32 v130, v119, v120 offset0:68 offset1:104
	v_add_u32_e32 v130, 0x600, v0
	ds_write2_b32 v130, v121, v122 offset0:12 offset1:192
	v_add_u32_e32 v130, 0x800, v0
	ds_write2_b32 v130, v123, v124 offset0:100 offset1:136
	v_add_u32_e32 v130, 0xa00, v0
	ds_write2_b32 v130, v125, v126 offset0:44 offset1:224
	v_add_u32_e32 v130, 0xc00, v0
	s_cmpk_lt_u32 s6, 0xa00
	ds_write2_b32 v0, v115, v116 offset0:36 offset1:72
	ds_write2_b32 v130, v127, v128 offset0:132 offset1:168
	ds_write_b32 v0, v129 offset:3888
	s_cselect_b64 s[0:1], -1, 0
	v_mov_b32_e32 v0, 0x3e38aa3b
	v_cndmask_b32_e64 v142, 1.0, v0, s[0:1]
	v_lshlrev_b32_e32 v0, 3, v184
	v_lshrrev_b32_e32 v188, 2, v183
	s_movk_i32 s4, 0x90
	v_and_b32_e32 v187, 24, v0
	v_mad_u32_u24 v147, v188, s4, v170
	s_waitcnt lgkmcnt(0)
	v_lshl_add_u32 v130, v187, 2, v147
	ds_read_b128 v[134:137], v130
	ds_read_b128 v[130:133], v130 offset:16
	v_and_b32_e32 v144, 2, v184
	v_or_b32_e32 v150, v188, v140
	s_movk_i32 s4, 0x100
	v_cmp_eq_u32_e32 vcc, 0, v144
	v_cmp_gt_i32_e64 s[4:5], s4, v150
	s_and_saveexec_b64 s[16:17], s[4:5]
	s_xor_b64 s[4:5], exec, s[16:17]
	s_cbranch_execz .LBB0_1127
	s_waitcnt lgkmcnt(1)
	v_pk_mul_f32 v[152:153], v[142:143], v[134:135] op_sel_hi:[0,1]
	v_pk_mul_f32 v[154:155], v[142:143], v[136:137] op_sel_hi:[0,1]
	s_waitcnt lgkmcnt(0)
	v_pk_mul_f32 v[156:157], v[142:143], v[130:131] op_sel_hi:[0,1]
	v_mul_f32_e32 v145, v142, v132
